# GEMM loops: load segments run at setprio 1, MFMA segments at 0 (load segment measured critical); on top of v12
# baseline (speedup 1.0000x reference)
.LBB0_80:
	s_add_u32 s2, s14, 0x100
	v_mov_b32_e32 v0, 0
	s_addc_u32 s8, s15, 0
	s_mov_b32 s9, -2
	v_mov_b32_e32 v1, v0
	v_mov_b32_e32 v2, v0
	v_mov_b32_e32 v3, v0
	v_mov_b32_e32 v6, v0
	s_waitcnt lgkmcnt(0)
	v_mov_b32_e32 v7, v0
	v_mov_b32_e32 v8, v0
	v_mov_b32_e32 v9, v0
	v_mov_b32_e32 v18, v0
	v_mov_b32_e32 v19, v0
	v_mov_b32_e32 v20, v0
	v_mov_b32_e32 v21, v0
	v_mov_b32_e32 v22, v0
	v_mov_b32_e32 v23, v0
	v_mov_b32_e32 v24, v0
	v_mov_b32_e32 v25, v0
	v_mov_b32_e32 v34, v0
	v_mov_b32_e32 v35, v0
	v_mov_b32_e32 v36, v0
	v_mov_b32_e32 v37, v0
	v_mov_b32_e32 v38, v0
	v_mov_b32_e32 v39, v0
	v_mov_b32_e32 v40, v0
	v_mov_b32_e32 v41, v0
	v_mov_b32_e32 v50, v0
	v_mov_b32_e32 v51, v0
	v_mov_b32_e32 v52, v0
	v_mov_b32_e32 v53, v0
	v_mov_b32_e32 v54, v0
	v_mov_b32_e32 v55, v0
	v_mov_b32_e32 v56, v0
	v_mov_b32_e32 v57, v0
	v_mov_b32_e32 v10, v0
	v_mov_b32_e32 v11, v0
	v_mov_b32_e32 v12, v0
	v_mov_b32_e32 v13, v0
	v_mov_b32_e32 v14, v0
	v_mov_b32_e32 v15, v0
	v_mov_b32_e32 v16, v0
	v_mov_b32_e32 v17, v0
	v_mov_b32_e32 v26, v0
	v_mov_b32_e32 v27, v0
	v_mov_b32_e32 v28, v0
	v_mov_b32_e32 v29, v0
	v_mov_b32_e32 v30, v0
	v_mov_b32_e32 v31, v0
	v_mov_b32_e32 v32, v0
	v_mov_b32_e32 v33, v0
	v_mov_b32_e32 v42, v0
	v_mov_b32_e32 v43, v0
	v_mov_b32_e32 v44, v0
	v_mov_b32_e32 v45, v0
	v_mov_b32_e32 v46, v0
	v_mov_b32_e32 v47, v0
	v_mov_b32_e32 v48, v0
	v_mov_b32_e32 v49, v0
	v_mov_b32_e32 v58, v0
	v_mov_b32_e32 v59, v0
	v_mov_b32_e32 v60, v0
	v_mov_b32_e32 v61, v0
	v_mov_b32_e32 v62, v0
	v_mov_b32_e32 v63, v0
	v_mov_b32_e32 v64, v0
	v_mov_b32_e32 v65, v0
	v_mov_b32_e32 v66, v0
	v_mov_b32_e32 v67, v0
	v_mov_b32_e32 v68, v0
	v_mov_b32_e32 v69, v0
	v_mov_b32_e32 v70, v0
	v_mov_b32_e32 v71, v0
	v_mov_b32_e32 v72, v0
	v_mov_b32_e32 v73, v0
	v_mov_b32_e32 v82, v0
	v_mov_b32_e32 v83, v0
	v_mov_b32_e32 v84, v0
	v_mov_b32_e32 v85, v0
	v_mov_b32_e32 v86, v0
	v_mov_b32_e32 v87, v0
	v_mov_b32_e32 v88, v0
	v_mov_b32_e32 v89, v0
	v_mov_b32_e32 v98, v0
	v_mov_b32_e32 v99, v0
	v_mov_b32_e32 v100, v0
	v_mov_b32_e32 v101, v0
	v_mov_b32_e32 v102, v0
	v_mov_b32_e32 v103, v0
	v_mov_b32_e32 v104, v0
	v_mov_b32_e32 v105, v0
	v_mov_b32_e32 v114, v0
	v_mov_b32_e32 v115, v0
	v_mov_b32_e32 v116, v0
	v_mov_b32_e32 v117, v0
	v_mov_b32_e32 v118, v0
	v_mov_b32_e32 v119, v0
	v_mov_b32_e32 v120, v0
	v_mov_b32_e32 v121, v0
	v_mov_b32_e32 v74, v0
	v_mov_b32_e32 v75, v0
	v_mov_b32_e32 v76, v0
	v_mov_b32_e32 v77, v0
	v_mov_b32_e32 v78, v0
	v_mov_b32_e32 v79, v0
	v_mov_b32_e32 v80, v0
	v_mov_b32_e32 v81, v0
	v_mov_b32_e32 v90, v0
	v_mov_b32_e32 v91, v0
	v_mov_b32_e32 v92, v0
	v_mov_b32_e32 v93, v0
	v_mov_b32_e32 v94, v0
	v_mov_b32_e32 v95, v0
	v_mov_b32_e32 v96, v0
	v_mov_b32_e32 v97, v0
	v_mov_b32_e32 v106, v0
	v_mov_b32_e32 v107, v0
	v_mov_b32_e32 v108, v0
	v_mov_b32_e32 v109, v0
	v_mov_b32_e32 v110, v0
	v_mov_b32_e32 v111, v0
	v_mov_b32_e32 v112, v0
	v_mov_b32_e32 v113, v0
	v_mov_b32_e32 v122, v0
	v_mov_b32_e32 v123, v0
	v_mov_b32_e32 v124, v0
	v_mov_b32_e32 v125, v0
	v_mov_b32_e32 v126, v0
	v_mov_b32_e32 v127, v0
	v_mov_b32_e32 v128, v0
	v_mov_b32_e32 v129, v0
	s_cmp_eq_u32 s36, 1
	s_cbranch_scc1 .LBB0_81
	s_add_u32 s14, s0, 0x100
	s_addc_u32 s15, s1, 0
	s_add_i32 s3, 0, 0x10000
	s_cmpk_eq_i32 s9, 0x7c
	s_cselect_b32 s27, s43, s15
	s_cselect_b32 s26, s42, s14
	v_add_u32_e32 v162, s3, v145
	s_cselect_b32 s23, s79, s8
	s_cselect_b32 s22, s78, s2
	s_add_i32 s4, 0, 0x14000
	ds_read_b128 v[140:143], v162
	ds_read_b128 v[148:151], v162 offset:1024
	ds_read_b128 v[172:175], v162 offset:2048
	ds_read_b128 v[190:193], v162 offset:3072
	v_add_u32_e32 v162, s4, v145
	ds_read_b128 v[194:197], v162
	ds_read_b128 v[198:201], v162 offset:1024
	ds_read_b128 v[202:205], v162 offset:2048
	ds_read_b128 v[206:209], v162 offset:3072
	v_lshl_add_u64 v[162:163], s[0:1], 0, v[136:137]
	s_add_i32 m0, s30, 0xc000
	ds_read_b128 v[210:213], v147
	ds_read_b128 v[214:217], v147 offset:1024
	ds_read_b128 v[218:221], v147 offset:2048
	ds_read_b128 v[222:225], v147 offset:3072
	ds_read_b128 v[226:229], v147 offset:4096
	ds_read_b128 v[230:233], v147 offset:5120
	ds_read_b128 v[234:237], v147 offset:6144
	ds_read_b128 v[238:241], v147 offset:7168
	global_load_lds_dwordx4 v[162:163], off
	v_lshl_add_u64 v[162:163], s[0:1], 0, v[138:139]
	s_add_i32 m0, s30, 0xe000
	s_nop 0
	global_load_lds_dwordx4 v[162:163], off
	s_waitcnt vmcnt(24)
	s_waitcnt lgkmcnt(0)
	s_barrier
	s_setprio 0
	s_waitcnt lgkmcnt(0)
	v_mfma_f32_16x16x32_bf16 v[126:129], v[140:143], v[210:213], v[126:129]
	v_mfma_f32_16x16x32_bf16 v[122:125], v[172:175], v[210:213], v[122:125]
	v_mfma_f32_16x16x32_bf16 v[110:113], v[140:143], v[218:221], v[110:113]
	v_mfma_f32_16x16x32_bf16 v[106:109], v[172:175], v[218:221], v[106:109]
	v_mfma_f32_16x16x32_bf16 v[94:97], v[140:143], v[226:229], v[94:97]
	v_mfma_f32_16x16x32_bf16 v[90:93], v[172:175], v[226:229], v[90:93]
	v_mfma_f32_16x16x32_bf16 v[78:81], v[140:143], v[234:237], v[78:81]
	v_mfma_f32_16x16x32_bf16 v[74:77], v[172:175], v[234:237], v[74:77]
	v_mfma_f32_16x16x32_bf16 v[126:129], v[148:151], v[214:217], v[126:129]
	v_mfma_f32_16x16x32_bf16 v[122:125], v[190:193], v[214:217], v[122:125]
	v_mfma_f32_16x16x32_bf16 v[110:113], v[148:151], v[222:225], v[110:113]
	v_mfma_f32_16x16x32_bf16 v[106:109], v[190:193], v[222:225], v[106:109]
	v_mfma_f32_16x16x32_bf16 v[94:97], v[148:151], v[230:233], v[94:97]
	v_mfma_f32_16x16x32_bf16 v[90:93], v[190:193], v[230:233], v[90:93]
	v_mfma_f32_16x16x32_bf16 v[78:81], v[148:151], v[238:241], v[78:81]
	v_mfma_f32_16x16x32_bf16 v[74:77], v[190:193], v[238:241], v[74:77]
	v_mfma_f32_16x16x32_bf16 v[118:121], v[194:197], v[210:213], v[118:121]
	v_mfma_f32_16x16x32_bf16 v[114:117], v[202:205], v[210:213], v[114:117]
	v_mfma_f32_16x16x32_bf16 v[102:105], v[194:197], v[218:221], v[102:105]
	v_mfma_f32_16x16x32_bf16 v[98:101], v[202:205], v[218:221], v[98:101]
	v_mfma_f32_16x16x32_bf16 v[86:89], v[194:197], v[226:229], v[86:89]
	v_mfma_f32_16x16x32_bf16 v[82:85], v[202:205], v[226:229], v[82:85]
	v_mfma_f32_16x16x32_bf16 v[70:73], v[194:197], v[234:237], v[70:73]
	v_mfma_f32_16x16x32_bf16 v[66:69], v[202:205], v[234:237], v[66:69]
	v_mfma_f32_16x16x32_bf16 v[118:121], v[198:201], v[214:217], v[118:121]
	v_mfma_f32_16x16x32_bf16 v[114:117], v[206:209], v[214:217], v[114:117]
	v_mfma_f32_16x16x32_bf16 v[102:105], v[198:201], v[222:225], v[102:105]
	v_mfma_f32_16x16x32_bf16 v[98:101], v[206:209], v[222:225], v[98:101]
	v_mfma_f32_16x16x32_bf16 v[86:89], v[198:201], v[230:233], v[86:89]
	v_mfma_f32_16x16x32_bf16 v[82:85], v[206:209], v[230:233], v[82:85]
	v_mfma_f32_16x16x32_bf16 v[70:73], v[198:201], v[238:241], v[70:73]
	v_mfma_f32_16x16x32_bf16 v[66:69], v[206:209], v[238:241], v[66:69]
	s_setprio 1
	s_barrier
	s_add_i32 s0, s3, s11
	v_lshl_add_u64 v[162:163], s[22:23], 0, v[4:5]
	s_mov_b32 m0, s0
	ds_read_b128 v[210:213], v147 offset:16384
	ds_read_b128 v[214:217], v147 offset:17408
	ds_read_b128 v[218:221], v147 offset:18432
	ds_read_b128 v[222:225], v147 offset:19456
	ds_read_b128 v[226:229], v147 offset:20480
	ds_read_b128 v[230:233], v147 offset:21504
	ds_read_b128 v[234:237], v147 offset:22528
	ds_read_b128 v[238:241], v147 offset:23552
	global_load_lds_dwordx4 v[162:163], off
	s_add_i32 m0, s0, 0x2000
	s_add_u32 s0, s22, 0x208000
	v_lshl_add_u64 v[166:167], s[22:23], 0, v[130:131]
	s_addc_u32 s1, s23, 0
	s_add_i32 s3, s4, s11
	global_load_lds_dwordx4 v[166:167], off
	v_lshl_add_u64 v[176:177], s[0:1], 0, v[4:5]
	s_mov_b32 m0, s3
	v_lshl_add_u64 v[180:181], s[26:27], 0, v[132:133]
	global_load_lds_dwordx4 v[176:177], off
	v_lshl_add_u64 v[176:177], s[0:1], 0, v[130:131]
	s_add_i32 m0, s3, 0x2000
	s_nop 0
	global_load_lds_dwordx4 v[176:177], off
	v_lshl_add_u64 v[176:177], s[26:27], 0, v[134:135]
	s_mov_b32 m0, s30
	s_nop 0
	global_load_lds_dwordx4 v[176:177], off
	s_mov_b32 m0, s31
	s_nop 0
	global_load_lds_dwordx4 v[180:181], off
	s_waitcnt vmcnt(24)
	s_waitcnt lgkmcnt(0)
	s_barrier
	s_setprio 0
	s_waitcnt lgkmcnt(0)
	v_mfma_f32_16x16x32_bf16 v[62:65], v[140:143], v[210:213], v[62:65]
	v_mfma_f32_16x16x32_bf16 v[58:61], v[172:175], v[210:213], v[58:61]
	v_mfma_f32_16x16x32_bf16 v[46:49], v[140:143], v[218:221], v[46:49]
	v_mfma_f32_16x16x32_bf16 v[42:45], v[172:175], v[218:221], v[42:45]
	v_mfma_f32_16x16x32_bf16 v[30:33], v[140:143], v[226:229], v[30:33]
	v_mfma_f32_16x16x32_bf16 v[26:29], v[172:175], v[226:229], v[26:29]
	v_mfma_f32_16x16x32_bf16 v[14:17], v[140:143], v[234:237], v[14:17]
	v_mfma_f32_16x16x32_bf16 v[10:13], v[172:175], v[234:237], v[10:13]
	v_mfma_f32_16x16x32_bf16 v[62:65], v[148:151], v[214:217], v[62:65]
	v_mfma_f32_16x16x32_bf16 v[58:61], v[190:193], v[214:217], v[58:61]
	v_mfma_f32_16x16x32_bf16 v[46:49], v[148:151], v[222:225], v[46:49]
	v_mfma_f32_16x16x32_bf16 v[42:45], v[190:193], v[222:225], v[42:45]
	v_mfma_f32_16x16x32_bf16 v[30:33], v[148:151], v[230:233], v[30:33]
	v_mfma_f32_16x16x32_bf16 v[26:29], v[190:193], v[230:233], v[26:29]
	v_mfma_f32_16x16x32_bf16 v[14:17], v[148:151], v[238:241], v[14:17]
	v_mfma_f32_16x16x32_bf16 v[10:13], v[190:193], v[238:241], v[10:13]
	v_mfma_f32_16x16x32_bf16 v[54:57], v[194:197], v[210:213], v[54:57]
	v_mfma_f32_16x16x32_bf16 v[50:53], v[202:205], v[210:213], v[50:53]
	v_mfma_f32_16x16x32_bf16 v[38:41], v[194:197], v[218:221], v[38:41]
	v_mfma_f32_16x16x32_bf16 v[34:37], v[202:205], v[218:221], v[34:37]
	v_mfma_f32_16x16x32_bf16 v[22:25], v[194:197], v[226:229], v[22:25]
	v_mfma_f32_16x16x32_bf16 v[18:21], v[202:205], v[226:229], v[18:21]
	v_mfma_f32_16x16x32_bf16 v[6:9], v[194:197], v[234:237], v[6:9]
	v_mfma_f32_16x16x32_bf16 v[0:3], v[202:205], v[234:237], v[0:3]
	v_mfma_f32_16x16x32_bf16 v[54:57], v[198:201], v[214:217], v[54:57]
	v_mfma_f32_16x16x32_bf16 v[50:53], v[206:209], v[214:217], v[50:53]
	v_mfma_f32_16x16x32_bf16 v[38:41], v[198:201], v[222:225], v[38:41]
	v_mfma_f32_16x16x32_bf16 v[34:37], v[206:209], v[222:225], v[34:37]
	v_mfma_f32_16x16x32_bf16 v[22:25], v[198:201], v[230:233], v[22:25]
	v_mfma_f32_16x16x32_bf16 v[18:21], v[206:209], v[230:233], v[18:21]
	v_mfma_f32_16x16x32_bf16 v[6:9], v[198:201], v[238:241], v[6:9]
	v_mfma_f32_16x16x32_bf16 v[0:3], v[206:209], v[238:241], v[0:3]
	s_setprio 1
	s_barrier
	s_branch .Lpeelmid_81
.LBB0_81:
	s_add_u32 s14, s0, 0x100
	s_addc_u32 s15, s1, 0
	s_add_i32 s3, 0, 0x10000
	s_cmpk_eq_i32 s9, 0x7c
	s_cselect_b32 s27, s43, s15
	s_cselect_b32 s26, s42, s14
	v_add_u32_e32 v162, s3, v145
	s_cselect_b32 s23, s79, s8
	s_cselect_b32 s22, s78, s2
	s_add_i32 s4, 0, 0x14000
	ds_read_b128 v[140:143], v162
	ds_read_b128 v[148:151], v162 offset:1024
	ds_read_b128 v[172:175], v162 offset:2048
	ds_read_b128 v[190:193], v162 offset:3072
	v_add_u32_e32 v162, s4, v145
	ds_read_b128 v[194:197], v162
	ds_read_b128 v[198:201], v162 offset:1024
	ds_read_b128 v[202:205], v162 offset:2048
	ds_read_b128 v[206:209], v162 offset:3072
	v_lshl_add_u64 v[162:163], s[0:1], 0, v[136:137]
	s_add_i32 m0, s30, 0xc000
	ds_read_b128 v[210:213], v147
	ds_read_b128 v[214:217], v147 offset:1024
	ds_read_b128 v[218:221], v147 offset:2048
	ds_read_b128 v[222:225], v147 offset:3072
	ds_read_b128 v[226:229], v147 offset:4096
	ds_read_b128 v[230:233], v147 offset:5120
	ds_read_b128 v[234:237], v147 offset:6144
	ds_read_b128 v[238:241], v147 offset:7168
	global_load_lds_dwordx4 v[162:163], off
	v_lshl_add_u64 v[162:163], s[0:1], 0, v[138:139]
	s_add_i32 m0, s30, 0xe000
	s_nop 0
	global_load_lds_dwordx4 v[162:163], off
	s_waitcnt vmcnt(8)
	s_waitcnt lgkmcnt(0)
	s_barrier
	s_setprio 0
	s_waitcnt lgkmcnt(0)
	v_mfma_f32_16x16x32_bf16 v[126:129], v[140:143], v[210:213], v[126:129]
	v_mfma_f32_16x16x32_bf16 v[122:125], v[172:175], v[210:213], v[122:125]
	v_mfma_f32_16x16x32_bf16 v[110:113], v[140:143], v[218:221], v[110:113]
	v_mfma_f32_16x16x32_bf16 v[106:109], v[172:175], v[218:221], v[106:109]
	v_mfma_f32_16x16x32_bf16 v[94:97], v[140:143], v[226:229], v[94:97]
	v_mfma_f32_16x16x32_bf16 v[90:93], v[172:175], v[226:229], v[90:93]
	v_mfma_f32_16x16x32_bf16 v[78:81], v[140:143], v[234:237], v[78:81]
	v_mfma_f32_16x16x32_bf16 v[74:77], v[172:175], v[234:237], v[74:77]
	v_mfma_f32_16x16x32_bf16 v[126:129], v[148:151], v[214:217], v[126:129]
	v_mfma_f32_16x16x32_bf16 v[122:125], v[190:193], v[214:217], v[122:125]
	v_mfma_f32_16x16x32_bf16 v[110:113], v[148:151], v[222:225], v[110:113]
	v_mfma_f32_16x16x32_bf16 v[106:109], v[190:193], v[222:225], v[106:109]
	v_mfma_f32_16x16x32_bf16 v[94:97], v[148:151], v[230:233], v[94:97]
	v_mfma_f32_16x16x32_bf16 v[90:93], v[190:193], v[230:233], v[90:93]
	v_mfma_f32_16x16x32_bf16 v[78:81], v[148:151], v[238:241], v[78:81]
	v_mfma_f32_16x16x32_bf16 v[74:77], v[190:193], v[238:241], v[74:77]
	v_mfma_f32_16x16x32_bf16 v[118:121], v[194:197], v[210:213], v[118:121]
	v_mfma_f32_16x16x32_bf16 v[114:117], v[202:205], v[210:213], v[114:117]
	v_mfma_f32_16x16x32_bf16 v[102:105], v[194:197], v[218:221], v[102:105]
	v_mfma_f32_16x16x32_bf16 v[98:101], v[202:205], v[218:221], v[98:101]
	v_mfma_f32_16x16x32_bf16 v[86:89], v[194:197], v[226:229], v[86:89]
	v_mfma_f32_16x16x32_bf16 v[82:85], v[202:205], v[226:229], v[82:85]
	v_mfma_f32_16x16x32_bf16 v[70:73], v[194:197], v[234:237], v[70:73]
	v_mfma_f32_16x16x32_bf16 v[66:69], v[202:205], v[234:237], v[66:69]
	v_mfma_f32_16x16x32_bf16 v[118:121], v[198:201], v[214:217], v[118:121]
	v_mfma_f32_16x16x32_bf16 v[114:117], v[206:209], v[214:217], v[114:117]
	v_mfma_f32_16x16x32_bf16 v[102:105], v[198:201], v[222:225], v[102:105]
	v_mfma_f32_16x16x32_bf16 v[98:101], v[206:209], v[222:225], v[98:101]
	v_mfma_f32_16x16x32_bf16 v[86:89], v[198:201], v[230:233], v[86:89]
	v_mfma_f32_16x16x32_bf16 v[82:85], v[206:209], v[230:233], v[82:85]
	v_mfma_f32_16x16x32_bf16 v[70:73], v[198:201], v[238:241], v[70:73]
	v_mfma_f32_16x16x32_bf16 v[66:69], v[206:209], v[238:241], v[66:69]
	s_setprio 1
	s_barrier
	s_add_i32 s0, s3, s11
	v_lshl_add_u64 v[162:163], s[22:23], 0, v[4:5]
	s_mov_b32 m0, s0
	ds_read_b128 v[210:213], v147 offset:16384
	ds_read_b128 v[214:217], v147 offset:17408
	ds_read_b128 v[218:221], v147 offset:18432
	ds_read_b128 v[222:225], v147 offset:19456
	ds_read_b128 v[226:229], v147 offset:20480
	ds_read_b128 v[230:233], v147 offset:21504
	ds_read_b128 v[234:237], v147 offset:22528
	ds_read_b128 v[238:241], v147 offset:23552
	global_load_lds_dwordx4 v[162:163], off
	s_add_i32 m0, s0, 0x2000
	s_add_u32 s0, s22, 0x208000
	v_lshl_add_u64 v[166:167], s[22:23], 0, v[130:131]
	s_addc_u32 s1, s23, 0
	s_add_i32 s3, s4, s11
	global_load_lds_dwordx4 v[166:167], off
	v_lshl_add_u64 v[176:177], s[0:1], 0, v[4:5]
	s_mov_b32 m0, s3
	v_lshl_add_u64 v[180:181], s[26:27], 0, v[132:133]
	global_load_lds_dwordx4 v[176:177], off
	v_lshl_add_u64 v[176:177], s[0:1], 0, v[130:131]
	s_add_i32 m0, s3, 0x2000
	s_nop 0
	global_load_lds_dwordx4 v[176:177], off
	v_lshl_add_u64 v[176:177], s[26:27], 0, v[134:135]
	s_mov_b32 m0, s30
	s_nop 0
	global_load_lds_dwordx4 v[176:177], off
	s_mov_b32 m0, s31
	s_nop 0
	global_load_lds_dwordx4 v[180:181], off
	s_waitcnt vmcnt(8)
	s_waitcnt lgkmcnt(0)
	s_barrier
	s_setprio 0
	s_waitcnt lgkmcnt(0)
	v_mfma_f32_16x16x32_bf16 v[62:65], v[140:143], v[210:213], v[62:65]
	v_mfma_f32_16x16x32_bf16 v[58:61], v[172:175], v[210:213], v[58:61]
	v_mfma_f32_16x16x32_bf16 v[46:49], v[140:143], v[218:221], v[46:49]
	v_mfma_f32_16x16x32_bf16 v[42:45], v[172:175], v[218:221], v[42:45]
	v_mfma_f32_16x16x32_bf16 v[30:33], v[140:143], v[226:229], v[30:33]
	v_mfma_f32_16x16x32_bf16 v[26:29], v[172:175], v[226:229], v[26:29]
	v_mfma_f32_16x16x32_bf16 v[14:17], v[140:143], v[234:237], v[14:17]
	v_mfma_f32_16x16x32_bf16 v[10:13], v[172:175], v[234:237], v[10:13]
	v_mfma_f32_16x16x32_bf16 v[62:65], v[148:151], v[214:217], v[62:65]
	v_mfma_f32_16x16x32_bf16 v[58:61], v[190:193], v[214:217], v[58:61]
	v_mfma_f32_16x16x32_bf16 v[46:49], v[148:151], v[222:225], v[46:49]
	v_mfma_f32_16x16x32_bf16 v[42:45], v[190:193], v[222:225], v[42:45]
	v_mfma_f32_16x16x32_bf16 v[30:33], v[148:151], v[230:233], v[30:33]
	v_mfma_f32_16x16x32_bf16 v[26:29], v[190:193], v[230:233], v[26:29]
	v_mfma_f32_16x16x32_bf16 v[14:17], v[148:151], v[238:241], v[14:17]
	v_mfma_f32_16x16x32_bf16 v[10:13], v[190:193], v[238:241], v[10:13]
	v_mfma_f32_16x16x32_bf16 v[54:57], v[194:197], v[210:213], v[54:57]
	v_mfma_f32_16x16x32_bf16 v[50:53], v[202:205], v[210:213], v[50:53]
	v_mfma_f32_16x16x32_bf16 v[38:41], v[194:197], v[218:221], v[38:41]
	v_mfma_f32_16x16x32_bf16 v[34:37], v[202:205], v[218:221], v[34:37]
	v_mfma_f32_16x16x32_bf16 v[22:25], v[194:197], v[226:229], v[22:25]
	v_mfma_f32_16x16x32_bf16 v[18:21], v[202:205], v[226:229], v[18:21]
	v_mfma_f32_16x16x32_bf16 v[6:9], v[194:197], v[234:237], v[6:9]
	v_mfma_f32_16x16x32_bf16 v[0:3], v[202:205], v[234:237], v[0:3]
	v_mfma_f32_16x16x32_bf16 v[54:57], v[198:201], v[214:217], v[54:57]
	v_mfma_f32_16x16x32_bf16 v[50:53], v[206:209], v[214:217], v[50:53]
	v_mfma_f32_16x16x32_bf16 v[38:41], v[198:201], v[222:225], v[38:41]
	v_mfma_f32_16x16x32_bf16 v[34:37], v[206:209], v[222:225], v[34:37]
	v_mfma_f32_16x16x32_bf16 v[22:25], v[198:201], v[230:233], v[22:25]
	v_mfma_f32_16x16x32_bf16 v[18:21], v[206:209], v[230:233], v[18:21]
	v_mfma_f32_16x16x32_bf16 v[6:9], v[198:201], v[238:241], v[6:9]
	v_mfma_f32_16x16x32_bf16 v[0:3], v[206:209], v[238:241], v[0:3]
	s_setprio 1
	s_barrier
.Lpeelmid_81:
	s_add_i32 s3, 0, 0x18000
	v_add_u32_e32 v164, s3, v145
	s_add_i32 s4, 0, 0x1c000
	ds_read_b128 v[140:143], v164
	ds_read_b128 v[148:151], v164 offset:1024
	ds_read_b128 v[172:175], v164 offset:2048
	ds_read_b128 v[190:193], v164 offset:3072
	v_add_u32_e32 v164, s4, v145
	ds_read_b128 v[194:197], v164
	ds_read_b128 v[198:201], v164 offset:1024
	ds_read_b128 v[202:205], v164 offset:2048
	ds_read_b128 v[206:209], v164 offset:3072
	s_add_u32 s0, s26, 0x208000
	s_addc_u32 s1, s27, 0
	s_mov_b32 m0, s34
	v_lshl_add_u64 v[242:243], s[0:1], 0, v[134:135]
	ds_read_b128 v[210:213], v147 offset:32768
	ds_read_b128 v[214:217], v147 offset:33792
	ds_read_b128 v[218:221], v147 offset:34816
	ds_read_b128 v[222:225], v147 offset:35840
	ds_read_b128 v[226:229], v147 offset:36864
	ds_read_b128 v[230:233], v147 offset:37888
	ds_read_b128 v[234:237], v147 offset:38912
	ds_read_b128 v[238:241], v147 offset:39936
	global_load_lds_dwordx4 v[242:243], off
	v_lshl_add_u64 v[242:243], s[0:1], 0, v[132:133]
	s_mov_b32 m0, s35
	s_nop 0
	global_load_lds_dwordx4 v[242:243], off
	s_waitcnt vmcnt(8)
	s_waitcnt lgkmcnt(0)
	s_barrier
	s_setprio 0
	s_waitcnt lgkmcnt(0)
	v_mfma_f32_16x16x32_bf16 v[126:129], v[140:143], v[210:213], v[126:129]
	v_mfma_f32_16x16x32_bf16 v[122:125], v[172:175], v[210:213], v[122:125]
	v_mfma_f32_16x16x32_bf16 v[110:113], v[140:143], v[218:221], v[110:113]
	v_mfma_f32_16x16x32_bf16 v[106:109], v[172:175], v[218:221], v[106:109]
	v_mfma_f32_16x16x32_bf16 v[94:97], v[140:143], v[226:229], v[94:97]
	v_mfma_f32_16x16x32_bf16 v[90:93], v[172:175], v[226:229], v[90:93]
	v_mfma_f32_16x16x32_bf16 v[78:81], v[140:143], v[234:237], v[78:81]
	v_mfma_f32_16x16x32_bf16 v[74:77], v[172:175], v[234:237], v[74:77]
	v_mfma_f32_16x16x32_bf16 v[126:129], v[148:151], v[214:217], v[126:129]
	v_mfma_f32_16x16x32_bf16 v[122:125], v[190:193], v[214:217], v[122:125]
	v_mfma_f32_16x16x32_bf16 v[110:113], v[148:151], v[222:225], v[110:113]
	v_mfma_f32_16x16x32_bf16 v[106:109], v[190:193], v[222:225], v[106:109]
	v_mfma_f32_16x16x32_bf16 v[94:97], v[148:151], v[230:233], v[94:97]
	v_mfma_f32_16x16x32_bf16 v[90:93], v[190:193], v[230:233], v[90:93]
	v_mfma_f32_16x16x32_bf16 v[78:81], v[148:151], v[238:241], v[78:81]
	v_mfma_f32_16x16x32_bf16 v[74:77], v[190:193], v[238:241], v[74:77]
	v_mfma_f32_16x16x32_bf16 v[118:121], v[194:197], v[210:213], v[118:121]
	v_mfma_f32_16x16x32_bf16 v[114:117], v[202:205], v[210:213], v[114:117]
	v_mfma_f32_16x16x32_bf16 v[102:105], v[194:197], v[218:221], v[102:105]
	v_mfma_f32_16x16x32_bf16 v[98:101], v[202:205], v[218:221], v[98:101]
	v_mfma_f32_16x16x32_bf16 v[86:89], v[194:197], v[226:229], v[86:89]
	v_mfma_f32_16x16x32_bf16 v[82:85], v[202:205], v[226:229], v[82:85]
	v_mfma_f32_16x16x32_bf16 v[70:73], v[194:197], v[234:237], v[70:73]
	v_mfma_f32_16x16x32_bf16 v[66:69], v[202:205], v[234:237], v[66:69]
	v_mfma_f32_16x16x32_bf16 v[118:121], v[198:201], v[214:217], v[118:121]
	v_mfma_f32_16x16x32_bf16 v[114:117], v[206:209], v[214:217], v[114:117]
	v_mfma_f32_16x16x32_bf16 v[102:105], v[198:201], v[222:225], v[102:105]
	v_mfma_f32_16x16x32_bf16 v[98:101], v[206:209], v[222:225], v[98:101]
	v_mfma_f32_16x16x32_bf16 v[86:89], v[198:201], v[230:233], v[86:89]
	v_mfma_f32_16x16x32_bf16 v[82:85], v[206:209], v[230:233], v[82:85]
	v_mfma_f32_16x16x32_bf16 v[70:73], v[198:201], v[238:241], v[70:73]
	v_mfma_f32_16x16x32_bf16 v[66:69], v[206:209], v[238:241], v[66:69]
	s_setprio 1
	s_barrier
	s_add_i32 s0, s3, s11
	v_lshl_add_u64 v[162:163], v[162:163], 0, s[70:71]
	s_mov_b32 m0, s0
	ds_read_b128 v[210:213], v147 offset:49152
	ds_read_b128 v[214:217], v147 offset:50176
	ds_read_b128 v[218:221], v147 offset:51200
	ds_read_b128 v[222:225], v147 offset:52224
	ds_read_b128 v[226:229], v147 offset:53248
	ds_read_b128 v[230:233], v147 offset:54272
	ds_read_b128 v[234:237], v147 offset:55296
	ds_read_b128 v[238:241], v147 offset:56320
	global_load_lds_dwordx4 v[162:163], off
	s_add_i32 m0, s0, 0x2000
	s_add_u32 s0, s22, 0x208080
	v_lshl_add_u64 v[162:163], v[166:167], 0, s[70:71]
	s_addc_u32 s1, s23, 0
	s_add_i32 s3, s4, s11
	global_load_lds_dwordx4 v[162:163], off
	v_lshl_add_u64 v[162:163], s[0:1], 0, v[4:5]
	s_mov_b32 m0, s3
	s_nop 0
	global_load_lds_dwordx4 v[162:163], off
	v_lshl_add_u64 v[162:163], s[0:1], 0, v[130:131]
	s_add_i32 m0, s3, 0x2000
	s_nop 0
	global_load_lds_dwordx4 v[162:163], off
	v_lshl_add_u64 v[162:163], v[176:177], 0, s[70:71]
	s_mov_b32 m0, s51
	s_nop 0
	global_load_lds_dwordx4 v[162:163], off
	v_lshl_add_u64 v[162:163], v[180:181], 0, s[70:71]
	s_mov_b32 m0, s52
	s_nop 0
	global_load_lds_dwordx4 v[162:163], off
	s_waitcnt vmcnt(8)
	s_waitcnt lgkmcnt(0)
	s_barrier
	s_setprio 0
	s_waitcnt lgkmcnt(0)
	v_mfma_f32_16x16x32_bf16 v[62:65], v[140:143], v[210:213], v[62:65]
	v_mfma_f32_16x16x32_bf16 v[58:61], v[172:175], v[210:213], v[58:61]
	v_mfma_f32_16x16x32_bf16 v[46:49], v[140:143], v[218:221], v[46:49]
	v_mfma_f32_16x16x32_bf16 v[42:45], v[172:175], v[218:221], v[42:45]
	v_mfma_f32_16x16x32_bf16 v[30:33], v[140:143], v[226:229], v[30:33]
	v_mfma_f32_16x16x32_bf16 v[26:29], v[172:175], v[226:229], v[26:29]
	v_mfma_f32_16x16x32_bf16 v[14:17], v[140:143], v[234:237], v[14:17]
	v_mfma_f32_16x16x32_bf16 v[10:13], v[172:175], v[234:237], v[10:13]
	v_mfma_f32_16x16x32_bf16 v[62:65], v[148:151], v[214:217], v[62:65]
	v_mfma_f32_16x16x32_bf16 v[58:61], v[190:193], v[214:217], v[58:61]
	v_mfma_f32_16x16x32_bf16 v[46:49], v[148:151], v[222:225], v[46:49]
	v_mfma_f32_16x16x32_bf16 v[42:45], v[190:193], v[222:225], v[42:45]
	v_mfma_f32_16x16x32_bf16 v[30:33], v[148:151], v[230:233], v[30:33]
	v_mfma_f32_16x16x32_bf16 v[26:29], v[190:193], v[230:233], v[26:29]
	v_mfma_f32_16x16x32_bf16 v[14:17], v[148:151], v[238:241], v[14:17]
	v_mfma_f32_16x16x32_bf16 v[10:13], v[190:193], v[238:241], v[10:13]
	v_mfma_f32_16x16x32_bf16 v[54:57], v[194:197], v[210:213], v[54:57]
	v_mfma_f32_16x16x32_bf16 v[50:53], v[202:205], v[210:213], v[50:53]
	v_mfma_f32_16x16x32_bf16 v[38:41], v[194:197], v[218:221], v[38:41]
	v_mfma_f32_16x16x32_bf16 v[34:37], v[202:205], v[218:221], v[34:37]
	v_mfma_f32_16x16x32_bf16 v[22:25], v[194:197], v[226:229], v[22:25]
	v_mfma_f32_16x16x32_bf16 v[18:21], v[202:205], v[226:229], v[18:21]
	v_mfma_f32_16x16x32_bf16 v[6:9], v[194:197], v[234:237], v[6:9]
	v_mfma_f32_16x16x32_bf16 v[0:3], v[202:205], v[234:237], v[0:3]
	v_mfma_f32_16x16x32_bf16 v[54:57], v[198:201], v[214:217], v[54:57]
	v_mfma_f32_16x16x32_bf16 v[50:53], v[206:209], v[214:217], v[50:53]
	v_mfma_f32_16x16x32_bf16 v[38:41], v[198:201], v[222:225], v[38:41]
	v_mfma_f32_16x16x32_bf16 v[34:37], v[206:209], v[222:225], v[34:37]
	v_mfma_f32_16x16x32_bf16 v[22:25], v[198:201], v[230:233], v[22:25]
	v_mfma_f32_16x16x32_bf16 v[18:21], v[206:209], v[230:233], v[18:21]
	v_mfma_f32_16x16x32_bf16 v[6:9], v[198:201], v[238:241], v[6:9]
	v_mfma_f32_16x16x32_bf16 v[0:3], v[206:209], v[238:241], v[0:3]
	s_setprio 1
	s_barrier
	s_add_i32 s9, s9, 2
	s_add_u32 s2, s2, 0x100
	s_addc_u32 s8, s8, 0
	s_cmpk_gt_u32 s9, 0x7d
	s_mov_b64 s[0:1], s[14:15]
	s_cbranch_scc0 .LBB0_81
	s_and_b64 vcc, exec, s[48:49]
	s_cbranch_vccz .LBB0_84
	s_barrier

.LBB0_123:
	s_ashr_i32 s3, s51, 24
	s_lshl_b32 s2, s51, 8
	s_andn2_b32 s3, s3, 63
	s_add_i32 s2, s3, s2
	s_ashr_i32 s3, s2, 31
	s_lshl_b64 s[2:3], s[2:3], 12
	s_add_u32 s48, s11, s2
	s_addc_u32 s49, s26, s3
	s_and_b64 s[2:3], s[38:39], exec
	s_cselect_b32 s2, s49, s1
	s_cselect_b32 s8, s48, s0
	s_ashr_i32 s47, s46, 31
	s_lshl_b64 s[4:5], s[46:47], 20
	v_readlane_b32 s6, v254, 1
	v_readlane_b32 s7, v254, 2
	s_add_u32 s78, s6, s4
	s_addc_u32 s79, s7, s5
	s_and_b64 s[4:5], s[38:39], exec
	s_cselect_b32 s10, s79, s15
	s_cselect_b32 s24, s78, s14
	s_add_u32 s22, s0, 0x80080
	s_addc_u32 s23, s1, 0
	s_add_u32 s9, s14, 0x100
	v_mov_b32_e32 v0, 0
	s_addc_u32 s25, s15, 0
	s_mov_b32 s28, -2
	v_mov_b32_e32 v1, v0
	v_mov_b32_e32 v2, v0
	v_mov_b32_e32 v3, v0
	v_mov_b32_e32 v6, v0
	v_mov_b32_e32 v7, v0
	v_mov_b32_e32 v8, v0
	v_mov_b32_e32 v9, v0
	v_mov_b32_e32 v10, v0
	v_mov_b32_e32 v11, v0
	v_mov_b32_e32 v12, v0
	v_mov_b32_e32 v13, v0
	v_mov_b32_e32 v14, v0
	v_mov_b32_e32 v15, v0
	v_mov_b32_e32 v16, v0
	v_mov_b32_e32 v17, v0
	v_mov_b32_e32 v18, v0
	v_mov_b32_e32 v19, v0
	v_mov_b32_e32 v20, v0
	v_mov_b32_e32 v21, v0
	v_mov_b32_e32 v22, v0
	v_mov_b32_e32 v23, v0
	v_mov_b32_e32 v24, v0
	v_mov_b32_e32 v25, v0
	v_mov_b32_e32 v26, v0
	v_mov_b32_e32 v27, v0
	v_mov_b32_e32 v28, v0
	v_mov_b32_e32 v29, v0
	v_mov_b32_e32 v30, v0
	v_mov_b32_e32 v31, v0
	v_mov_b32_e32 v32, v0
	v_mov_b32_e32 v33, v0
	v_mov_b32_e32 v58, v0
	v_mov_b32_e32 v59, v0
	v_mov_b32_e32 v60, v0
	v_mov_b32_e32 v61, v0
	v_mov_b32_e32 v62, v0
	v_mov_b32_e32 v63, v0
	v_mov_b32_e32 v64, v0
	v_mov_b32_e32 v65, v0
	v_mov_b32_e32 v74, v0
	v_mov_b32_e32 v75, v0
	v_mov_b32_e32 v76, v0
	v_mov_b32_e32 v77, v0
	v_mov_b32_e32 v78, v0
	v_mov_b32_e32 v79, v0
	v_mov_b32_e32 v80, v0
	v_mov_b32_e32 v81, v0
	v_mov_b32_e32 v82, v0
	v_mov_b32_e32 v83, v0
	v_mov_b32_e32 v84, v0
	v_mov_b32_e32 v85, v0
	v_mov_b32_e32 v86, v0
	v_mov_b32_e32 v87, v0
	v_mov_b32_e32 v88, v0
	v_mov_b32_e32 v89, v0
	v_mov_b32_e32 v90, v0
	v_mov_b32_e32 v91, v0
	v_mov_b32_e32 v92, v0
	v_mov_b32_e32 v93, v0
	v_mov_b32_e32 v94, v0
	v_mov_b32_e32 v95, v0
	v_mov_b32_e32 v96, v0
	v_mov_b32_e32 v97, v0
	v_mov_b32_e32 v34, v0
	v_mov_b32_e32 v35, v0
	v_mov_b32_e32 v36, v0
	v_mov_b32_e32 v37, v0
	v_mov_b32_e32 v38, v0
	v_mov_b32_e32 v39, v0
	v_mov_b32_e32 v40, v0
	v_mov_b32_e32 v41, v0
	v_mov_b32_e32 v42, v0
	v_mov_b32_e32 v43, v0
	v_mov_b32_e32 v44, v0
	v_mov_b32_e32 v45, v0
	v_mov_b32_e32 v46, v0
	v_mov_b32_e32 v47, v0
	v_mov_b32_e32 v48, v0
	v_mov_b32_e32 v49, v0
	v_mov_b32_e32 v50, v0
	v_mov_b32_e32 v51, v0
	v_mov_b32_e32 v52, v0
	v_mov_b32_e32 v53, v0
	v_mov_b32_e32 v54, v0
	v_mov_b32_e32 v55, v0
	v_mov_b32_e32 v56, v0
	v_mov_b32_e32 v57, v0
	v_mov_b32_e32 v66, v0
	v_mov_b32_e32 v67, v0
	v_mov_b32_e32 v68, v0
	v_mov_b32_e32 v69, v0
	v_mov_b32_e32 v70, v0
	v_mov_b32_e32 v71, v0
	v_mov_b32_e32 v72, v0
	v_mov_b32_e32 v73, v0
	v_mov_b32_e32 v98, v0
	v_mov_b32_e32 v99, v0
	v_mov_b32_e32 v100, v0
	v_mov_b32_e32 v101, v0
	v_mov_b32_e32 v102, v0
	v_mov_b32_e32 v103, v0
	v_mov_b32_e32 v104, v0
	v_mov_b32_e32 v105, v0
	v_mov_b32_e32 v106, v0
	v_mov_b32_e32 v107, v0
	v_mov_b32_e32 v108, v0
	v_mov_b32_e32 v109, v0
	v_mov_b32_e32 v110, v0
	v_mov_b32_e32 v111, v0
	v_mov_b32_e32 v112, v0
	v_mov_b32_e32 v113, v0
	v_mov_b32_e32 v114, v0
	v_mov_b32_e32 v115, v0
	v_mov_b32_e32 v116, v0
	v_mov_b32_e32 v117, v0
	v_mov_b32_e32 v118, v0
	v_mov_b32_e32 v119, v0
	v_mov_b32_e32 v120, v0
	v_mov_b32_e32 v121, v0
	v_mov_b32_e32 v122, v0
	v_mov_b32_e32 v123, v0
	v_mov_b32_e32 v124, v0
	v_mov_b32_e32 v125, v0
	v_mov_b32_e32 v126, v0
	v_mov_b32_e32 v127, v0
	v_mov_b32_e32 v128, v0
	v_mov_b32_e32 v129, v0
	s_cmp_eq_u32 s50, 1
	s_cbranch_scc1 .LBB0_124
	s_add_u32 s0, s22, 0xfff80080
	s_addc_u32 s1, s23, -1
	s_add_i32 s3, 0, 0x10000
	s_cmp_eq_u32 s28, 28
	s_cselect_b32 s15, s2, s1
	s_cselect_b32 s14, s8, s0
	v_add_u32_e32 v162, s3, v141
	s_cselect_b32 s1, s10, s25
	s_cselect_b32 s0, s24, s9
	s_add_i32 s6, 0, 0x14000
	ds_read_b128 v[144:147], v162
	ds_read_b128 v[148:151], v162 offset:1024
	ds_read_b128 v[172:175], v162 offset:2048
	ds_read_b128 v[190:193], v162 offset:3072
	v_add_u32_e32 v162, s6, v141
	ds_read_b128 v[194:197], v162
	ds_read_b128 v[198:201], v162 offset:1024
	ds_read_b128 v[202:205], v162 offset:2048
	ds_read_b128 v[206:209], v162 offset:3072
	v_lshl_add_u64 v[162:163], s[22:23], 0, v[136:137]
	s_add_i32 m0, s30, 0xc000
	ds_read_b128 v[210:213], v143
	ds_read_b128 v[214:217], v143 offset:1024
	ds_read_b128 v[218:221], v143 offset:2048
	ds_read_b128 v[222:225], v143 offset:3072
	ds_read_b128 v[226:229], v143 offset:4096
	ds_read_b128 v[230:233], v143 offset:5120
	ds_read_b128 v[234:237], v143 offset:6144
	ds_read_b128 v[238:241], v143 offset:7168
	global_load_lds_dwordx4 v[162:163], off
	v_lshl_add_u64 v[162:163], s[22:23], 0, v[138:139]
	s_add_i32 m0, s30, 0xe000
	s_nop 0
	global_load_lds_dwordx4 v[162:163], off
	s_waitcnt vmcnt(24)
	s_waitcnt lgkmcnt(0)
	s_barrier
	s_setprio 0
	s_waitcnt lgkmcnt(0)
	v_mfma_f32_16x16x32_bf16 v[126:129], v[144:147], v[210:213], v[126:129]
	v_mfma_f32_16x16x32_bf16 v[122:125], v[172:175], v[210:213], v[122:125]
	v_mfma_f32_16x16x32_bf16 v[118:121], v[144:147], v[218:221], v[118:121]
	v_mfma_f32_16x16x32_bf16 v[114:117], v[172:175], v[218:221], v[114:117]
	v_mfma_f32_16x16x32_bf16 v[110:113], v[144:147], v[226:229], v[110:113]
	v_mfma_f32_16x16x32_bf16 v[106:109], v[172:175], v[226:229], v[106:109]
	v_mfma_f32_16x16x32_bf16 v[102:105], v[144:147], v[234:237], v[102:105]
	v_mfma_f32_16x16x32_bf16 v[98:101], v[172:175], v[234:237], v[98:101]
	v_mfma_f32_16x16x32_bf16 v[126:129], v[148:151], v[214:217], v[126:129]
	v_mfma_f32_16x16x32_bf16 v[122:125], v[190:193], v[214:217], v[122:125]
	v_mfma_f32_16x16x32_bf16 v[118:121], v[148:151], v[222:225], v[118:121]
	v_mfma_f32_16x16x32_bf16 v[114:117], v[190:193], v[222:225], v[114:117]
	v_mfma_f32_16x16x32_bf16 v[110:113], v[148:151], v[230:233], v[110:113]
	v_mfma_f32_16x16x32_bf16 v[106:109], v[190:193], v[230:233], v[106:109]
	v_mfma_f32_16x16x32_bf16 v[102:105], v[148:151], v[238:241], v[102:105]
	v_mfma_f32_16x16x32_bf16 v[98:101], v[190:193], v[238:241], v[98:101]
	v_mfma_f32_16x16x32_bf16 v[70:73], v[194:197], v[210:213], v[70:73]
	v_mfma_f32_16x16x32_bf16 v[66:69], v[202:205], v[210:213], v[66:69]
	v_mfma_f32_16x16x32_bf16 v[54:57], v[194:197], v[218:221], v[54:57]
	v_mfma_f32_16x16x32_bf16 v[50:53], v[202:205], v[218:221], v[50:53]
	v_mfma_f32_16x16x32_bf16 v[46:49], v[194:197], v[226:229], v[46:49]
	v_mfma_f32_16x16x32_bf16 v[42:45], v[202:205], v[226:229], v[42:45]
	v_mfma_f32_16x16x32_bf16 v[38:41], v[194:197], v[234:237], v[38:41]
	v_mfma_f32_16x16x32_bf16 v[34:37], v[202:205], v[234:237], v[34:37]
	v_mfma_f32_16x16x32_bf16 v[70:73], v[198:201], v[214:217], v[70:73]
	v_mfma_f32_16x16x32_bf16 v[66:69], v[206:209], v[214:217], v[66:69]
	v_mfma_f32_16x16x32_bf16 v[54:57], v[198:201], v[222:225], v[54:57]
	v_mfma_f32_16x16x32_bf16 v[50:53], v[206:209], v[222:225], v[50:53]
	v_mfma_f32_16x16x32_bf16 v[46:49], v[198:201], v[230:233], v[46:49]
	v_mfma_f32_16x16x32_bf16 v[42:45], v[206:209], v[230:233], v[42:45]
	v_mfma_f32_16x16x32_bf16 v[38:41], v[198:201], v[238:241], v[38:41]
	v_mfma_f32_16x16x32_bf16 v[34:37], v[206:209], v[238:241], v[34:37]
	s_setprio 1
	s_barrier
	s_add_i32 s3, s3, s27
	v_lshl_add_u64 v[162:163], s[0:1], 0, v[4:5]
	s_mov_b32 m0, s3
	ds_read_b128 v[210:213], v143 offset:16384
	ds_read_b128 v[214:217], v143 offset:17408
	ds_read_b128 v[218:221], v143 offset:18432
	ds_read_b128 v[222:225], v143 offset:19456
	ds_read_b128 v[226:229], v143 offset:20480
	ds_read_b128 v[230:233], v143 offset:21504
	ds_read_b128 v[234:237], v143 offset:22528
	ds_read_b128 v[238:241], v143 offset:23552
	global_load_lds_dwordx4 v[162:163], off
	s_add_i32 m0, s3, 0x2000
	s_add_u32 s4, s0, 0x80000
	v_lshl_add_u64 v[166:167], s[0:1], 0, v[130:131]
	s_addc_u32 s5, s1, 0
	s_add_i32 s3, s6, s27
	global_load_lds_dwordx4 v[166:167], off
	v_lshl_add_u64 v[176:177], s[4:5], 0, v[4:5]
	s_mov_b32 m0, s3
	v_lshl_add_u64 v[180:181], s[14:15], 0, v[132:133]
	global_load_lds_dwordx4 v[176:177], off
	v_lshl_add_u64 v[176:177], s[4:5], 0, v[130:131]
	s_add_i32 m0, s3, 0x2000
	s_nop 0
	global_load_lds_dwordx4 v[176:177], off
	v_lshl_add_u64 v[176:177], s[14:15], 0, v[134:135]
	s_mov_b32 m0, s30
	s_nop 0
	global_load_lds_dwordx4 v[176:177], off
	s_mov_b32 m0, s31
	s_nop 0
	global_load_lds_dwordx4 v[180:181], off
	s_waitcnt vmcnt(24)
	s_waitcnt lgkmcnt(0)
	s_barrier
	s_setprio 0
	s_waitcnt lgkmcnt(0)
	v_mfma_f32_16x16x32_bf16 v[94:97], v[144:147], v[210:213], v[94:97]
	v_mfma_f32_16x16x32_bf16 v[90:93], v[172:175], v[210:213], v[90:93]
	v_mfma_f32_16x16x32_bf16 v[86:89], v[144:147], v[218:221], v[86:89]
	v_mfma_f32_16x16x32_bf16 v[82:85], v[172:175], v[218:221], v[82:85]
	v_mfma_f32_16x16x32_bf16 v[78:81], v[144:147], v[226:229], v[78:81]
	v_mfma_f32_16x16x32_bf16 v[74:77], v[172:175], v[226:229], v[74:77]
	v_mfma_f32_16x16x32_bf16 v[62:65], v[144:147], v[234:237], v[62:65]
	v_mfma_f32_16x16x32_bf16 v[58:61], v[172:175], v[234:237], v[58:61]
	v_mfma_f32_16x16x32_bf16 v[94:97], v[148:151], v[214:217], v[94:97]
	v_mfma_f32_16x16x32_bf16 v[90:93], v[190:193], v[214:217], v[90:93]
	v_mfma_f32_16x16x32_bf16 v[86:89], v[148:151], v[222:225], v[86:89]
	v_mfma_f32_16x16x32_bf16 v[82:85], v[190:193], v[222:225], v[82:85]
	v_mfma_f32_16x16x32_bf16 v[78:81], v[148:151], v[230:233], v[78:81]
	v_mfma_f32_16x16x32_bf16 v[74:77], v[190:193], v[230:233], v[74:77]
	v_mfma_f32_16x16x32_bf16 v[62:65], v[148:151], v[238:241], v[62:65]
	v_mfma_f32_16x16x32_bf16 v[58:61], v[190:193], v[238:241], v[58:61]
	v_mfma_f32_16x16x32_bf16 v[30:33], v[194:197], v[210:213], v[30:33]
	v_mfma_f32_16x16x32_bf16 v[26:29], v[202:205], v[210:213], v[26:29]
	v_mfma_f32_16x16x32_bf16 v[22:25], v[194:197], v[218:221], v[22:25]
	v_mfma_f32_16x16x32_bf16 v[18:21], v[202:205], v[218:221], v[18:21]
	v_mfma_f32_16x16x32_bf16 v[14:17], v[194:197], v[226:229], v[14:17]
	v_mfma_f32_16x16x32_bf16 v[10:13], v[202:205], v[226:229], v[10:13]
	v_mfma_f32_16x16x32_bf16 v[6:9], v[194:197], v[234:237], v[6:9]
	v_mfma_f32_16x16x32_bf16 v[0:3], v[202:205], v[234:237], v[0:3]
	v_mfma_f32_16x16x32_bf16 v[30:33], v[198:201], v[214:217], v[30:33]
	v_mfma_f32_16x16x32_bf16 v[26:29], v[206:209], v[214:217], v[26:29]
	v_mfma_f32_16x16x32_bf16 v[22:25], v[198:201], v[222:225], v[22:25]
	v_mfma_f32_16x16x32_bf16 v[18:21], v[206:209], v[222:225], v[18:21]
	v_mfma_f32_16x16x32_bf16 v[14:17], v[198:201], v[230:233], v[14:17]
	v_mfma_f32_16x16x32_bf16 v[10:13], v[206:209], v[230:233], v[10:13]
	v_mfma_f32_16x16x32_bf16 v[6:9], v[198:201], v[238:241], v[6:9]
	v_mfma_f32_16x16x32_bf16 v[0:3], v[206:209], v[238:241], v[0:3]
	s_setprio 1
	s_barrier
	s_branch .Lpeelmid_124
.LBB0_124:
	s_add_u32 s0, s22, 0xfff80080
	s_addc_u32 s1, s23, -1
	s_add_i32 s3, 0, 0x10000
	s_cmp_eq_u32 s28, 28
	s_cselect_b32 s15, s2, s1
	s_cselect_b32 s14, s8, s0
	v_add_u32_e32 v162, s3, v141
	s_cselect_b32 s1, s10, s25
	s_cselect_b32 s0, s24, s9
	s_add_i32 s6, 0, 0x14000
	ds_read_b128 v[144:147], v162
	ds_read_b128 v[148:151], v162 offset:1024
	ds_read_b128 v[172:175], v162 offset:2048
	ds_read_b128 v[190:193], v162 offset:3072
	v_add_u32_e32 v162, s6, v141
	ds_read_b128 v[194:197], v162
	ds_read_b128 v[198:201], v162 offset:1024
	ds_read_b128 v[202:205], v162 offset:2048
	ds_read_b128 v[206:209], v162 offset:3072
	v_lshl_add_u64 v[162:163], s[22:23], 0, v[136:137]
	s_add_i32 m0, s30, 0xc000
	ds_read_b128 v[210:213], v143
	ds_read_b128 v[214:217], v143 offset:1024
	ds_read_b128 v[218:221], v143 offset:2048
	ds_read_b128 v[222:225], v143 offset:3072
	ds_read_b128 v[226:229], v143 offset:4096
	ds_read_b128 v[230:233], v143 offset:5120
	ds_read_b128 v[234:237], v143 offset:6144
	ds_read_b128 v[238:241], v143 offset:7168
	global_load_lds_dwordx4 v[162:163], off
	v_lshl_add_u64 v[162:163], s[22:23], 0, v[138:139]
	s_add_i32 m0, s30, 0xe000
	s_nop 0
	global_load_lds_dwordx4 v[162:163], off
	s_waitcnt vmcnt(8)
	s_waitcnt lgkmcnt(0)
	s_barrier
	s_setprio 0
	s_waitcnt lgkmcnt(0)
	v_mfma_f32_16x16x32_bf16 v[126:129], v[144:147], v[210:213], v[126:129]
	v_mfma_f32_16x16x32_bf16 v[122:125], v[172:175], v[210:213], v[122:125]
	v_mfma_f32_16x16x32_bf16 v[118:121], v[144:147], v[218:221], v[118:121]
	v_mfma_f32_16x16x32_bf16 v[114:117], v[172:175], v[218:221], v[114:117]
	v_mfma_f32_16x16x32_bf16 v[110:113], v[144:147], v[226:229], v[110:113]
	v_mfma_f32_16x16x32_bf16 v[106:109], v[172:175], v[226:229], v[106:109]
	v_mfma_f32_16x16x32_bf16 v[102:105], v[144:147], v[234:237], v[102:105]
	v_mfma_f32_16x16x32_bf16 v[98:101], v[172:175], v[234:237], v[98:101]
	v_mfma_f32_16x16x32_bf16 v[126:129], v[148:151], v[214:217], v[126:129]
	v_mfma_f32_16x16x32_bf16 v[122:125], v[190:193], v[214:217], v[122:125]
	v_mfma_f32_16x16x32_bf16 v[118:121], v[148:151], v[222:225], v[118:121]
	v_mfma_f32_16x16x32_bf16 v[114:117], v[190:193], v[222:225], v[114:117]
	v_mfma_f32_16x16x32_bf16 v[110:113], v[148:151], v[230:233], v[110:113]
	v_mfma_f32_16x16x32_bf16 v[106:109], v[190:193], v[230:233], v[106:109]
	v_mfma_f32_16x16x32_bf16 v[102:105], v[148:151], v[238:241], v[102:105]
	v_mfma_f32_16x16x32_bf16 v[98:101], v[190:193], v[238:241], v[98:101]
	v_mfma_f32_16x16x32_bf16 v[70:73], v[194:197], v[210:213], v[70:73]
	v_mfma_f32_16x16x32_bf16 v[66:69], v[202:205], v[210:213], v[66:69]
	v_mfma_f32_16x16x32_bf16 v[54:57], v[194:197], v[218:221], v[54:57]
	v_mfma_f32_16x16x32_bf16 v[50:53], v[202:205], v[218:221], v[50:53]
	v_mfma_f32_16x16x32_bf16 v[46:49], v[194:197], v[226:229], v[46:49]
	v_mfma_f32_16x16x32_bf16 v[42:45], v[202:205], v[226:229], v[42:45]
	v_mfma_f32_16x16x32_bf16 v[38:41], v[194:197], v[234:237], v[38:41]
	v_mfma_f32_16x16x32_bf16 v[34:37], v[202:205], v[234:237], v[34:37]
	v_mfma_f32_16x16x32_bf16 v[70:73], v[198:201], v[214:217], v[70:73]
	v_mfma_f32_16x16x32_bf16 v[66:69], v[206:209], v[214:217], v[66:69]
	v_mfma_f32_16x16x32_bf16 v[54:57], v[198:201], v[222:225], v[54:57]
	v_mfma_f32_16x16x32_bf16 v[50:53], v[206:209], v[222:225], v[50:53]
	v_mfma_f32_16x16x32_bf16 v[46:49], v[198:201], v[230:233], v[46:49]
	v_mfma_f32_16x16x32_bf16 v[42:45], v[206:209], v[230:233], v[42:45]
	v_mfma_f32_16x16x32_bf16 v[38:41], v[198:201], v[238:241], v[38:41]
	v_mfma_f32_16x16x32_bf16 v[34:37], v[206:209], v[238:241], v[34:37]
	s_setprio 1
	s_barrier
	s_add_i32 s3, s3, s27
	v_lshl_add_u64 v[162:163], s[0:1], 0, v[4:5]
	s_mov_b32 m0, s3
	ds_read_b128 v[210:213], v143 offset:16384
	ds_read_b128 v[214:217], v143 offset:17408
	ds_read_b128 v[218:221], v143 offset:18432
	ds_read_b128 v[222:225], v143 offset:19456
	ds_read_b128 v[226:229], v143 offset:20480
	ds_read_b128 v[230:233], v143 offset:21504
	ds_read_b128 v[234:237], v143 offset:22528
	ds_read_b128 v[238:241], v143 offset:23552
	global_load_lds_dwordx4 v[162:163], off
	s_add_i32 m0, s3, 0x2000
	s_add_u32 s4, s0, 0x80000
	v_lshl_add_u64 v[166:167], s[0:1], 0, v[130:131]
	s_addc_u32 s5, s1, 0
	s_add_i32 s3, s6, s27
	global_load_lds_dwordx4 v[166:167], off
	v_lshl_add_u64 v[176:177], s[4:5], 0, v[4:5]
	s_mov_b32 m0, s3
	v_lshl_add_u64 v[180:181], s[14:15], 0, v[132:133]
	global_load_lds_dwordx4 v[176:177], off
	v_lshl_add_u64 v[176:177], s[4:5], 0, v[130:131]
	s_add_i32 m0, s3, 0x2000
	s_nop 0
	global_load_lds_dwordx4 v[176:177], off
	v_lshl_add_u64 v[176:177], s[14:15], 0, v[134:135]
	s_mov_b32 m0, s30
	s_nop 0
	global_load_lds_dwordx4 v[176:177], off
	s_mov_b32 m0, s31
	s_nop 0
	global_load_lds_dwordx4 v[180:181], off
	s_waitcnt vmcnt(8)
	s_waitcnt lgkmcnt(0)
	s_barrier
	s_setprio 0
	s_waitcnt lgkmcnt(0)
	v_mfma_f32_16x16x32_bf16 v[94:97], v[144:147], v[210:213], v[94:97]
	v_mfma_f32_16x16x32_bf16 v[90:93], v[172:175], v[210:213], v[90:93]
	v_mfma_f32_16x16x32_bf16 v[86:89], v[144:147], v[218:221], v[86:89]
	v_mfma_f32_16x16x32_bf16 v[82:85], v[172:175], v[218:221], v[82:85]
	v_mfma_f32_16x16x32_bf16 v[78:81], v[144:147], v[226:229], v[78:81]
	v_mfma_f32_16x16x32_bf16 v[74:77], v[172:175], v[226:229], v[74:77]
	v_mfma_f32_16x16x32_bf16 v[62:65], v[144:147], v[234:237], v[62:65]
	v_mfma_f32_16x16x32_bf16 v[58:61], v[172:175], v[234:237], v[58:61]
	v_mfma_f32_16x16x32_bf16 v[94:97], v[148:151], v[214:217], v[94:97]
	v_mfma_f32_16x16x32_bf16 v[90:93], v[190:193], v[214:217], v[90:93]
	v_mfma_f32_16x16x32_bf16 v[86:89], v[148:151], v[222:225], v[86:89]
	v_mfma_f32_16x16x32_bf16 v[82:85], v[190:193], v[222:225], v[82:85]
	v_mfma_f32_16x16x32_bf16 v[78:81], v[148:151], v[230:233], v[78:81]
	v_mfma_f32_16x16x32_bf16 v[74:77], v[190:193], v[230:233], v[74:77]
	v_mfma_f32_16x16x32_bf16 v[62:65], v[148:151], v[238:241], v[62:65]
	v_mfma_f32_16x16x32_bf16 v[58:61], v[190:193], v[238:241], v[58:61]
	v_mfma_f32_16x16x32_bf16 v[30:33], v[194:197], v[210:213], v[30:33]
	v_mfma_f32_16x16x32_bf16 v[26:29], v[202:205], v[210:213], v[26:29]
	v_mfma_f32_16x16x32_bf16 v[22:25], v[194:197], v[218:221], v[22:25]
	v_mfma_f32_16x16x32_bf16 v[18:21], v[202:205], v[218:221], v[18:21]
	v_mfma_f32_16x16x32_bf16 v[14:17], v[194:197], v[226:229], v[14:17]
	v_mfma_f32_16x16x32_bf16 v[10:13], v[202:205], v[226:229], v[10:13]
	v_mfma_f32_16x16x32_bf16 v[6:9], v[194:197], v[234:237], v[6:9]
	v_mfma_f32_16x16x32_bf16 v[0:3], v[202:205], v[234:237], v[0:3]
	v_mfma_f32_16x16x32_bf16 v[30:33], v[198:201], v[214:217], v[30:33]
	v_mfma_f32_16x16x32_bf16 v[26:29], v[206:209], v[214:217], v[26:29]
	v_mfma_f32_16x16x32_bf16 v[22:25], v[198:201], v[222:225], v[22:25]
	v_mfma_f32_16x16x32_bf16 v[18:21], v[206:209], v[222:225], v[18:21]
	v_mfma_f32_16x16x32_bf16 v[14:17], v[198:201], v[230:233], v[14:17]
	v_mfma_f32_16x16x32_bf16 v[10:13], v[206:209], v[230:233], v[10:13]
	v_mfma_f32_16x16x32_bf16 v[6:9], v[198:201], v[238:241], v[6:9]
	v_mfma_f32_16x16x32_bf16 v[0:3], v[206:209], v[238:241], v[0:3]
	s_setprio 1
	s_barrier
.Lpeelmid_124:
	s_add_i32 s3, 0, 0x18000
	v_add_u32_e32 v164, s3, v141
	s_add_i32 s6, 0, 0x1c000
	ds_read_b128 v[144:147], v164
	ds_read_b128 v[148:151], v164 offset:1024
	ds_read_b128 v[172:175], v164 offset:2048
	ds_read_b128 v[190:193], v164 offset:3072
	v_add_u32_e32 v164, s6, v141
	ds_read_b128 v[194:197], v164
	ds_read_b128 v[198:201], v164 offset:1024
	ds_read_b128 v[202:205], v164 offset:2048
	ds_read_b128 v[206:209], v164 offset:3072
	s_add_u32 s4, s14, 0x80000
	s_addc_u32 s5, s15, 0
	s_mov_b32 m0, s34
	v_lshl_add_u64 v[242:243], s[4:5], 0, v[134:135]
	ds_read_b128 v[210:213], v143 offset:32768
	ds_read_b128 v[214:217], v143 offset:33792
	ds_read_b128 v[218:221], v143 offset:34816
	ds_read_b128 v[222:225], v143 offset:35840
	ds_read_b128 v[226:229], v143 offset:36864
	ds_read_b128 v[230:233], v143 offset:37888
	ds_read_b128 v[234:237], v143 offset:38912
	ds_read_b128 v[238:241], v143 offset:39936
	global_load_lds_dwordx4 v[242:243], off
	v_lshl_add_u64 v[242:243], s[4:5], 0, v[132:133]
	s_mov_b32 m0, s35
	s_nop 0
	global_load_lds_dwordx4 v[242:243], off
	s_waitcnt vmcnt(8)
	s_waitcnt lgkmcnt(0)
	s_barrier
	s_setprio 0
	s_waitcnt lgkmcnt(0)
	v_mfma_f32_16x16x32_bf16 v[126:129], v[144:147], v[210:213], v[126:129]
	v_mfma_f32_16x16x32_bf16 v[122:125], v[172:175], v[210:213], v[122:125]
	v_mfma_f32_16x16x32_bf16 v[118:121], v[144:147], v[218:221], v[118:121]
	v_mfma_f32_16x16x32_bf16 v[114:117], v[172:175], v[218:221], v[114:117]
	v_mfma_f32_16x16x32_bf16 v[110:113], v[144:147], v[226:229], v[110:113]
	v_mfma_f32_16x16x32_bf16 v[106:109], v[172:175], v[226:229], v[106:109]
	v_mfma_f32_16x16x32_bf16 v[102:105], v[144:147], v[234:237], v[102:105]
	v_mfma_f32_16x16x32_bf16 v[98:101], v[172:175], v[234:237], v[98:101]
	v_mfma_f32_16x16x32_bf16 v[126:129], v[148:151], v[214:217], v[126:129]
	v_mfma_f32_16x16x32_bf16 v[122:125], v[190:193], v[214:217], v[122:125]
	v_mfma_f32_16x16x32_bf16 v[118:121], v[148:151], v[222:225], v[118:121]
	v_mfma_f32_16x16x32_bf16 v[114:117], v[190:193], v[222:225], v[114:117]
	v_mfma_f32_16x16x32_bf16 v[110:113], v[148:151], v[230:233], v[110:113]
	v_mfma_f32_16x16x32_bf16 v[106:109], v[190:193], v[230:233], v[106:109]
	v_mfma_f32_16x16x32_bf16 v[102:105], v[148:151], v[238:241], v[102:105]
	v_mfma_f32_16x16x32_bf16 v[98:101], v[190:193], v[238:241], v[98:101]
	v_mfma_f32_16x16x32_bf16 v[70:73], v[194:197], v[210:213], v[70:73]
	v_mfma_f32_16x16x32_bf16 v[66:69], v[202:205], v[210:213], v[66:69]
	v_mfma_f32_16x16x32_bf16 v[54:57], v[194:197], v[218:221], v[54:57]
	v_mfma_f32_16x16x32_bf16 v[50:53], v[202:205], v[218:221], v[50:53]
	v_mfma_f32_16x16x32_bf16 v[46:49], v[194:197], v[226:229], v[46:49]
	v_mfma_f32_16x16x32_bf16 v[42:45], v[202:205], v[226:229], v[42:45]
	v_mfma_f32_16x16x32_bf16 v[38:41], v[194:197], v[234:237], v[38:41]
	v_mfma_f32_16x16x32_bf16 v[34:37], v[202:205], v[234:237], v[34:37]
	v_mfma_f32_16x16x32_bf16 v[70:73], v[198:201], v[214:217], v[70:73]
	v_mfma_f32_16x16x32_bf16 v[66:69], v[206:209], v[214:217], v[66:69]
	v_mfma_f32_16x16x32_bf16 v[54:57], v[198:201], v[222:225], v[54:57]
	v_mfma_f32_16x16x32_bf16 v[50:53], v[206:209], v[222:225], v[50:53]
	v_mfma_f32_16x16x32_bf16 v[46:49], v[198:201], v[230:233], v[46:49]
	v_mfma_f32_16x16x32_bf16 v[42:45], v[206:209], v[230:233], v[42:45]
	v_mfma_f32_16x16x32_bf16 v[38:41], v[198:201], v[238:241], v[38:41]
	v_mfma_f32_16x16x32_bf16 v[34:37], v[206:209], v[238:241], v[34:37]
	s_setprio 1
	s_barrier
	s_add_i32 s3, s3, s27
	v_lshl_add_u64 v[162:163], v[162:163], 0, s[70:71]
	s_mov_b32 m0, s3
	ds_read_b128 v[210:213], v143 offset:49152
	ds_read_b128 v[214:217], v143 offset:50176
	ds_read_b128 v[218:221], v143 offset:51200
	ds_read_b128 v[222:225], v143 offset:52224
	ds_read_b128 v[226:229], v143 offset:53248
	ds_read_b128 v[230:233], v143 offset:54272
	ds_read_b128 v[234:237], v143 offset:55296
	ds_read_b128 v[238:241], v143 offset:56320
	global_load_lds_dwordx4 v[162:163], off
	s_add_i32 m0, s3, 0x2000
	s_add_u32 s0, s0, 0x80080
	v_lshl_add_u64 v[162:163], v[166:167], 0, s[70:71]
	s_addc_u32 s1, s1, 0
	s_add_i32 s3, s6, s27
	global_load_lds_dwordx4 v[162:163], off
	v_lshl_add_u64 v[162:163], s[0:1], 0, v[4:5]
	s_mov_b32 m0, s3
	s_nop 0
	global_load_lds_dwordx4 v[162:163], off
	v_lshl_add_u64 v[162:163], s[0:1], 0, v[130:131]
	s_add_i32 m0, s3, 0x2000
	s_nop 0
	global_load_lds_dwordx4 v[162:163], off
	v_lshl_add_u64 v[162:163], v[176:177], 0, s[70:71]
	s_mov_b32 m0, s36
	s_nop 0
	global_load_lds_dwordx4 v[162:163], off
	v_lshl_add_u64 v[162:163], v[180:181], 0, s[70:71]
	s_mov_b32 m0, s37
	s_nop 0
	global_load_lds_dwordx4 v[162:163], off
	s_waitcnt vmcnt(8)
	s_waitcnt lgkmcnt(0)
	s_barrier
	s_setprio 0
	s_waitcnt lgkmcnt(0)
	v_mfma_f32_16x16x32_bf16 v[94:97], v[144:147], v[210:213], v[94:97]
	v_mfma_f32_16x16x32_bf16 v[90:93], v[172:175], v[210:213], v[90:93]
	v_mfma_f32_16x16x32_bf16 v[86:89], v[144:147], v[218:221], v[86:89]
	v_mfma_f32_16x16x32_bf16 v[82:85], v[172:175], v[218:221], v[82:85]
	v_mfma_f32_16x16x32_bf16 v[78:81], v[144:147], v[226:229], v[78:81]
	v_mfma_f32_16x16x32_bf16 v[74:77], v[172:175], v[226:229], v[74:77]
	v_mfma_f32_16x16x32_bf16 v[62:65], v[144:147], v[234:237], v[62:65]
	v_mfma_f32_16x16x32_bf16 v[58:61], v[172:175], v[234:237], v[58:61]
	v_mfma_f32_16x16x32_bf16 v[94:97], v[148:151], v[214:217], v[94:97]
	v_mfma_f32_16x16x32_bf16 v[90:93], v[190:193], v[214:217], v[90:93]
	v_mfma_f32_16x16x32_bf16 v[86:89], v[148:151], v[222:225], v[86:89]
	v_mfma_f32_16x16x32_bf16 v[82:85], v[190:193], v[222:225], v[82:85]
	v_mfma_f32_16x16x32_bf16 v[78:81], v[148:151], v[230:233], v[78:81]
	v_mfma_f32_16x16x32_bf16 v[74:77], v[190:193], v[230:233], v[74:77]
	v_mfma_f32_16x16x32_bf16 v[62:65], v[148:151], v[238:241], v[62:65]
	v_mfma_f32_16x16x32_bf16 v[58:61], v[190:193], v[238:241], v[58:61]
	v_mfma_f32_16x16x32_bf16 v[30:33], v[194:197], v[210:213], v[30:33]
	v_mfma_f32_16x16x32_bf16 v[26:29], v[202:205], v[210:213], v[26:29]
	v_mfma_f32_16x16x32_bf16 v[22:25], v[194:197], v[218:221], v[22:25]
	v_mfma_f32_16x16x32_bf16 v[18:21], v[202:205], v[218:221], v[18:21]
	v_mfma_f32_16x16x32_bf16 v[14:17], v[194:197], v[226:229], v[14:17]
	v_mfma_f32_16x16x32_bf16 v[10:13], v[202:205], v[226:229], v[10:13]
	v_mfma_f32_16x16x32_bf16 v[6:9], v[194:197], v[234:237], v[6:9]
	v_mfma_f32_16x16x32_bf16 v[0:3], v[202:205], v[234:237], v[0:3]
	v_mfma_f32_16x16x32_bf16 v[30:33], v[198:201], v[214:217], v[30:33]
	v_mfma_f32_16x16x32_bf16 v[26:29], v[206:209], v[214:217], v[26:29]
	v_mfma_f32_16x16x32_bf16 v[22:25], v[198:201], v[222:225], v[22:25]
	v_mfma_f32_16x16x32_bf16 v[18:21], v[206:209], v[222:225], v[18:21]
	v_mfma_f32_16x16x32_bf16 v[14:17], v[198:201], v[230:233], v[14:17]
	v_mfma_f32_16x16x32_bf16 v[10:13], v[206:209], v[230:233], v[10:13]
	v_mfma_f32_16x16x32_bf16 v[6:9], v[198:201], v[238:241], v[6:9]
	v_mfma_f32_16x16x32_bf16 v[0:3], v[206:209], v[238:241], v[0:3]
	s_setprio 1
	s_barrier
	s_add_i32 s28, s28, 2
	s_add_u32 s22, s22, 0x100
	s_addc_u32 s23, s23, 0
	s_add_u32 s9, s9, 0x100
	s_addc_u32 s25, s25, 0
	s_cmp_gt_u32 s28, 29
	s_cbranch_scc0 .LBB0_124
	s_and_b64 vcc, exec, s[42:43]
	s_cbranch_vccz .LBB0_127
	s_barrier

.LBB0_162:
	s_ashr_i32 s49, s48, 31
	s_lshl_b64 s[2:3], s[48:49], 20
	v_readlane_b32 s4, v253, 61
	v_readlane_b32 s5, v253, 62
	s_add_u32 s82, s4, s2
	s_addc_u32 s83, s5, s3
	s_and_b64 s[2:3], s[42:43], exec
	s_cselect_b32 s2, s83, s1
	s_cselect_b32 s8, s82, s0
	s_add_u32 s22, s14, 0x80080
	s_addc_u32 s23, s15, 0
	s_add_u32 s9, s0, 0x100
	v_mov_b32_e32 v0, 0
	s_addc_u32 s10, s1, 0
	s_mov_b32 s24, -2
	v_mov_b32_e32 v1, v0
	v_mov_b32_e32 v2, v0
	v_mov_b32_e32 v3, v0
	v_mov_b32_e32 v6, v0
	s_waitcnt lgkmcnt(0)
	v_mov_b32_e32 v7, v0
	v_mov_b32_e32 v8, v0
	v_mov_b32_e32 v9, v0
	v_mov_b32_e32 v18, v0
	v_mov_b32_e32 v19, v0
	v_mov_b32_e32 v20, v0
	v_mov_b32_e32 v21, v0
	v_mov_b32_e32 v22, v0
	v_mov_b32_e32 v23, v0
	v_mov_b32_e32 v24, v0
	v_mov_b32_e32 v25, v0
	v_mov_b32_e32 v34, v0
	v_mov_b32_e32 v35, v0
	v_mov_b32_e32 v36, v0
	v_mov_b32_e32 v37, v0
	v_mov_b32_e32 v38, v0
	v_mov_b32_e32 v39, v0
	v_mov_b32_e32 v40, v0
	v_mov_b32_e32 v41, v0
	v_mov_b32_e32 v50, v0
	v_mov_b32_e32 v51, v0
	v_mov_b32_e32 v52, v0
	v_mov_b32_e32 v53, v0
	v_mov_b32_e32 v54, v0
	v_mov_b32_e32 v55, v0
	v_mov_b32_e32 v56, v0
	v_mov_b32_e32 v57, v0
	v_mov_b32_e32 v10, v0
	v_mov_b32_e32 v11, v0
	v_mov_b32_e32 v12, v0
	v_mov_b32_e32 v13, v0
	v_mov_b32_e32 v14, v0
	v_mov_b32_e32 v15, v0
	v_mov_b32_e32 v16, v0
	v_mov_b32_e32 v17, v0
	v_mov_b32_e32 v26, v0
	v_mov_b32_e32 v27, v0
	v_mov_b32_e32 v28, v0
	v_mov_b32_e32 v29, v0
	v_mov_b32_e32 v30, v0
	v_mov_b32_e32 v31, v0
	v_mov_b32_e32 v32, v0
	v_mov_b32_e32 v33, v0
	v_mov_b32_e32 v42, v0
	v_mov_b32_e32 v43, v0
	v_mov_b32_e32 v44, v0
	v_mov_b32_e32 v45, v0
	v_mov_b32_e32 v46, v0
	v_mov_b32_e32 v47, v0
	v_mov_b32_e32 v48, v0
	v_mov_b32_e32 v49, v0
	v_mov_b32_e32 v58, v0
	v_mov_b32_e32 v59, v0
	v_mov_b32_e32 v60, v0
	v_mov_b32_e32 v61, v0
	v_mov_b32_e32 v62, v0
	v_mov_b32_e32 v63, v0
	v_mov_b32_e32 v64, v0
	v_mov_b32_e32 v65, v0
	v_mov_b32_e32 v66, v0
	v_mov_b32_e32 v67, v0
	v_mov_b32_e32 v68, v0
	v_mov_b32_e32 v69, v0
	v_mov_b32_e32 v70, v0
	v_mov_b32_e32 v71, v0
	v_mov_b32_e32 v72, v0
	v_mov_b32_e32 v73, v0
	v_mov_b32_e32 v82, v0
	v_mov_b32_e32 v83, v0
	v_mov_b32_e32 v84, v0
	v_mov_b32_e32 v85, v0
	v_mov_b32_e32 v86, v0
	v_mov_b32_e32 v87, v0
	v_mov_b32_e32 v88, v0
	v_mov_b32_e32 v89, v0
	v_mov_b32_e32 v98, v0
	v_mov_b32_e32 v99, v0
	v_mov_b32_e32 v100, v0
	v_mov_b32_e32 v101, v0
	v_mov_b32_e32 v102, v0
	v_mov_b32_e32 v103, v0
	v_mov_b32_e32 v104, v0
	v_mov_b32_e32 v105, v0
	v_mov_b32_e32 v114, v0
	v_mov_b32_e32 v115, v0
	v_mov_b32_e32 v116, v0
	v_mov_b32_e32 v117, v0
	v_mov_b32_e32 v118, v0
	v_mov_b32_e32 v119, v0
	v_mov_b32_e32 v120, v0
	v_mov_b32_e32 v121, v0
	v_mov_b32_e32 v74, v0
	v_mov_b32_e32 v75, v0
	v_mov_b32_e32 v76, v0
	v_mov_b32_e32 v77, v0
	v_mov_b32_e32 v78, v0
	v_mov_b32_e32 v79, v0
	v_mov_b32_e32 v80, v0
	v_mov_b32_e32 v81, v0
	v_mov_b32_e32 v90, v0
	v_mov_b32_e32 v91, v0
	v_mov_b32_e32 v92, v0
	v_mov_b32_e32 v93, v0
	v_mov_b32_e32 v94, v0
	v_mov_b32_e32 v95, v0
	v_mov_b32_e32 v96, v0
	v_mov_b32_e32 v97, v0
	v_mov_b32_e32 v106, v0
	v_mov_b32_e32 v107, v0
	v_mov_b32_e32 v108, v0
	v_mov_b32_e32 v109, v0
	v_mov_b32_e32 v110, v0
	v_mov_b32_e32 v111, v0
	v_mov_b32_e32 v112, v0
	v_mov_b32_e32 v113, v0
	v_mov_b32_e32 v122, v0
	v_mov_b32_e32 v123, v0
	v_mov_b32_e32 v124, v0
	v_mov_b32_e32 v125, v0
	v_mov_b32_e32 v126, v0
	v_mov_b32_e32 v127, v0
	v_mov_b32_e32 v128, v0
	v_mov_b32_e32 v129, v0
	s_cmp_eq_u32 s37, 1
	s_cbranch_scc1 .LBB0_163
	s_add_u32 s0, s22, 0xfff80080
	s_addc_u32 s1, s23, -1
	s_add_i32 s3, 0, 0x10000
	s_cmp_eq_u32 s24, 28
	s_cselect_b32 s15, s79, s1
	s_cselect_b32 s14, s78, s0
	v_add_u32_e32 v162, s3, v145
	s_cselect_b32 s1, s2, s10
	s_cselect_b32 s0, s8, s9
	s_add_i32 s6, 0, 0x14000
	ds_read_b128 v[140:143], v162
	ds_read_b128 v[148:151], v162 offset:1024
	ds_read_b128 v[172:175], v162 offset:2048
	ds_read_b128 v[190:193], v162 offset:3072
	v_add_u32_e32 v162, s6, v145
	ds_read_b128 v[194:197], v162
	ds_read_b128 v[198:201], v162 offset:1024
	ds_read_b128 v[202:205], v162 offset:2048
	ds_read_b128 v[206:209], v162 offset:3072
	v_lshl_add_u64 v[162:163], s[22:23], 0, v[136:137]
	s_add_i32 m0, s26, 0xc000
	ds_read_b128 v[210:213], v147
	ds_read_b128 v[214:217], v147 offset:1024
	ds_read_b128 v[218:221], v147 offset:2048
	ds_read_b128 v[222:225], v147 offset:3072
	ds_read_b128 v[226:229], v147 offset:4096
	ds_read_b128 v[230:233], v147 offset:5120
	ds_read_b128 v[234:237], v147 offset:6144
	ds_read_b128 v[238:241], v147 offset:7168
	global_load_lds_dwordx4 v[162:163], off
	v_lshl_add_u64 v[162:163], s[22:23], 0, v[138:139]
	s_add_i32 m0, s26, 0xe000
	s_nop 0
	global_load_lds_dwordx4 v[162:163], off
	s_waitcnt vmcnt(24)
	s_waitcnt lgkmcnt(0)
	s_barrier
	s_setprio 0
	s_waitcnt lgkmcnt(0)
	v_mfma_f32_16x16x32_bf16 v[126:129], v[140:143], v[210:213], v[126:129]
	v_mfma_f32_16x16x32_bf16 v[122:125], v[172:175], v[210:213], v[122:125]
	v_mfma_f32_16x16x32_bf16 v[110:113], v[140:143], v[218:221], v[110:113]
	v_mfma_f32_16x16x32_bf16 v[106:109], v[172:175], v[218:221], v[106:109]
	v_mfma_f32_16x16x32_bf16 v[94:97], v[140:143], v[226:229], v[94:97]
	v_mfma_f32_16x16x32_bf16 v[90:93], v[172:175], v[226:229], v[90:93]
	v_mfma_f32_16x16x32_bf16 v[78:81], v[140:143], v[234:237], v[78:81]
	v_mfma_f32_16x16x32_bf16 v[74:77], v[172:175], v[234:237], v[74:77]
	v_mfma_f32_16x16x32_bf16 v[126:129], v[148:151], v[214:217], v[126:129]
	v_mfma_f32_16x16x32_bf16 v[122:125], v[190:193], v[214:217], v[122:125]
	v_mfma_f32_16x16x32_bf16 v[110:113], v[148:151], v[222:225], v[110:113]
	v_mfma_f32_16x16x32_bf16 v[106:109], v[190:193], v[222:225], v[106:109]
	v_mfma_f32_16x16x32_bf16 v[94:97], v[148:151], v[230:233], v[94:97]
	v_mfma_f32_16x16x32_bf16 v[90:93], v[190:193], v[230:233], v[90:93]
	v_mfma_f32_16x16x32_bf16 v[78:81], v[148:151], v[238:241], v[78:81]
	v_mfma_f32_16x16x32_bf16 v[74:77], v[190:193], v[238:241], v[74:77]
	v_mfma_f32_16x16x32_bf16 v[118:121], v[194:197], v[210:213], v[118:121]
	v_mfma_f32_16x16x32_bf16 v[114:117], v[202:205], v[210:213], v[114:117]
	v_mfma_f32_16x16x32_bf16 v[102:105], v[194:197], v[218:221], v[102:105]
	v_mfma_f32_16x16x32_bf16 v[98:101], v[202:205], v[218:221], v[98:101]
	v_mfma_f32_16x16x32_bf16 v[86:89], v[194:197], v[226:229], v[86:89]
	v_mfma_f32_16x16x32_bf16 v[82:85], v[202:205], v[226:229], v[82:85]
	v_mfma_f32_16x16x32_bf16 v[70:73], v[194:197], v[234:237], v[70:73]
	v_mfma_f32_16x16x32_bf16 v[66:69], v[202:205], v[234:237], v[66:69]
	v_mfma_f32_16x16x32_bf16 v[118:121], v[198:201], v[214:217], v[118:121]
	v_mfma_f32_16x16x32_bf16 v[114:117], v[206:209], v[214:217], v[114:117]
	v_mfma_f32_16x16x32_bf16 v[102:105], v[198:201], v[222:225], v[102:105]
	v_mfma_f32_16x16x32_bf16 v[98:101], v[206:209], v[222:225], v[98:101]
	v_mfma_f32_16x16x32_bf16 v[86:89], v[198:201], v[230:233], v[86:89]
	v_mfma_f32_16x16x32_bf16 v[82:85], v[206:209], v[230:233], v[82:85]
	v_mfma_f32_16x16x32_bf16 v[70:73], v[198:201], v[238:241], v[70:73]
	v_mfma_f32_16x16x32_bf16 v[66:69], v[206:209], v[238:241], v[66:69]
	s_setprio 1
	s_barrier
	s_add_i32 s3, s3, s11
	v_lshl_add_u64 v[162:163], s[0:1], 0, v[4:5]
	s_mov_b32 m0, s3
	ds_read_b128 v[210:213], v147 offset:16384
	ds_read_b128 v[214:217], v147 offset:17408
	ds_read_b128 v[218:221], v147 offset:18432
	ds_read_b128 v[222:225], v147 offset:19456
	ds_read_b128 v[226:229], v147 offset:20480
	ds_read_b128 v[230:233], v147 offset:21504
	ds_read_b128 v[234:237], v147 offset:22528
	ds_read_b128 v[238:241], v147 offset:23552
	global_load_lds_dwordx4 v[162:163], off
	s_add_i32 m0, s3, 0x2000
	s_add_u32 s4, s0, 0x80000
	v_lshl_add_u64 v[166:167], s[0:1], 0, v[130:131]
	s_addc_u32 s5, s1, 0
	s_add_i32 s3, s6, s11
	global_load_lds_dwordx4 v[166:167], off
	v_lshl_add_u64 v[176:177], s[4:5], 0, v[4:5]
	s_mov_b32 m0, s3
	v_lshl_add_u64 v[180:181], s[14:15], 0, v[132:133]
	global_load_lds_dwordx4 v[176:177], off
	v_lshl_add_u64 v[176:177], s[4:5], 0, v[130:131]
	s_add_i32 m0, s3, 0x2000
	s_nop 0
	global_load_lds_dwordx4 v[176:177], off
	v_lshl_add_u64 v[176:177], s[14:15], 0, v[134:135]
	s_mov_b32 m0, s26
	s_nop 0
	global_load_lds_dwordx4 v[176:177], off
	s_mov_b32 m0, s27
	s_nop 0
	global_load_lds_dwordx4 v[180:181], off
	s_waitcnt vmcnt(24)
	s_waitcnt lgkmcnt(0)
	s_barrier
	s_setprio 0
	s_waitcnt lgkmcnt(0)
	v_mfma_f32_16x16x32_bf16 v[62:65], v[140:143], v[210:213], v[62:65]
	v_mfma_f32_16x16x32_bf16 v[58:61], v[172:175], v[210:213], v[58:61]
	v_mfma_f32_16x16x32_bf16 v[46:49], v[140:143], v[218:221], v[46:49]
	v_mfma_f32_16x16x32_bf16 v[42:45], v[172:175], v[218:221], v[42:45]
	v_mfma_f32_16x16x32_bf16 v[30:33], v[140:143], v[226:229], v[30:33]
	v_mfma_f32_16x16x32_bf16 v[26:29], v[172:175], v[226:229], v[26:29]
	v_mfma_f32_16x16x32_bf16 v[14:17], v[140:143], v[234:237], v[14:17]
	v_mfma_f32_16x16x32_bf16 v[10:13], v[172:175], v[234:237], v[10:13]
	v_mfma_f32_16x16x32_bf16 v[62:65], v[148:151], v[214:217], v[62:65]
	v_mfma_f32_16x16x32_bf16 v[58:61], v[190:193], v[214:217], v[58:61]
	v_mfma_f32_16x16x32_bf16 v[46:49], v[148:151], v[222:225], v[46:49]
	v_mfma_f32_16x16x32_bf16 v[42:45], v[190:193], v[222:225], v[42:45]
	v_mfma_f32_16x16x32_bf16 v[30:33], v[148:151], v[230:233], v[30:33]
	v_mfma_f32_16x16x32_bf16 v[26:29], v[190:193], v[230:233], v[26:29]
	v_mfma_f32_16x16x32_bf16 v[14:17], v[148:151], v[238:241], v[14:17]
	v_mfma_f32_16x16x32_bf16 v[10:13], v[190:193], v[238:241], v[10:13]
	v_mfma_f32_16x16x32_bf16 v[54:57], v[194:197], v[210:213], v[54:57]
	v_mfma_f32_16x16x32_bf16 v[50:53], v[202:205], v[210:213], v[50:53]
	v_mfma_f32_16x16x32_bf16 v[38:41], v[194:197], v[218:221], v[38:41]
	v_mfma_f32_16x16x32_bf16 v[34:37], v[202:205], v[218:221], v[34:37]
	v_mfma_f32_16x16x32_bf16 v[22:25], v[194:197], v[226:229], v[22:25]
	v_mfma_f32_16x16x32_bf16 v[18:21], v[202:205], v[226:229], v[18:21]
	v_mfma_f32_16x16x32_bf16 v[6:9], v[194:197], v[234:237], v[6:9]
	v_mfma_f32_16x16x32_bf16 v[0:3], v[202:205], v[234:237], v[0:3]
	v_mfma_f32_16x16x32_bf16 v[54:57], v[198:201], v[214:217], v[54:57]
	v_mfma_f32_16x16x32_bf16 v[50:53], v[206:209], v[214:217], v[50:53]
	v_mfma_f32_16x16x32_bf16 v[38:41], v[198:201], v[222:225], v[38:41]
	v_mfma_f32_16x16x32_bf16 v[34:37], v[206:209], v[222:225], v[34:37]
	v_mfma_f32_16x16x32_bf16 v[22:25], v[198:201], v[230:233], v[22:25]
	v_mfma_f32_16x16x32_bf16 v[18:21], v[206:209], v[230:233], v[18:21]
	v_mfma_f32_16x16x32_bf16 v[6:9], v[198:201], v[238:241], v[6:9]
	v_mfma_f32_16x16x32_bf16 v[0:3], v[206:209], v[238:241], v[0:3]
	s_setprio 1
	s_barrier
	s_branch .Lpeelmid_163
.LBB0_163:
	s_add_u32 s0, s22, 0xfff80080
	s_addc_u32 s1, s23, -1
	s_add_i32 s3, 0, 0x10000
	s_cmp_eq_u32 s24, 28
	s_cselect_b32 s15, s79, s1
	s_cselect_b32 s14, s78, s0
	v_add_u32_e32 v162, s3, v145
	s_cselect_b32 s1, s2, s10
	s_cselect_b32 s0, s8, s9
	s_add_i32 s6, 0, 0x14000
	ds_read_b128 v[140:143], v162
	ds_read_b128 v[148:151], v162 offset:1024
	ds_read_b128 v[172:175], v162 offset:2048
	ds_read_b128 v[190:193], v162 offset:3072
	v_add_u32_e32 v162, s6, v145
	ds_read_b128 v[194:197], v162
	ds_read_b128 v[198:201], v162 offset:1024
	ds_read_b128 v[202:205], v162 offset:2048
	ds_read_b128 v[206:209], v162 offset:3072
	v_lshl_add_u64 v[162:163], s[22:23], 0, v[136:137]
	s_add_i32 m0, s26, 0xc000
	ds_read_b128 v[210:213], v147
	ds_read_b128 v[214:217], v147 offset:1024
	ds_read_b128 v[218:221], v147 offset:2048
	ds_read_b128 v[222:225], v147 offset:3072
	ds_read_b128 v[226:229], v147 offset:4096
	ds_read_b128 v[230:233], v147 offset:5120
	ds_read_b128 v[234:237], v147 offset:6144
	ds_read_b128 v[238:241], v147 offset:7168
	global_load_lds_dwordx4 v[162:163], off
	v_lshl_add_u64 v[162:163], s[22:23], 0, v[138:139]
	s_add_i32 m0, s26, 0xe000
	s_nop 0
	global_load_lds_dwordx4 v[162:163], off
	s_waitcnt vmcnt(8)
	s_waitcnt lgkmcnt(0)
	s_barrier
	s_setprio 0
	s_waitcnt lgkmcnt(0)
	v_mfma_f32_16x16x32_bf16 v[126:129], v[140:143], v[210:213], v[126:129]
	v_mfma_f32_16x16x32_bf16 v[122:125], v[172:175], v[210:213], v[122:125]
	v_mfma_f32_16x16x32_bf16 v[110:113], v[140:143], v[218:221], v[110:113]
	v_mfma_f32_16x16x32_bf16 v[106:109], v[172:175], v[218:221], v[106:109]
	v_mfma_f32_16x16x32_bf16 v[94:97], v[140:143], v[226:229], v[94:97]
	v_mfma_f32_16x16x32_bf16 v[90:93], v[172:175], v[226:229], v[90:93]
	v_mfma_f32_16x16x32_bf16 v[78:81], v[140:143], v[234:237], v[78:81]
	v_mfma_f32_16x16x32_bf16 v[74:77], v[172:175], v[234:237], v[74:77]
	v_mfma_f32_16x16x32_bf16 v[126:129], v[148:151], v[214:217], v[126:129]
	v_mfma_f32_16x16x32_bf16 v[122:125], v[190:193], v[214:217], v[122:125]
	v_mfma_f32_16x16x32_bf16 v[110:113], v[148:151], v[222:225], v[110:113]
	v_mfma_f32_16x16x32_bf16 v[106:109], v[190:193], v[222:225], v[106:109]
	v_mfma_f32_16x16x32_bf16 v[94:97], v[148:151], v[230:233], v[94:97]
	v_mfma_f32_16x16x32_bf16 v[90:93], v[190:193], v[230:233], v[90:93]
	v_mfma_f32_16x16x32_bf16 v[78:81], v[148:151], v[238:241], v[78:81]
	v_mfma_f32_16x16x32_bf16 v[74:77], v[190:193], v[238:241], v[74:77]
	v_mfma_f32_16x16x32_bf16 v[118:121], v[194:197], v[210:213], v[118:121]
	v_mfma_f32_16x16x32_bf16 v[114:117], v[202:205], v[210:213], v[114:117]
	v_mfma_f32_16x16x32_bf16 v[102:105], v[194:197], v[218:221], v[102:105]
	v_mfma_f32_16x16x32_bf16 v[98:101], v[202:205], v[218:221], v[98:101]
	v_mfma_f32_16x16x32_bf16 v[86:89], v[194:197], v[226:229], v[86:89]
	v_mfma_f32_16x16x32_bf16 v[82:85], v[202:205], v[226:229], v[82:85]
	v_mfma_f32_16x16x32_bf16 v[70:73], v[194:197], v[234:237], v[70:73]
	v_mfma_f32_16x16x32_bf16 v[66:69], v[202:205], v[234:237], v[66:69]
	v_mfma_f32_16x16x32_bf16 v[118:121], v[198:201], v[214:217], v[118:121]
	v_mfma_f32_16x16x32_bf16 v[114:117], v[206:209], v[214:217], v[114:117]
	v_mfma_f32_16x16x32_bf16 v[102:105], v[198:201], v[222:225], v[102:105]
	v_mfma_f32_16x16x32_bf16 v[98:101], v[206:209], v[222:225], v[98:101]
	v_mfma_f32_16x16x32_bf16 v[86:89], v[198:201], v[230:233], v[86:89]
	v_mfma_f32_16x16x32_bf16 v[82:85], v[206:209], v[230:233], v[82:85]
	v_mfma_f32_16x16x32_bf16 v[70:73], v[198:201], v[238:241], v[70:73]
	v_mfma_f32_16x16x32_bf16 v[66:69], v[206:209], v[238:241], v[66:69]
	s_setprio 1
	s_barrier
	s_add_i32 s3, s3, s11
	v_lshl_add_u64 v[162:163], s[0:1], 0, v[4:5]
	s_mov_b32 m0, s3
	ds_read_b128 v[210:213], v147 offset:16384
	ds_read_b128 v[214:217], v147 offset:17408
	ds_read_b128 v[218:221], v147 offset:18432
	ds_read_b128 v[222:225], v147 offset:19456
	ds_read_b128 v[226:229], v147 offset:20480
	ds_read_b128 v[230:233], v147 offset:21504
	ds_read_b128 v[234:237], v147 offset:22528
	ds_read_b128 v[238:241], v147 offset:23552
	global_load_lds_dwordx4 v[162:163], off
	s_add_i32 m0, s3, 0x2000
	s_add_u32 s4, s0, 0x80000
	v_lshl_add_u64 v[166:167], s[0:1], 0, v[130:131]
	s_addc_u32 s5, s1, 0
	s_add_i32 s3, s6, s11
	global_load_lds_dwordx4 v[166:167], off
	v_lshl_add_u64 v[176:177], s[4:5], 0, v[4:5]
	s_mov_b32 m0, s3
	v_lshl_add_u64 v[180:181], s[14:15], 0, v[132:133]
	global_load_lds_dwordx4 v[176:177], off
	v_lshl_add_u64 v[176:177], s[4:5], 0, v[130:131]
	s_add_i32 m0, s3, 0x2000
	s_nop 0
	global_load_lds_dwordx4 v[176:177], off
	v_lshl_add_u64 v[176:177], s[14:15], 0, v[134:135]
	s_mov_b32 m0, s26
	s_nop 0
	global_load_lds_dwordx4 v[176:177], off
	s_mov_b32 m0, s27
	s_nop 0
	global_load_lds_dwordx4 v[180:181], off
	s_waitcnt vmcnt(8)
	s_waitcnt lgkmcnt(0)
	s_barrier
	s_setprio 0
	s_waitcnt lgkmcnt(0)
	v_mfma_f32_16x16x32_bf16 v[62:65], v[140:143], v[210:213], v[62:65]
	v_mfma_f32_16x16x32_bf16 v[58:61], v[172:175], v[210:213], v[58:61]
	v_mfma_f32_16x16x32_bf16 v[46:49], v[140:143], v[218:221], v[46:49]
	v_mfma_f32_16x16x32_bf16 v[42:45], v[172:175], v[218:221], v[42:45]
	v_mfma_f32_16x16x32_bf16 v[30:33], v[140:143], v[226:229], v[30:33]
	v_mfma_f32_16x16x32_bf16 v[26:29], v[172:175], v[226:229], v[26:29]
	v_mfma_f32_16x16x32_bf16 v[14:17], v[140:143], v[234:237], v[14:17]
	v_mfma_f32_16x16x32_bf16 v[10:13], v[172:175], v[234:237], v[10:13]
	v_mfma_f32_16x16x32_bf16 v[62:65], v[148:151], v[214:217], v[62:65]
	v_mfma_f32_16x16x32_bf16 v[58:61], v[190:193], v[214:217], v[58:61]
	v_mfma_f32_16x16x32_bf16 v[46:49], v[148:151], v[222:225], v[46:49]
	v_mfma_f32_16x16x32_bf16 v[42:45], v[190:193], v[222:225], v[42:45]
	v_mfma_f32_16x16x32_bf16 v[30:33], v[148:151], v[230:233], v[30:33]
	v_mfma_f32_16x16x32_bf16 v[26:29], v[190:193], v[230:233], v[26:29]
	v_mfma_f32_16x16x32_bf16 v[14:17], v[148:151], v[238:241], v[14:17]
	v_mfma_f32_16x16x32_bf16 v[10:13], v[190:193], v[238:241], v[10:13]
	v_mfma_f32_16x16x32_bf16 v[54:57], v[194:197], v[210:213], v[54:57]
	v_mfma_f32_16x16x32_bf16 v[50:53], v[202:205], v[210:213], v[50:53]
	v_mfma_f32_16x16x32_bf16 v[38:41], v[194:197], v[218:221], v[38:41]
	v_mfma_f32_16x16x32_bf16 v[34:37], v[202:205], v[218:221], v[34:37]
	v_mfma_f32_16x16x32_bf16 v[22:25], v[194:197], v[226:229], v[22:25]
	v_mfma_f32_16x16x32_bf16 v[18:21], v[202:205], v[226:229], v[18:21]
	v_mfma_f32_16x16x32_bf16 v[6:9], v[194:197], v[234:237], v[6:9]
	v_mfma_f32_16x16x32_bf16 v[0:3], v[202:205], v[234:237], v[0:3]
	v_mfma_f32_16x16x32_bf16 v[54:57], v[198:201], v[214:217], v[54:57]
	v_mfma_f32_16x16x32_bf16 v[50:53], v[206:209], v[214:217], v[50:53]
	v_mfma_f32_16x16x32_bf16 v[38:41], v[198:201], v[222:225], v[38:41]
	v_mfma_f32_16x16x32_bf16 v[34:37], v[206:209], v[222:225], v[34:37]
	v_mfma_f32_16x16x32_bf16 v[22:25], v[198:201], v[230:233], v[22:25]
	v_mfma_f32_16x16x32_bf16 v[18:21], v[206:209], v[230:233], v[18:21]
	v_mfma_f32_16x16x32_bf16 v[6:9], v[198:201], v[238:241], v[6:9]
	v_mfma_f32_16x16x32_bf16 v[0:3], v[206:209], v[238:241], v[0:3]
	s_setprio 1
	s_barrier
.Lpeelmid_163:
	s_add_i32 s3, 0, 0x18000
	v_add_u32_e32 v164, s3, v145
	s_add_i32 s6, 0, 0x1c000
	ds_read_b128 v[140:143], v164
	ds_read_b128 v[148:151], v164 offset:1024
	ds_read_b128 v[172:175], v164 offset:2048
	ds_read_b128 v[190:193], v164 offset:3072
	v_add_u32_e32 v164, s6, v145
	ds_read_b128 v[194:197], v164
	ds_read_b128 v[198:201], v164 offset:1024
	ds_read_b128 v[202:205], v164 offset:2048
	ds_read_b128 v[206:209], v164 offset:3072
	s_add_u32 s4, s14, 0x80000
	s_addc_u32 s5, s15, 0
	s_mov_b32 m0, s30
	v_lshl_add_u64 v[242:243], s[4:5], 0, v[134:135]
	ds_read_b128 v[210:213], v147 offset:32768
	ds_read_b128 v[214:217], v147 offset:33792
	ds_read_b128 v[218:221], v147 offset:34816
	ds_read_b128 v[222:225], v147 offset:35840
	ds_read_b128 v[226:229], v147 offset:36864
	ds_read_b128 v[230:233], v147 offset:37888
	ds_read_b128 v[234:237], v147 offset:38912
	ds_read_b128 v[238:241], v147 offset:39936
	global_load_lds_dwordx4 v[242:243], off
	v_lshl_add_u64 v[242:243], s[4:5], 0, v[132:133]
	s_mov_b32 m0, s31
	s_nop 0
	global_load_lds_dwordx4 v[242:243], off
	s_waitcnt vmcnt(8)
	s_waitcnt lgkmcnt(0)
	s_barrier
	s_setprio 0
	s_waitcnt lgkmcnt(0)
	v_mfma_f32_16x16x32_bf16 v[126:129], v[140:143], v[210:213], v[126:129]
	v_mfma_f32_16x16x32_bf16 v[122:125], v[172:175], v[210:213], v[122:125]
	v_mfma_f32_16x16x32_bf16 v[110:113], v[140:143], v[218:221], v[110:113]
	v_mfma_f32_16x16x32_bf16 v[106:109], v[172:175], v[218:221], v[106:109]
	v_mfma_f32_16x16x32_bf16 v[94:97], v[140:143], v[226:229], v[94:97]
	v_mfma_f32_16x16x32_bf16 v[90:93], v[172:175], v[226:229], v[90:93]
	v_mfma_f32_16x16x32_bf16 v[78:81], v[140:143], v[234:237], v[78:81]
	v_mfma_f32_16x16x32_bf16 v[74:77], v[172:175], v[234:237], v[74:77]
	v_mfma_f32_16x16x32_bf16 v[126:129], v[148:151], v[214:217], v[126:129]
	v_mfma_f32_16x16x32_bf16 v[122:125], v[190:193], v[214:217], v[122:125]
	v_mfma_f32_16x16x32_bf16 v[110:113], v[148:151], v[222:225], v[110:113]
	v_mfma_f32_16x16x32_bf16 v[106:109], v[190:193], v[222:225], v[106:109]
	v_mfma_f32_16x16x32_bf16 v[94:97], v[148:151], v[230:233], v[94:97]
	v_mfma_f32_16x16x32_bf16 v[90:93], v[190:193], v[230:233], v[90:93]
	v_mfma_f32_16x16x32_bf16 v[78:81], v[148:151], v[238:241], v[78:81]
	v_mfma_f32_16x16x32_bf16 v[74:77], v[190:193], v[238:241], v[74:77]
	v_mfma_f32_16x16x32_bf16 v[118:121], v[194:197], v[210:213], v[118:121]
	v_mfma_f32_16x16x32_bf16 v[114:117], v[202:205], v[210:213], v[114:117]
	v_mfma_f32_16x16x32_bf16 v[102:105], v[194:197], v[218:221], v[102:105]
	v_mfma_f32_16x16x32_bf16 v[98:101], v[202:205], v[218:221], v[98:101]
	v_mfma_f32_16x16x32_bf16 v[86:89], v[194:197], v[226:229], v[86:89]
	v_mfma_f32_16x16x32_bf16 v[82:85], v[202:205], v[226:229], v[82:85]
	v_mfma_f32_16x16x32_bf16 v[70:73], v[194:197], v[234:237], v[70:73]
	v_mfma_f32_16x16x32_bf16 v[66:69], v[202:205], v[234:237], v[66:69]
	v_mfma_f32_16x16x32_bf16 v[118:121], v[198:201], v[214:217], v[118:121]
	v_mfma_f32_16x16x32_bf16 v[114:117], v[206:209], v[214:217], v[114:117]
	v_mfma_f32_16x16x32_bf16 v[102:105], v[198:201], v[222:225], v[102:105]
	v_mfma_f32_16x16x32_bf16 v[98:101], v[206:209], v[222:225], v[98:101]
	v_mfma_f32_16x16x32_bf16 v[86:89], v[198:201], v[230:233], v[86:89]
	v_mfma_f32_16x16x32_bf16 v[82:85], v[206:209], v[230:233], v[82:85]
	v_mfma_f32_16x16x32_bf16 v[70:73], v[198:201], v[238:241], v[70:73]
	v_mfma_f32_16x16x32_bf16 v[66:69], v[206:209], v[238:241], v[66:69]
	s_setprio 1
	s_barrier
	s_add_i32 s3, s3, s11
	v_lshl_add_u64 v[162:163], v[162:163], 0, s[70:71]
	s_mov_b32 m0, s3
	ds_read_b128 v[210:213], v147 offset:49152
	ds_read_b128 v[214:217], v147 offset:50176
	ds_read_b128 v[218:221], v147 offset:51200
	ds_read_b128 v[222:225], v147 offset:52224
	ds_read_b128 v[226:229], v147 offset:53248
	ds_read_b128 v[230:233], v147 offset:54272
	ds_read_b128 v[234:237], v147 offset:55296
	ds_read_b128 v[238:241], v147 offset:56320
	global_load_lds_dwordx4 v[162:163], off
	s_add_i32 m0, s3, 0x2000
	s_add_u32 s0, s0, 0x80080
	v_lshl_add_u64 v[162:163], v[166:167], 0, s[70:71]
	s_addc_u32 s1, s1, 0
	s_add_i32 s3, s6, s11
	global_load_lds_dwordx4 v[162:163], off
	v_lshl_add_u64 v[162:163], s[0:1], 0, v[4:5]
	s_mov_b32 m0, s3
	s_nop 0
	global_load_lds_dwordx4 v[162:163], off
	v_lshl_add_u64 v[162:163], s[0:1], 0, v[130:131]
	s_add_i32 m0, s3, 0x2000
	s_nop 0
	global_load_lds_dwordx4 v[162:163], off
	v_lshl_add_u64 v[162:163], v[176:177], 0, s[70:71]
	s_mov_b32 m0, s35
	s_nop 0
	global_load_lds_dwordx4 v[162:163], off
	v_lshl_add_u64 v[162:163], v[180:181], 0, s[70:71]
	s_mov_b32 m0, s36
	s_nop 0
	global_load_lds_dwordx4 v[162:163], off
	s_waitcnt vmcnt(8)
	s_waitcnt lgkmcnt(0)
	s_barrier
	s_setprio 0
	s_waitcnt lgkmcnt(0)
	v_mfma_f32_16x16x32_bf16 v[62:65], v[140:143], v[210:213], v[62:65]
	v_mfma_f32_16x16x32_bf16 v[58:61], v[172:175], v[210:213], v[58:61]
	v_mfma_f32_16x16x32_bf16 v[46:49], v[140:143], v[218:221], v[46:49]
	v_mfma_f32_16x16x32_bf16 v[42:45], v[172:175], v[218:221], v[42:45]
	v_mfma_f32_16x16x32_bf16 v[30:33], v[140:143], v[226:229], v[30:33]
	v_mfma_f32_16x16x32_bf16 v[26:29], v[172:175], v[226:229], v[26:29]
	v_mfma_f32_16x16x32_bf16 v[14:17], v[140:143], v[234:237], v[14:17]
	v_mfma_f32_16x16x32_bf16 v[10:13], v[172:175], v[234:237], v[10:13]
	v_mfma_f32_16x16x32_bf16 v[62:65], v[148:151], v[214:217], v[62:65]
	v_mfma_f32_16x16x32_bf16 v[58:61], v[190:193], v[214:217], v[58:61]
	v_mfma_f32_16x16x32_bf16 v[46:49], v[148:151], v[222:225], v[46:49]
	v_mfma_f32_16x16x32_bf16 v[42:45], v[190:193], v[222:225], v[42:45]
	v_mfma_f32_16x16x32_bf16 v[30:33], v[148:151], v[230:233], v[30:33]
	v_mfma_f32_16x16x32_bf16 v[26:29], v[190:193], v[230:233], v[26:29]
	v_mfma_f32_16x16x32_bf16 v[14:17], v[148:151], v[238:241], v[14:17]
	v_mfma_f32_16x16x32_bf16 v[10:13], v[190:193], v[238:241], v[10:13]
	v_mfma_f32_16x16x32_bf16 v[54:57], v[194:197], v[210:213], v[54:57]
	v_mfma_f32_16x16x32_bf16 v[50:53], v[202:205], v[210:213], v[50:53]
	v_mfma_f32_16x16x32_bf16 v[38:41], v[194:197], v[218:221], v[38:41]
	v_mfma_f32_16x16x32_bf16 v[34:37], v[202:205], v[218:221], v[34:37]
	v_mfma_f32_16x16x32_bf16 v[22:25], v[194:197], v[226:229], v[22:25]
	v_mfma_f32_16x16x32_bf16 v[18:21], v[202:205], v[226:229], v[18:21]
	v_mfma_f32_16x16x32_bf16 v[6:9], v[194:197], v[234:237], v[6:9]
	v_mfma_f32_16x16x32_bf16 v[0:3], v[202:205], v[234:237], v[0:3]
	v_mfma_f32_16x16x32_bf16 v[54:57], v[198:201], v[214:217], v[54:57]
	v_mfma_f32_16x16x32_bf16 v[50:53], v[206:209], v[214:217], v[50:53]
	v_mfma_f32_16x16x32_bf16 v[38:41], v[198:201], v[222:225], v[38:41]
	v_mfma_f32_16x16x32_bf16 v[34:37], v[206:209], v[222:225], v[34:37]
	v_mfma_f32_16x16x32_bf16 v[22:25], v[198:201], v[230:233], v[22:25]
	v_mfma_f32_16x16x32_bf16 v[18:21], v[206:209], v[230:233], v[18:21]
	v_mfma_f32_16x16x32_bf16 v[6:9], v[198:201], v[238:241], v[6:9]
	v_mfma_f32_16x16x32_bf16 v[0:3], v[206:209], v[238:241], v[0:3]
	s_setprio 1
	s_barrier
	s_add_i32 s24, s24, 2
	s_add_u32 s22, s22, 0x100
	s_addc_u32 s23, s23, 0
	s_add_u32 s9, s9, 0x100
	s_addc_u32 s10, s10, 0
	s_cmp_gt_u32 s24, 29
	s_cbranch_scc0 .LBB0_163
	s_and_b64 vcc, exec, s[46:47]
	s_cbranch_vccz .LBB0_166
	s_barrier

.LBB0_204:
	s_ashr_i32 s49, s48, 31
	s_lshl_b64 s[2:3], s[48:49], 19
	v_readlane_b32 s4, v253, 17
	v_readlane_b32 s5, v253, 18
	s_add_u32 s84, s4, s2
	s_addc_u32 s85, s5, s3
	s_and_b64 s[2:3], s[42:43], exec
	s_cselect_b32 s2, s85, s15
	s_cselect_b32 s8, s84, s14
	s_add_u32 s22, s0, 0x40080
	s_addc_u32 s23, s1, 0
	s_add_u32 s9, s14, 0x100
	v_mov_b32_e32 v0, 0
	s_addc_u32 s10, s15, 0
	s_mov_b32 s24, -2
	v_mov_b32_e32 v1, v0
	v_mov_b32_e32 v2, v0
	v_mov_b32_e32 v3, v0
	v_mov_b32_e32 v6, v0
	v_mov_b32_e32 v7, v0
	v_mov_b32_e32 v8, v0
	v_mov_b32_e32 v9, v0
	v_mov_b32_e32 v10, v0
	v_mov_b32_e32 v11, v0
	v_mov_b32_e32 v12, v0
	v_mov_b32_e32 v13, v0
	v_mov_b32_e32 v14, v0
	v_mov_b32_e32 v15, v0
	v_mov_b32_e32 v16, v0
	v_mov_b32_e32 v17, v0
	v_mov_b32_e32 v18, v0
	v_mov_b32_e32 v19, v0
	v_mov_b32_e32 v20, v0
	v_mov_b32_e32 v21, v0
	v_mov_b32_e32 v22, v0
	v_mov_b32_e32 v23, v0
	v_mov_b32_e32 v24, v0
	v_mov_b32_e32 v25, v0
	v_mov_b32_e32 v26, v0
	v_mov_b32_e32 v27, v0
	v_mov_b32_e32 v28, v0
	v_mov_b32_e32 v29, v0
	v_mov_b32_e32 v30, v0
	v_mov_b32_e32 v31, v0
	v_mov_b32_e32 v32, v0
	v_mov_b32_e32 v33, v0
	v_mov_b32_e32 v66, v0
	v_mov_b32_e32 v67, v0
	v_mov_b32_e32 v68, v0
	v_mov_b32_e32 v69, v0
	v_mov_b32_e32 v70, v0
	v_mov_b32_e32 v71, v0
	v_mov_b32_e32 v72, v0
	v_mov_b32_e32 v73, v0
	v_mov_b32_e32 v74, v0
	v_mov_b32_e32 v75, v0
	v_mov_b32_e32 v76, v0
	v_mov_b32_e32 v77, v0
	v_mov_b32_e32 v78, v0
	v_mov_b32_e32 v79, v0
	v_mov_b32_e32 v80, v0
	v_mov_b32_e32 v81, v0
	v_mov_b32_e32 v82, v0
	v_mov_b32_e32 v83, v0
	v_mov_b32_e32 v84, v0
	v_mov_b32_e32 v85, v0
	v_mov_b32_e32 v86, v0
	v_mov_b32_e32 v87, v0
	v_mov_b32_e32 v88, v0
	v_mov_b32_e32 v89, v0
	v_mov_b32_e32 v90, v0
	v_mov_b32_e32 v91, v0
	v_mov_b32_e32 v92, v0
	v_mov_b32_e32 v93, v0
	v_mov_b32_e32 v94, v0
	v_mov_b32_e32 v95, v0
	v_mov_b32_e32 v96, v0
	v_mov_b32_e32 v97, v0
	v_mov_b32_e32 v34, v0
	v_mov_b32_e32 v35, v0
	v_mov_b32_e32 v36, v0
	v_mov_b32_e32 v37, v0
	v_mov_b32_e32 v38, v0
	v_mov_b32_e32 v39, v0
	v_mov_b32_e32 v40, v0
	v_mov_b32_e32 v41, v0
	v_mov_b32_e32 v42, v0
	v_mov_b32_e32 v43, v0
	v_mov_b32_e32 v44, v0
	v_mov_b32_e32 v45, v0
	v_mov_b32_e32 v46, v0
	v_mov_b32_e32 v47, v0
	v_mov_b32_e32 v48, v0
	v_mov_b32_e32 v49, v0
	v_mov_b32_e32 v50, v0
	v_mov_b32_e32 v51, v0
	v_mov_b32_e32 v52, v0
	v_mov_b32_e32 v53, v0
	v_mov_b32_e32 v54, v0
	v_mov_b32_e32 v55, v0
	v_mov_b32_e32 v56, v0
	v_mov_b32_e32 v57, v0
	v_mov_b32_e32 v58, v0
	v_mov_b32_e32 v59, v0
	v_mov_b32_e32 v60, v0
	v_mov_b32_e32 v61, v0
	v_mov_b32_e32 v62, v0
	v_mov_b32_e32 v63, v0
	v_mov_b32_e32 v64, v0
	v_mov_b32_e32 v65, v0
	v_mov_b32_e32 v98, v0
	v_mov_b32_e32 v99, v0
	v_mov_b32_e32 v100, v0
	v_mov_b32_e32 v101, v0
	v_mov_b32_e32 v102, v0
	v_mov_b32_e32 v103, v0
	v_mov_b32_e32 v104, v0
	v_mov_b32_e32 v105, v0
	v_mov_b32_e32 v106, v0
	v_mov_b32_e32 v107, v0
	v_mov_b32_e32 v108, v0
	v_mov_b32_e32 v109, v0
	v_mov_b32_e32 v110, v0
	v_mov_b32_e32 v111, v0
	v_mov_b32_e32 v112, v0
	v_mov_b32_e32 v113, v0
	v_mov_b32_e32 v114, v0
	v_mov_b32_e32 v115, v0
	v_mov_b32_e32 v116, v0
	v_mov_b32_e32 v117, v0
	v_mov_b32_e32 v118, v0
	v_mov_b32_e32 v119, v0
	v_mov_b32_e32 v120, v0
	v_mov_b32_e32 v121, v0
	v_mov_b32_e32 v122, v0
	v_mov_b32_e32 v123, v0
	v_mov_b32_e32 v124, v0
	v_mov_b32_e32 v125, v0
	v_mov_b32_e32 v126, v0
	v_mov_b32_e32 v127, v0
	v_mov_b32_e32 v128, v0
	v_mov_b32_e32 v129, v0
	s_cmp_eq_u32 s37, 1
	s_cbranch_scc1 .LBB0_205
	s_add_u32 s0, s22, 0xfffc0080
	s_addc_u32 s1, s23, -1
	s_add_i32 s3, 0, 0x10000
	s_cmp_eq_u32 s24, 12
	s_cselect_b32 s15, s83, s1
	s_cselect_b32 s14, s82, s0
	v_add_u32_e32 v144, s3, v168
	s_cselect_b32 s1, s2, s10
	s_cselect_b32 s0, s8, s9
	s_add_i32 s6, 0, 0x14000
	ds_read_b128 v[140:143], v144
	ds_read_b128 v[174:177], v144 offset:1024
	ds_read_b128 v[190:193], v144 offset:2048
	ds_read_b128 v[194:197], v144 offset:3072
	v_add_u32_e32 v144, s6, v168
	ds_read_b128 v[198:201], v144
	ds_read_b128 v[202:205], v144 offset:1024
	ds_read_b128 v[206:209], v144 offset:2048
	ds_read_b128 v[210:213], v144 offset:3072
	v_lshl_add_u64 v[144:145], s[22:23], 0, v[136:137]
	s_add_i32 m0, s27, 0xc000
	ds_read_b128 v[214:217], v172
	ds_read_b128 v[218:221], v172 offset:1024
	ds_read_b128 v[222:225], v172 offset:2048
	ds_read_b128 v[226:229], v172 offset:3072
	ds_read_b128 v[230:233], v172 offset:4096
	ds_read_b128 v[234:237], v172 offset:5120
	ds_read_b128 v[238:241], v172 offset:6144
	ds_read_b128 v[242:245], v172 offset:7168
	global_load_lds_dwordx4 v[144:145], off
	v_lshl_add_u64 v[144:145], s[22:23], 0, v[138:139]
	s_add_i32 m0, s27, 0xe000
	s_nop 0
	global_load_lds_dwordx4 v[144:145], off
	s_waitcnt vmcnt(24)
	s_waitcnt lgkmcnt(0)
	s_barrier
	s_setprio 0
	s_waitcnt lgkmcnt(0)
	v_mfma_f32_16x16x32_bf16 v[126:129], v[140:143], v[214:217], v[126:129]
	v_mfma_f32_16x16x32_bf16 v[122:125], v[190:193], v[214:217], v[122:125]
	v_mfma_f32_16x16x32_bf16 v[118:121], v[140:143], v[222:225], v[118:121]
	v_mfma_f32_16x16x32_bf16 v[114:117], v[190:193], v[222:225], v[114:117]
	v_mfma_f32_16x16x32_bf16 v[110:113], v[140:143], v[230:233], v[110:113]
	v_mfma_f32_16x16x32_bf16 v[106:109], v[190:193], v[230:233], v[106:109]
	v_mfma_f32_16x16x32_bf16 v[102:105], v[140:143], v[238:241], v[102:105]
	v_mfma_f32_16x16x32_bf16 v[98:101], v[190:193], v[238:241], v[98:101]
	v_mfma_f32_16x16x32_bf16 v[126:129], v[174:177], v[218:221], v[126:129]
	v_mfma_f32_16x16x32_bf16 v[122:125], v[194:197], v[218:221], v[122:125]
	v_mfma_f32_16x16x32_bf16 v[118:121], v[174:177], v[226:229], v[118:121]
	v_mfma_f32_16x16x32_bf16 v[114:117], v[194:197], v[226:229], v[114:117]
	v_mfma_f32_16x16x32_bf16 v[110:113], v[174:177], v[234:237], v[110:113]
	v_mfma_f32_16x16x32_bf16 v[106:109], v[194:197], v[234:237], v[106:109]
	v_mfma_f32_16x16x32_bf16 v[102:105], v[174:177], v[242:245], v[102:105]
	v_mfma_f32_16x16x32_bf16 v[98:101], v[194:197], v[242:245], v[98:101]
	v_mfma_f32_16x16x32_bf16 v[62:65], v[198:201], v[214:217], v[62:65]
	v_mfma_f32_16x16x32_bf16 v[58:61], v[206:209], v[214:217], v[58:61]
	v_mfma_f32_16x16x32_bf16 v[54:57], v[198:201], v[222:225], v[54:57]
	v_mfma_f32_16x16x32_bf16 v[50:53], v[206:209], v[222:225], v[50:53]
	v_mfma_f32_16x16x32_bf16 v[46:49], v[198:201], v[230:233], v[46:49]
	v_mfma_f32_16x16x32_bf16 v[42:45], v[206:209], v[230:233], v[42:45]
	v_mfma_f32_16x16x32_bf16 v[38:41], v[198:201], v[238:241], v[38:41]
	v_mfma_f32_16x16x32_bf16 v[34:37], v[206:209], v[238:241], v[34:37]
	v_mfma_f32_16x16x32_bf16 v[62:65], v[202:205], v[218:221], v[62:65]
	v_mfma_f32_16x16x32_bf16 v[58:61], v[210:213], v[218:221], v[58:61]
	v_mfma_f32_16x16x32_bf16 v[54:57], v[202:205], v[226:229], v[54:57]
	v_mfma_f32_16x16x32_bf16 v[50:53], v[210:213], v[226:229], v[50:53]
	v_mfma_f32_16x16x32_bf16 v[46:49], v[202:205], v[234:237], v[46:49]
	v_mfma_f32_16x16x32_bf16 v[42:45], v[210:213], v[234:237], v[42:45]
	v_mfma_f32_16x16x32_bf16 v[38:41], v[202:205], v[242:245], v[38:41]
	v_mfma_f32_16x16x32_bf16 v[34:37], v[210:213], v[242:245], v[34:37]
	s_setprio 1
	s_barrier
	s_add_i32 s3, s3, s26
	v_lshl_add_u64 v[144:145], s[0:1], 0, v[4:5]
	s_mov_b32 m0, s3
	ds_read_b128 v[214:217], v172 offset:16384
	ds_read_b128 v[218:221], v172 offset:17408
	ds_read_b128 v[222:225], v172 offset:18432
	ds_read_b128 v[226:229], v172 offset:19456
	ds_read_b128 v[230:233], v172 offset:20480
	ds_read_b128 v[234:237], v172 offset:21504
	ds_read_b128 v[238:241], v172 offset:22528
	ds_read_b128 v[242:245], v172 offset:23552
	global_load_lds_dwordx4 v[144:145], off
	s_add_i32 m0, s3, 0x2000
	s_add_u32 s4, s0, 0x40000
	v_lshl_add_u64 v[246:247], s[0:1], 0, v[134:135]
	s_addc_u32 s5, s1, 0
	s_add_i32 s3, s6, s26
	global_load_lds_dwordx4 v[246:247], off
	v_lshl_add_u64 v[248:249], s[4:5], 0, v[4:5]
	s_mov_b32 m0, s3
	v_lshl_add_u64 v[250:251], s[14:15], 0, v[132:133]
	global_load_lds_dwordx4 v[248:249], off
	v_lshl_add_u64 v[248:249], s[4:5], 0, v[134:135]
	s_add_i32 m0, s3, 0x2000
	s_nop 0
	global_load_lds_dwordx4 v[248:249], off
	v_lshl_add_u64 v[248:249], s[14:15], 0, v[130:131]
	s_mov_b32 m0, s27
	s_nop 0
	global_load_lds_dwordx4 v[248:249], off
	s_mov_b32 m0, s30
	s_nop 0
	global_load_lds_dwordx4 v[250:251], off
	s_waitcnt vmcnt(24)
	s_waitcnt lgkmcnt(0)
	s_barrier
	s_setprio 0
	s_waitcnt lgkmcnt(0)
	v_mfma_f32_16x16x32_bf16 v[94:97], v[140:143], v[214:217], v[94:97]
	v_mfma_f32_16x16x32_bf16 v[90:93], v[190:193], v[214:217], v[90:93]
	v_mfma_f32_16x16x32_bf16 v[86:89], v[140:143], v[222:225], v[86:89]
	v_mfma_f32_16x16x32_bf16 v[82:85], v[190:193], v[222:225], v[82:85]
	v_mfma_f32_16x16x32_bf16 v[78:81], v[140:143], v[230:233], v[78:81]
	v_mfma_f32_16x16x32_bf16 v[74:77], v[190:193], v[230:233], v[74:77]
	v_mfma_f32_16x16x32_bf16 v[70:73], v[140:143], v[238:241], v[70:73]
	v_mfma_f32_16x16x32_bf16 v[66:69], v[190:193], v[238:241], v[66:69]
	v_mfma_f32_16x16x32_bf16 v[94:97], v[174:177], v[218:221], v[94:97]
	v_mfma_f32_16x16x32_bf16 v[90:93], v[194:197], v[218:221], v[90:93]
	v_mfma_f32_16x16x32_bf16 v[86:89], v[174:177], v[226:229], v[86:89]
	v_mfma_f32_16x16x32_bf16 v[82:85], v[194:197], v[226:229], v[82:85]
	v_mfma_f32_16x16x32_bf16 v[78:81], v[174:177], v[234:237], v[78:81]
	v_mfma_f32_16x16x32_bf16 v[74:77], v[194:197], v[234:237], v[74:77]
	v_mfma_f32_16x16x32_bf16 v[70:73], v[174:177], v[242:245], v[70:73]
	v_mfma_f32_16x16x32_bf16 v[66:69], v[194:197], v[242:245], v[66:69]
	v_mfma_f32_16x16x32_bf16 v[30:33], v[198:201], v[214:217], v[30:33]
	v_mfma_f32_16x16x32_bf16 v[26:29], v[206:209], v[214:217], v[26:29]
	v_mfma_f32_16x16x32_bf16 v[22:25], v[198:201], v[222:225], v[22:25]
	v_mfma_f32_16x16x32_bf16 v[18:21], v[206:209], v[222:225], v[18:21]
	v_mfma_f32_16x16x32_bf16 v[14:17], v[198:201], v[230:233], v[14:17]
	v_mfma_f32_16x16x32_bf16 v[10:13], v[206:209], v[230:233], v[10:13]
	v_mfma_f32_16x16x32_bf16 v[6:9], v[198:201], v[238:241], v[6:9]
	v_mfma_f32_16x16x32_bf16 v[0:3], v[206:209], v[238:241], v[0:3]
	v_mfma_f32_16x16x32_bf16 v[30:33], v[202:205], v[218:221], v[30:33]
	v_mfma_f32_16x16x32_bf16 v[26:29], v[210:213], v[218:221], v[26:29]
	v_mfma_f32_16x16x32_bf16 v[22:25], v[202:205], v[226:229], v[22:25]
	v_mfma_f32_16x16x32_bf16 v[18:21], v[210:213], v[226:229], v[18:21]
	v_mfma_f32_16x16x32_bf16 v[14:17], v[202:205], v[234:237], v[14:17]
	v_mfma_f32_16x16x32_bf16 v[10:13], v[210:213], v[234:237], v[10:13]
	v_mfma_f32_16x16x32_bf16 v[6:9], v[202:205], v[242:245], v[6:9]
	v_mfma_f32_16x16x32_bf16 v[0:3], v[210:213], v[242:245], v[0:3]
	s_setprio 1
	s_barrier
	s_branch .Lpeelmid_205
.LBB0_205:
	s_add_u32 s0, s22, 0xfffc0080
	s_addc_u32 s1, s23, -1
	s_add_i32 s3, 0, 0x10000
	s_cmp_eq_u32 s24, 12
	s_cselect_b32 s15, s83, s1
	s_cselect_b32 s14, s82, s0
	v_add_u32_e32 v144, s3, v168
	s_cselect_b32 s1, s2, s10
	s_cselect_b32 s0, s8, s9
	s_add_i32 s6, 0, 0x14000
	ds_read_b128 v[140:143], v144
	ds_read_b128 v[174:177], v144 offset:1024
	ds_read_b128 v[190:193], v144 offset:2048
	ds_read_b128 v[194:197], v144 offset:3072
	v_add_u32_e32 v144, s6, v168
	ds_read_b128 v[198:201], v144
	ds_read_b128 v[202:205], v144 offset:1024
	ds_read_b128 v[206:209], v144 offset:2048
	ds_read_b128 v[210:213], v144 offset:3072
	v_lshl_add_u64 v[144:145], s[22:23], 0, v[136:137]
	s_add_i32 m0, s27, 0xc000
	ds_read_b128 v[214:217], v172
	ds_read_b128 v[218:221], v172 offset:1024
	ds_read_b128 v[222:225], v172 offset:2048
	ds_read_b128 v[226:229], v172 offset:3072
	ds_read_b128 v[230:233], v172 offset:4096
	ds_read_b128 v[234:237], v172 offset:5120
	ds_read_b128 v[238:241], v172 offset:6144
	ds_read_b128 v[242:245], v172 offset:7168
	global_load_lds_dwordx4 v[144:145], off
	v_lshl_add_u64 v[144:145], s[22:23], 0, v[138:139]
	s_add_i32 m0, s27, 0xe000
	s_nop 0
	global_load_lds_dwordx4 v[144:145], off
	s_waitcnt vmcnt(8)
	s_waitcnt lgkmcnt(0)
	s_barrier
	s_setprio 0
	s_waitcnt lgkmcnt(0)
	v_mfma_f32_16x16x32_bf16 v[126:129], v[140:143], v[214:217], v[126:129]
	v_mfma_f32_16x16x32_bf16 v[122:125], v[190:193], v[214:217], v[122:125]
	v_mfma_f32_16x16x32_bf16 v[118:121], v[140:143], v[222:225], v[118:121]
	v_mfma_f32_16x16x32_bf16 v[114:117], v[190:193], v[222:225], v[114:117]
	v_mfma_f32_16x16x32_bf16 v[110:113], v[140:143], v[230:233], v[110:113]
	v_mfma_f32_16x16x32_bf16 v[106:109], v[190:193], v[230:233], v[106:109]
	v_mfma_f32_16x16x32_bf16 v[102:105], v[140:143], v[238:241], v[102:105]
	v_mfma_f32_16x16x32_bf16 v[98:101], v[190:193], v[238:241], v[98:101]
	v_mfma_f32_16x16x32_bf16 v[126:129], v[174:177], v[218:221], v[126:129]
	v_mfma_f32_16x16x32_bf16 v[122:125], v[194:197], v[218:221], v[122:125]
	v_mfma_f32_16x16x32_bf16 v[118:121], v[174:177], v[226:229], v[118:121]
	v_mfma_f32_16x16x32_bf16 v[114:117], v[194:197], v[226:229], v[114:117]
	v_mfma_f32_16x16x32_bf16 v[110:113], v[174:177], v[234:237], v[110:113]
	v_mfma_f32_16x16x32_bf16 v[106:109], v[194:197], v[234:237], v[106:109]
	v_mfma_f32_16x16x32_bf16 v[102:105], v[174:177], v[242:245], v[102:105]
	v_mfma_f32_16x16x32_bf16 v[98:101], v[194:197], v[242:245], v[98:101]
	v_mfma_f32_16x16x32_bf16 v[62:65], v[198:201], v[214:217], v[62:65]
	v_mfma_f32_16x16x32_bf16 v[58:61], v[206:209], v[214:217], v[58:61]
	v_mfma_f32_16x16x32_bf16 v[54:57], v[198:201], v[222:225], v[54:57]
	v_mfma_f32_16x16x32_bf16 v[50:53], v[206:209], v[222:225], v[50:53]
	v_mfma_f32_16x16x32_bf16 v[46:49], v[198:201], v[230:233], v[46:49]
	v_mfma_f32_16x16x32_bf16 v[42:45], v[206:209], v[230:233], v[42:45]
	v_mfma_f32_16x16x32_bf16 v[38:41], v[198:201], v[238:241], v[38:41]
	v_mfma_f32_16x16x32_bf16 v[34:37], v[206:209], v[238:241], v[34:37]
	v_mfma_f32_16x16x32_bf16 v[62:65], v[202:205], v[218:221], v[62:65]
	v_mfma_f32_16x16x32_bf16 v[58:61], v[210:213], v[218:221], v[58:61]
	v_mfma_f32_16x16x32_bf16 v[54:57], v[202:205], v[226:229], v[54:57]
	v_mfma_f32_16x16x32_bf16 v[50:53], v[210:213], v[226:229], v[50:53]
	v_mfma_f32_16x16x32_bf16 v[46:49], v[202:205], v[234:237], v[46:49]
	v_mfma_f32_16x16x32_bf16 v[42:45], v[210:213], v[234:237], v[42:45]
	v_mfma_f32_16x16x32_bf16 v[38:41], v[202:205], v[242:245], v[38:41]
	v_mfma_f32_16x16x32_bf16 v[34:37], v[210:213], v[242:245], v[34:37]
	s_setprio 1
	s_barrier
	s_add_i32 s3, s3, s26
	v_lshl_add_u64 v[144:145], s[0:1], 0, v[4:5]
	s_mov_b32 m0, s3
	ds_read_b128 v[214:217], v172 offset:16384
	ds_read_b128 v[218:221], v172 offset:17408
	ds_read_b128 v[222:225], v172 offset:18432
	ds_read_b128 v[226:229], v172 offset:19456
	ds_read_b128 v[230:233], v172 offset:20480
	ds_read_b128 v[234:237], v172 offset:21504
	ds_read_b128 v[238:241], v172 offset:22528
	ds_read_b128 v[242:245], v172 offset:23552
	global_load_lds_dwordx4 v[144:145], off
	s_add_i32 m0, s3, 0x2000
	s_add_u32 s4, s0, 0x40000
	v_lshl_add_u64 v[246:247], s[0:1], 0, v[134:135]
	s_addc_u32 s5, s1, 0
	s_add_i32 s3, s6, s26
	global_load_lds_dwordx4 v[246:247], off
	v_lshl_add_u64 v[248:249], s[4:5], 0, v[4:5]
	s_mov_b32 m0, s3
	v_lshl_add_u64 v[250:251], s[14:15], 0, v[132:133]
	global_load_lds_dwordx4 v[248:249], off
	v_lshl_add_u64 v[248:249], s[4:5], 0, v[134:135]
	s_add_i32 m0, s3, 0x2000
	s_nop 0
	global_load_lds_dwordx4 v[248:249], off
	v_lshl_add_u64 v[248:249], s[14:15], 0, v[130:131]
	s_mov_b32 m0, s27
	s_nop 0
	global_load_lds_dwordx4 v[248:249], off
	s_mov_b32 m0, s30
	s_nop 0
	global_load_lds_dwordx4 v[250:251], off
	s_waitcnt vmcnt(8)
	s_waitcnt lgkmcnt(0)
	s_barrier
	s_setprio 0
	s_waitcnt lgkmcnt(0)
	v_mfma_f32_16x16x32_bf16 v[94:97], v[140:143], v[214:217], v[94:97]
	v_mfma_f32_16x16x32_bf16 v[90:93], v[190:193], v[214:217], v[90:93]
	v_mfma_f32_16x16x32_bf16 v[86:89], v[140:143], v[222:225], v[86:89]
	v_mfma_f32_16x16x32_bf16 v[82:85], v[190:193], v[222:225], v[82:85]
	v_mfma_f32_16x16x32_bf16 v[78:81], v[140:143], v[230:233], v[78:81]
	v_mfma_f32_16x16x32_bf16 v[74:77], v[190:193], v[230:233], v[74:77]
	v_mfma_f32_16x16x32_bf16 v[70:73], v[140:143], v[238:241], v[70:73]
	v_mfma_f32_16x16x32_bf16 v[66:69], v[190:193], v[238:241], v[66:69]
	v_mfma_f32_16x16x32_bf16 v[94:97], v[174:177], v[218:221], v[94:97]
	v_mfma_f32_16x16x32_bf16 v[90:93], v[194:197], v[218:221], v[90:93]
	v_mfma_f32_16x16x32_bf16 v[86:89], v[174:177], v[226:229], v[86:89]
	v_mfma_f32_16x16x32_bf16 v[82:85], v[194:197], v[226:229], v[82:85]
	v_mfma_f32_16x16x32_bf16 v[78:81], v[174:177], v[234:237], v[78:81]
	v_mfma_f32_16x16x32_bf16 v[74:77], v[194:197], v[234:237], v[74:77]
	v_mfma_f32_16x16x32_bf16 v[70:73], v[174:177], v[242:245], v[70:73]
	v_mfma_f32_16x16x32_bf16 v[66:69], v[194:197], v[242:245], v[66:69]
	v_mfma_f32_16x16x32_bf16 v[30:33], v[198:201], v[214:217], v[30:33]
	v_mfma_f32_16x16x32_bf16 v[26:29], v[206:209], v[214:217], v[26:29]
	v_mfma_f32_16x16x32_bf16 v[22:25], v[198:201], v[222:225], v[22:25]
	v_mfma_f32_16x16x32_bf16 v[18:21], v[206:209], v[222:225], v[18:21]
	v_mfma_f32_16x16x32_bf16 v[14:17], v[198:201], v[230:233], v[14:17]
	v_mfma_f32_16x16x32_bf16 v[10:13], v[206:209], v[230:233], v[10:13]
	v_mfma_f32_16x16x32_bf16 v[6:9], v[198:201], v[238:241], v[6:9]
	v_mfma_f32_16x16x32_bf16 v[0:3], v[206:209], v[238:241], v[0:3]
	v_mfma_f32_16x16x32_bf16 v[30:33], v[202:205], v[218:221], v[30:33]
	v_mfma_f32_16x16x32_bf16 v[26:29], v[210:213], v[218:221], v[26:29]
	v_mfma_f32_16x16x32_bf16 v[22:25], v[202:205], v[226:229], v[22:25]
	v_mfma_f32_16x16x32_bf16 v[18:21], v[210:213], v[226:229], v[18:21]
	v_mfma_f32_16x16x32_bf16 v[14:17], v[202:205], v[234:237], v[14:17]
	v_mfma_f32_16x16x32_bf16 v[10:13], v[210:213], v[234:237], v[10:13]
	v_mfma_f32_16x16x32_bf16 v[6:9], v[202:205], v[242:245], v[6:9]
	v_mfma_f32_16x16x32_bf16 v[0:3], v[210:213], v[242:245], v[0:3]
	s_setprio 1
	s_barrier
.Lpeelmid_205:
	s_add_i32 s3, 0, 0x18000
	v_add_u32_e32 v173, s3, v168
	s_add_i32 s6, 0, 0x1c000
	ds_read_b128 v[140:143], v173
	ds_read_b128 v[174:177], v173 offset:1024
	ds_read_b128 v[190:193], v173 offset:2048
	ds_read_b128 v[194:197], v173 offset:3072
	v_add_u32_e32 v173, s6, v168
	ds_read_b128 v[198:201], v173
	ds_read_b128 v[202:205], v173 offset:1024
	ds_read_b128 v[206:209], v173 offset:2048
	ds_read_b128 v[210:213], v173 offset:3072
	s_add_u32 s4, s14, 0x40000
	s_addc_u32 s5, s15, 0
	s_mov_b32 m0, s31
	v_lshl_add_u64 v[180:181], s[4:5], 0, v[130:131]
	ds_read_b128 v[214:217], v172 offset:32768
	ds_read_b128 v[218:221], v172 offset:33792
	ds_read_b128 v[222:225], v172 offset:34816
	ds_read_b128 v[226:229], v172 offset:35840
	ds_read_b128 v[230:233], v172 offset:36864
	ds_read_b128 v[234:237], v172 offset:37888
	ds_read_b128 v[238:241], v172 offset:38912
	ds_read_b128 v[242:245], v172 offset:39936
	global_load_lds_dwordx4 v[180:181], off
	v_lshl_add_u64 v[180:181], s[4:5], 0, v[132:133]
	s_mov_b32 m0, s34
	s_nop 0
	global_load_lds_dwordx4 v[180:181], off
	s_waitcnt vmcnt(8)
	s_waitcnt lgkmcnt(0)
	s_barrier
	s_setprio 0
	s_waitcnt lgkmcnt(0)
	v_mfma_f32_16x16x32_bf16 v[126:129], v[140:143], v[214:217], v[126:129]
	v_mfma_f32_16x16x32_bf16 v[122:125], v[190:193], v[214:217], v[122:125]
	v_mfma_f32_16x16x32_bf16 v[118:121], v[140:143], v[222:225], v[118:121]
	v_mfma_f32_16x16x32_bf16 v[114:117], v[190:193], v[222:225], v[114:117]
	v_mfma_f32_16x16x32_bf16 v[110:113], v[140:143], v[230:233], v[110:113]
	v_mfma_f32_16x16x32_bf16 v[106:109], v[190:193], v[230:233], v[106:109]
	v_mfma_f32_16x16x32_bf16 v[102:105], v[140:143], v[238:241], v[102:105]
	v_mfma_f32_16x16x32_bf16 v[98:101], v[190:193], v[238:241], v[98:101]
	v_mfma_f32_16x16x32_bf16 v[126:129], v[174:177], v[218:221], v[126:129]
	v_mfma_f32_16x16x32_bf16 v[122:125], v[194:197], v[218:221], v[122:125]
	v_mfma_f32_16x16x32_bf16 v[118:121], v[174:177], v[226:229], v[118:121]
	v_mfma_f32_16x16x32_bf16 v[114:117], v[194:197], v[226:229], v[114:117]
	v_mfma_f32_16x16x32_bf16 v[110:113], v[174:177], v[234:237], v[110:113]
	v_mfma_f32_16x16x32_bf16 v[106:109], v[194:197], v[234:237], v[106:109]
	v_mfma_f32_16x16x32_bf16 v[102:105], v[174:177], v[242:245], v[102:105]
	v_mfma_f32_16x16x32_bf16 v[98:101], v[194:197], v[242:245], v[98:101]
	v_mfma_f32_16x16x32_bf16 v[62:65], v[198:201], v[214:217], v[62:65]
	v_mfma_f32_16x16x32_bf16 v[58:61], v[206:209], v[214:217], v[58:61]
	v_mfma_f32_16x16x32_bf16 v[54:57], v[198:201], v[222:225], v[54:57]
	v_mfma_f32_16x16x32_bf16 v[50:53], v[206:209], v[222:225], v[50:53]
	v_mfma_f32_16x16x32_bf16 v[46:49], v[198:201], v[230:233], v[46:49]
	v_mfma_f32_16x16x32_bf16 v[42:45], v[206:209], v[230:233], v[42:45]
	v_mfma_f32_16x16x32_bf16 v[38:41], v[198:201], v[238:241], v[38:41]
	v_mfma_f32_16x16x32_bf16 v[34:37], v[206:209], v[238:241], v[34:37]
	v_mfma_f32_16x16x32_bf16 v[62:65], v[202:205], v[218:221], v[62:65]
	v_mfma_f32_16x16x32_bf16 v[58:61], v[210:213], v[218:221], v[58:61]
	v_mfma_f32_16x16x32_bf16 v[54:57], v[202:205], v[226:229], v[54:57]
	v_mfma_f32_16x16x32_bf16 v[50:53], v[210:213], v[226:229], v[50:53]
	v_mfma_f32_16x16x32_bf16 v[46:49], v[202:205], v[234:237], v[46:49]
	v_mfma_f32_16x16x32_bf16 v[42:45], v[210:213], v[234:237], v[42:45]
	v_mfma_f32_16x16x32_bf16 v[38:41], v[202:205], v[242:245], v[38:41]
	v_mfma_f32_16x16x32_bf16 v[34:37], v[210:213], v[242:245], v[34:37]
	s_setprio 1
	s_barrier
	s_add_i32 s3, s3, s26
	v_lshl_add_u64 v[144:145], v[144:145], 0, s[70:71]
	s_mov_b32 m0, s3
	ds_read_b128 v[214:217], v172 offset:49152
	ds_read_b128 v[218:221], v172 offset:50176
	ds_read_b128 v[222:225], v172 offset:51200
	ds_read_b128 v[226:229], v172 offset:52224
	ds_read_b128 v[230:233], v172 offset:53248
	ds_read_b128 v[234:237], v172 offset:54272
	ds_read_b128 v[238:241], v172 offset:55296
	ds_read_b128 v[242:245], v172 offset:56320
	global_load_lds_dwordx4 v[144:145], off
	s_add_i32 m0, s3, 0x2000
	s_add_u32 s0, s0, 0x40080
	v_lshl_add_u64 v[144:145], v[246:247], 0, s[70:71]
	s_addc_u32 s1, s1, 0
	s_add_i32 s3, s6, s26
	global_load_lds_dwordx4 v[144:145], off
	v_lshl_add_u64 v[144:145], s[0:1], 0, v[4:5]
	s_mov_b32 m0, s3
	s_nop 0
	global_load_lds_dwordx4 v[144:145], off
	v_lshl_add_u64 v[144:145], s[0:1], 0, v[134:135]
	s_add_i32 m0, s3, 0x2000
	s_nop 0
	global_load_lds_dwordx4 v[144:145], off
	v_lshl_add_u64 v[144:145], v[248:249], 0, s[70:71]
	s_mov_b32 m0, s35
	s_nop 0
	global_load_lds_dwordx4 v[144:145], off
	v_lshl_add_u64 v[144:145], v[250:251], 0, s[70:71]
	s_mov_b32 m0, s36
	s_nop 0
	global_load_lds_dwordx4 v[144:145], off
	s_waitcnt vmcnt(8)
	s_waitcnt lgkmcnt(0)
	s_barrier
	s_setprio 0
	s_waitcnt lgkmcnt(0)
	v_mfma_f32_16x16x32_bf16 v[94:97], v[140:143], v[214:217], v[94:97]
	v_mfma_f32_16x16x32_bf16 v[90:93], v[190:193], v[214:217], v[90:93]
	v_mfma_f32_16x16x32_bf16 v[86:89], v[140:143], v[222:225], v[86:89]
	v_mfma_f32_16x16x32_bf16 v[82:85], v[190:193], v[222:225], v[82:85]
	v_mfma_f32_16x16x32_bf16 v[78:81], v[140:143], v[230:233], v[78:81]
	v_mfma_f32_16x16x32_bf16 v[74:77], v[190:193], v[230:233], v[74:77]
	v_mfma_f32_16x16x32_bf16 v[70:73], v[140:143], v[238:241], v[70:73]
	v_mfma_f32_16x16x32_bf16 v[66:69], v[190:193], v[238:241], v[66:69]
	v_mfma_f32_16x16x32_bf16 v[94:97], v[174:177], v[218:221], v[94:97]
	v_mfma_f32_16x16x32_bf16 v[90:93], v[194:197], v[218:221], v[90:93]
	v_mfma_f32_16x16x32_bf16 v[86:89], v[174:177], v[226:229], v[86:89]
	v_mfma_f32_16x16x32_bf16 v[82:85], v[194:197], v[226:229], v[82:85]
	v_mfma_f32_16x16x32_bf16 v[78:81], v[174:177], v[234:237], v[78:81]
	v_mfma_f32_16x16x32_bf16 v[74:77], v[194:197], v[234:237], v[74:77]
	v_mfma_f32_16x16x32_bf16 v[70:73], v[174:177], v[242:245], v[70:73]
	v_mfma_f32_16x16x32_bf16 v[66:69], v[194:197], v[242:245], v[66:69]
	v_mfma_f32_16x16x32_bf16 v[30:33], v[198:201], v[214:217], v[30:33]
	v_mfma_f32_16x16x32_bf16 v[26:29], v[206:209], v[214:217], v[26:29]
	v_mfma_f32_16x16x32_bf16 v[22:25], v[198:201], v[222:225], v[22:25]
	v_mfma_f32_16x16x32_bf16 v[18:21], v[206:209], v[222:225], v[18:21]
	v_mfma_f32_16x16x32_bf16 v[14:17], v[198:201], v[230:233], v[14:17]
	v_mfma_f32_16x16x32_bf16 v[10:13], v[206:209], v[230:233], v[10:13]
	v_mfma_f32_16x16x32_bf16 v[6:9], v[198:201], v[238:241], v[6:9]
	v_mfma_f32_16x16x32_bf16 v[0:3], v[206:209], v[238:241], v[0:3]
	v_mfma_f32_16x16x32_bf16 v[30:33], v[202:205], v[218:221], v[30:33]
	v_mfma_f32_16x16x32_bf16 v[26:29], v[210:213], v[218:221], v[26:29]
	v_mfma_f32_16x16x32_bf16 v[22:25], v[202:205], v[226:229], v[22:25]
	v_mfma_f32_16x16x32_bf16 v[18:21], v[210:213], v[226:229], v[18:21]
	v_mfma_f32_16x16x32_bf16 v[14:17], v[202:205], v[234:237], v[14:17]
	v_mfma_f32_16x16x32_bf16 v[10:13], v[210:213], v[234:237], v[10:13]
	v_mfma_f32_16x16x32_bf16 v[6:9], v[202:205], v[242:245], v[6:9]
	v_mfma_f32_16x16x32_bf16 v[0:3], v[210:213], v[242:245], v[0:3]
	s_setprio 1
	s_barrier
	s_add_i32 s24, s24, 2
	s_add_u32 s22, s22, 0x100
	s_addc_u32 s23, s23, 0
	s_add_u32 s9, s9, 0x100
	s_addc_u32 s10, s10, 0
	s_cmp_gt_u32 s24, 13
	s_cbranch_scc0 .LBB0_205
	s_and_b64 vcc, exec, s[46:47]
	s_cbranch_vccz .LBB0_208
	s_barrier

.LBB0_227:
	s_ashr_i32 s47, s46, 31
	s_lshl_b64 s[2:3], s[46:47], 19
	v_readlane_b32 s4, v253, 25
	v_readlane_b32 s5, v253, 26
	s_add_u32 s82, s4, s2
	s_addc_u32 s83, s5, s3
	s_and_b64 s[2:3], s[40:41], exec
	s_cselect_b32 s2, s83, s15
	s_cselect_b32 s8, s82, s14
	s_add_u32 s22, s0, 0x40080
	s_addc_u32 s23, s1, 0
	s_add_u32 s9, s14, 0x100
	v_mov_b32_e32 v0, 0
	s_addc_u32 s10, s15, 0
	s_mov_b32 s24, -2
	v_mov_b32_e32 v1, v0
	v_mov_b32_e32 v2, v0
	v_mov_b32_e32 v3, v0
	v_mov_b32_e32 v6, v0
	v_mov_b32_e32 v7, v0
	v_mov_b32_e32 v8, v0
	v_mov_b32_e32 v9, v0
	v_mov_b32_e32 v10, v0
	v_mov_b32_e32 v11, v0
	v_mov_b32_e32 v12, v0
	v_mov_b32_e32 v13, v0
	v_mov_b32_e32 v14, v0
	v_mov_b32_e32 v15, v0
	v_mov_b32_e32 v16, v0
	v_mov_b32_e32 v17, v0
	v_mov_b32_e32 v18, v0
	v_mov_b32_e32 v19, v0
	v_mov_b32_e32 v20, v0
	v_mov_b32_e32 v21, v0
	v_mov_b32_e32 v22, v0
	v_mov_b32_e32 v23, v0
	v_mov_b32_e32 v24, v0
	v_mov_b32_e32 v25, v0
	v_mov_b32_e32 v26, v0
	v_mov_b32_e32 v27, v0
	v_mov_b32_e32 v28, v0
	v_mov_b32_e32 v29, v0
	v_mov_b32_e32 v30, v0
	v_mov_b32_e32 v31, v0
	v_mov_b32_e32 v32, v0
	v_mov_b32_e32 v33, v0
	v_mov_b32_e32 v62, v0
	v_mov_b32_e32 v63, v0
	v_mov_b32_e32 v64, v0
	v_mov_b32_e32 v65, v0
	v_mov_b32_e32 v70, v0
	v_mov_b32_e32 v71, v0
	v_mov_b32_e32 v72, v0
	v_mov_b32_e32 v73, v0
	v_mov_b32_e32 v74, v0
	v_mov_b32_e32 v75, v0
	v_mov_b32_e32 v76, v0
	v_mov_b32_e32 v77, v0
	v_mov_b32_e32 v78, v0
	v_mov_b32_e32 v79, v0
	v_mov_b32_e32 v80, v0
	v_mov_b32_e32 v81, v0
	v_mov_b32_e32 v82, v0
	v_mov_b32_e32 v83, v0
	v_mov_b32_e32 v84, v0
	v_mov_b32_e32 v85, v0
	v_mov_b32_e32 v86, v0
	v_mov_b32_e32 v87, v0
	v_mov_b32_e32 v88, v0
	v_mov_b32_e32 v89, v0
	v_mov_b32_e32 v90, v0
	v_mov_b32_e32 v91, v0
	v_mov_b32_e32 v92, v0
	v_mov_b32_e32 v93, v0
	v_mov_b32_e32 v94, v0
	v_mov_b32_e32 v95, v0
	v_mov_b32_e32 v96, v0
	v_mov_b32_e32 v97, v0
	v_mov_b32_e32 v34, v0
	v_mov_b32_e32 v35, v0
	v_mov_b32_e32 v36, v0
	v_mov_b32_e32 v37, v0
	v_mov_b32_e32 v38, v0
	v_mov_b32_e32 v39, v0
	v_mov_b32_e32 v40, v0
	v_mov_b32_e32 v41, v0
	v_mov_b32_e32 v42, v0
	v_mov_b32_e32 v43, v0
	v_mov_b32_e32 v44, v0
	v_mov_b32_e32 v45, v0
	v_mov_b32_e32 v46, v0
	v_mov_b32_e32 v47, v0
	v_mov_b32_e32 v48, v0
	v_mov_b32_e32 v49, v0
	v_mov_b32_e32 v50, v0
	v_mov_b32_e32 v51, v0
	v_mov_b32_e32 v52, v0
	v_mov_b32_e32 v53, v0
	v_mov_b32_e32 v54, v0
	v_mov_b32_e32 v55, v0
	v_mov_b32_e32 v56, v0
	v_mov_b32_e32 v57, v0
	v_mov_b32_e32 v58, v0
	v_mov_b32_e32 v59, v0
	v_mov_b32_e32 v60, v0
	v_mov_b32_e32 v61, v0
	v_mov_b32_e32 v66, v0
	v_mov_b32_e32 v67, v0
	v_mov_b32_e32 v68, v0
	v_mov_b32_e32 v69, v0
	v_mov_b32_e32 v98, v0
	v_mov_b32_e32 v99, v0
	v_mov_b32_e32 v100, v0
	v_mov_b32_e32 v101, v0
	v_mov_b32_e32 v102, v0
	v_mov_b32_e32 v103, v0
	v_mov_b32_e32 v104, v0
	v_mov_b32_e32 v105, v0
	v_mov_b32_e32 v106, v0
	v_mov_b32_e32 v107, v0
	v_mov_b32_e32 v108, v0
	v_mov_b32_e32 v109, v0
	v_mov_b32_e32 v110, v0
	v_mov_b32_e32 v111, v0
	v_mov_b32_e32 v112, v0
	v_mov_b32_e32 v113, v0
	v_mov_b32_e32 v114, v0
	v_mov_b32_e32 v115, v0
	v_mov_b32_e32 v116, v0
	v_mov_b32_e32 v117, v0
	v_mov_b32_e32 v118, v0
	v_mov_b32_e32 v119, v0
	v_mov_b32_e32 v120, v0
	v_mov_b32_e32 v121, v0
	v_mov_b32_e32 v122, v0
	v_mov_b32_e32 v123, v0
	v_mov_b32_e32 v124, v0
	v_mov_b32_e32 v125, v0
	v_mov_b32_e32 v126, v0
	v_mov_b32_e32 v127, v0
	v_mov_b32_e32 v128, v0
	v_mov_b32_e32 v129, v0
	s_cmp_eq_u32 s37, 1
	s_cbranch_scc1 .LBB0_228
	s_add_u32 s0, s22, 0xfffc0080
	s_addc_u32 s1, s23, -1
	s_add_i32 s3, 0, 0x10000
	s_cmp_eq_u32 s24, 12
	s_cselect_b32 s15, s49, s1
	s_cselect_b32 s14, s48, s0
	v_add_u32_e32 v162, s3, v149
	s_cselect_b32 s1, s2, s10
	s_cselect_b32 s0, s8, s9
	s_add_i32 s6, 0, 0x14000
	ds_read_b128 v[140:143], v162
	ds_read_b128 v[144:147], v162 offset:1024
	ds_read_b128 v[172:175], v162 offset:2048
	ds_read_b128 v[190:193], v162 offset:3072
	v_add_u32_e32 v162, s6, v149
	ds_read_b128 v[194:197], v162
	ds_read_b128 v[198:201], v162 offset:1024
	ds_read_b128 v[202:205], v162 offset:2048
	ds_read_b128 v[206:209], v162 offset:3072
	v_lshl_add_u64 v[162:163], s[22:23], 0, v[136:137]
	s_add_i32 m0, s27, 0xc000
	ds_read_b128 v[210:213], v151
	ds_read_b128 v[214:217], v151 offset:1024
	ds_read_b128 v[218:221], v151 offset:2048
	ds_read_b128 v[222:225], v151 offset:3072
	ds_read_b128 v[226:229], v151 offset:4096
	ds_read_b128 v[230:233], v151 offset:5120
	ds_read_b128 v[234:237], v151 offset:6144
	ds_read_b128 v[238:241], v151 offset:7168
	global_load_lds_dwordx4 v[162:163], off
	v_lshl_add_u64 v[162:163], s[22:23], 0, v[138:139]
	s_add_i32 m0, s27, 0xe000
	s_nop 0
	global_load_lds_dwordx4 v[162:163], off
	s_waitcnt vmcnt(24)
	s_waitcnt lgkmcnt(0)
	s_barrier
	s_setprio 0
	s_waitcnt lgkmcnt(0)
	v_mfma_f32_16x16x32_bf16 v[126:129], v[140:143], v[210:213], v[126:129]
	v_mfma_f32_16x16x32_bf16 v[122:125], v[172:175], v[210:213], v[122:125]
	v_mfma_f32_16x16x32_bf16 v[118:121], v[140:143], v[218:221], v[118:121]
	v_mfma_f32_16x16x32_bf16 v[114:117], v[172:175], v[218:221], v[114:117]
	v_mfma_f32_16x16x32_bf16 v[110:113], v[140:143], v[226:229], v[110:113]
	v_mfma_f32_16x16x32_bf16 v[106:109], v[172:175], v[226:229], v[106:109]
	v_mfma_f32_16x16x32_bf16 v[102:105], v[140:143], v[234:237], v[102:105]
	v_mfma_f32_16x16x32_bf16 v[98:101], v[172:175], v[234:237], v[98:101]
	v_mfma_f32_16x16x32_bf16 v[126:129], v[144:147], v[214:217], v[126:129]
	v_mfma_f32_16x16x32_bf16 v[122:125], v[190:193], v[214:217], v[122:125]
	v_mfma_f32_16x16x32_bf16 v[118:121], v[144:147], v[222:225], v[118:121]
	v_mfma_f32_16x16x32_bf16 v[114:117], v[190:193], v[222:225], v[114:117]
	v_mfma_f32_16x16x32_bf16 v[110:113], v[144:147], v[230:233], v[110:113]
	v_mfma_f32_16x16x32_bf16 v[106:109], v[190:193], v[230:233], v[106:109]
	v_mfma_f32_16x16x32_bf16 v[102:105], v[144:147], v[238:241], v[102:105]
	v_mfma_f32_16x16x32_bf16 v[98:101], v[190:193], v[238:241], v[98:101]
	v_mfma_f32_16x16x32_bf16 v[66:69], v[194:197], v[210:213], v[66:69]
	v_mfma_f32_16x16x32_bf16 v[58:61], v[202:205], v[210:213], v[58:61]
	v_mfma_f32_16x16x32_bf16 v[54:57], v[194:197], v[218:221], v[54:57]
	v_mfma_f32_16x16x32_bf16 v[50:53], v[202:205], v[218:221], v[50:53]
	v_mfma_f32_16x16x32_bf16 v[46:49], v[194:197], v[226:229], v[46:49]
	v_mfma_f32_16x16x32_bf16 v[42:45], v[202:205], v[226:229], v[42:45]
	v_mfma_f32_16x16x32_bf16 v[38:41], v[194:197], v[234:237], v[38:41]
	v_mfma_f32_16x16x32_bf16 v[34:37], v[202:205], v[234:237], v[34:37]
	v_mfma_f32_16x16x32_bf16 v[66:69], v[198:201], v[214:217], v[66:69]
	v_mfma_f32_16x16x32_bf16 v[58:61], v[206:209], v[214:217], v[58:61]
	v_mfma_f32_16x16x32_bf16 v[54:57], v[198:201], v[222:225], v[54:57]
	v_mfma_f32_16x16x32_bf16 v[50:53], v[206:209], v[222:225], v[50:53]
	v_mfma_f32_16x16x32_bf16 v[46:49], v[198:201], v[230:233], v[46:49]
	v_mfma_f32_16x16x32_bf16 v[42:45], v[206:209], v[230:233], v[42:45]
	v_mfma_f32_16x16x32_bf16 v[38:41], v[198:201], v[238:241], v[38:41]
	v_mfma_f32_16x16x32_bf16 v[34:37], v[206:209], v[238:241], v[34:37]
	s_setprio 1
	s_barrier
	s_add_i32 s3, s3, s26
	v_lshl_add_u64 v[162:163], s[0:1], 0, v[4:5]
	s_mov_b32 m0, s3
	ds_read_b128 v[210:213], v151 offset:16384
	ds_read_b128 v[214:217], v151 offset:17408
	ds_read_b128 v[218:221], v151 offset:18432
	ds_read_b128 v[222:225], v151 offset:19456
	ds_read_b128 v[226:229], v151 offset:20480
	ds_read_b128 v[230:233], v151 offset:21504
	ds_read_b128 v[234:237], v151 offset:22528
	ds_read_b128 v[238:241], v151 offset:23552
	global_load_lds_dwordx4 v[162:163], off
	s_add_i32 m0, s3, 0x2000
	s_add_u32 s4, s0, 0x40000
	v_lshl_add_u64 v[166:167], s[0:1], 0, v[134:135]
	s_addc_u32 s5, s1, 0
	s_add_i32 s3, s6, s26
	global_load_lds_dwordx4 v[166:167], off
	v_lshl_add_u64 v[176:177], s[4:5], 0, v[4:5]
	s_mov_b32 m0, s3
	v_lshl_add_u64 v[180:181], s[14:15], 0, v[132:133]
	global_load_lds_dwordx4 v[176:177], off
	v_lshl_add_u64 v[176:177], s[4:5], 0, v[134:135]
	s_add_i32 m0, s3, 0x2000
	s_nop 0
	global_load_lds_dwordx4 v[176:177], off
	v_lshl_add_u64 v[176:177], s[14:15], 0, v[130:131]
	s_mov_b32 m0, s27
	s_nop 0
	global_load_lds_dwordx4 v[176:177], off
	s_mov_b32 m0, s30
	s_nop 0
	global_load_lds_dwordx4 v[180:181], off
	s_waitcnt vmcnt(24)
	s_waitcnt lgkmcnt(0)
	s_barrier
	s_setprio 0
	s_waitcnt lgkmcnt(0)
	v_mfma_f32_16x16x32_bf16 v[94:97], v[140:143], v[210:213], v[94:97]
	v_mfma_f32_16x16x32_bf16 v[90:93], v[172:175], v[210:213], v[90:93]
	v_mfma_f32_16x16x32_bf16 v[86:89], v[140:143], v[218:221], v[86:89]
	v_mfma_f32_16x16x32_bf16 v[82:85], v[172:175], v[218:221], v[82:85]
	v_mfma_f32_16x16x32_bf16 v[78:81], v[140:143], v[226:229], v[78:81]
	v_mfma_f32_16x16x32_bf16 v[74:77], v[172:175], v[226:229], v[74:77]
	v_mfma_f32_16x16x32_bf16 v[70:73], v[140:143], v[234:237], v[70:73]
	v_mfma_f32_16x16x32_bf16 v[62:65], v[172:175], v[234:237], v[62:65]
	v_mfma_f32_16x16x32_bf16 v[94:97], v[144:147], v[214:217], v[94:97]
	v_mfma_f32_16x16x32_bf16 v[90:93], v[190:193], v[214:217], v[90:93]
	v_mfma_f32_16x16x32_bf16 v[86:89], v[144:147], v[222:225], v[86:89]
	v_mfma_f32_16x16x32_bf16 v[82:85], v[190:193], v[222:225], v[82:85]
	v_mfma_f32_16x16x32_bf16 v[78:81], v[144:147], v[230:233], v[78:81]
	v_mfma_f32_16x16x32_bf16 v[74:77], v[190:193], v[230:233], v[74:77]
	v_mfma_f32_16x16x32_bf16 v[70:73], v[144:147], v[238:241], v[70:73]
	v_mfma_f32_16x16x32_bf16 v[62:65], v[190:193], v[238:241], v[62:65]
	v_mfma_f32_16x16x32_bf16 v[30:33], v[194:197], v[210:213], v[30:33]
	v_mfma_f32_16x16x32_bf16 v[26:29], v[202:205], v[210:213], v[26:29]
	v_mfma_f32_16x16x32_bf16 v[22:25], v[194:197], v[218:221], v[22:25]
	v_mfma_f32_16x16x32_bf16 v[18:21], v[202:205], v[218:221], v[18:21]
	v_mfma_f32_16x16x32_bf16 v[14:17], v[194:197], v[226:229], v[14:17]
	v_mfma_f32_16x16x32_bf16 v[10:13], v[202:205], v[226:229], v[10:13]
	v_mfma_f32_16x16x32_bf16 v[6:9], v[194:197], v[234:237], v[6:9]
	v_mfma_f32_16x16x32_bf16 v[0:3], v[202:205], v[234:237], v[0:3]
	v_mfma_f32_16x16x32_bf16 v[30:33], v[198:201], v[214:217], v[30:33]
	v_mfma_f32_16x16x32_bf16 v[26:29], v[206:209], v[214:217], v[26:29]
	v_mfma_f32_16x16x32_bf16 v[22:25], v[198:201], v[222:225], v[22:25]
	v_mfma_f32_16x16x32_bf16 v[18:21], v[206:209], v[222:225], v[18:21]
	v_mfma_f32_16x16x32_bf16 v[14:17], v[198:201], v[230:233], v[14:17]
	v_mfma_f32_16x16x32_bf16 v[10:13], v[206:209], v[230:233], v[10:13]
	v_mfma_f32_16x16x32_bf16 v[6:9], v[198:201], v[238:241], v[6:9]
	v_mfma_f32_16x16x32_bf16 v[0:3], v[206:209], v[238:241], v[0:3]
	s_setprio 1
	s_barrier
	s_branch .Lpeelmid_228
.LBB0_228:
	s_add_u32 s0, s22, 0xfffc0080
	s_addc_u32 s1, s23, -1
	s_add_i32 s3, 0, 0x10000
	s_cmp_eq_u32 s24, 12
	s_cselect_b32 s15, s49, s1
	s_cselect_b32 s14, s48, s0
	v_add_u32_e32 v162, s3, v149
	s_cselect_b32 s1, s2, s10
	s_cselect_b32 s0, s8, s9
	s_add_i32 s6, 0, 0x14000
	ds_read_b128 v[140:143], v162
	ds_read_b128 v[144:147], v162 offset:1024
	ds_read_b128 v[172:175], v162 offset:2048
	ds_read_b128 v[190:193], v162 offset:3072
	v_add_u32_e32 v162, s6, v149
	ds_read_b128 v[194:197], v162
	ds_read_b128 v[198:201], v162 offset:1024
	ds_read_b128 v[202:205], v162 offset:2048
	ds_read_b128 v[206:209], v162 offset:3072
	v_lshl_add_u64 v[162:163], s[22:23], 0, v[136:137]
	s_add_i32 m0, s27, 0xc000
	ds_read_b128 v[210:213], v151
	ds_read_b128 v[214:217], v151 offset:1024
	ds_read_b128 v[218:221], v151 offset:2048
	ds_read_b128 v[222:225], v151 offset:3072
	ds_read_b128 v[226:229], v151 offset:4096
	ds_read_b128 v[230:233], v151 offset:5120
	ds_read_b128 v[234:237], v151 offset:6144
	ds_read_b128 v[238:241], v151 offset:7168
	global_load_lds_dwordx4 v[162:163], off
	v_lshl_add_u64 v[162:163], s[22:23], 0, v[138:139]
	s_add_i32 m0, s27, 0xe000
	s_nop 0
	global_load_lds_dwordx4 v[162:163], off
	s_waitcnt vmcnt(8)
	s_waitcnt lgkmcnt(0)
	s_barrier
	s_setprio 0
	s_waitcnt lgkmcnt(0)
	v_mfma_f32_16x16x32_bf16 v[126:129], v[140:143], v[210:213], v[126:129]
	v_mfma_f32_16x16x32_bf16 v[122:125], v[172:175], v[210:213], v[122:125]
	v_mfma_f32_16x16x32_bf16 v[118:121], v[140:143], v[218:221], v[118:121]
	v_mfma_f32_16x16x32_bf16 v[114:117], v[172:175], v[218:221], v[114:117]
	v_mfma_f32_16x16x32_bf16 v[110:113], v[140:143], v[226:229], v[110:113]
	v_mfma_f32_16x16x32_bf16 v[106:109], v[172:175], v[226:229], v[106:109]
	v_mfma_f32_16x16x32_bf16 v[102:105], v[140:143], v[234:237], v[102:105]
	v_mfma_f32_16x16x32_bf16 v[98:101], v[172:175], v[234:237], v[98:101]
	v_mfma_f32_16x16x32_bf16 v[126:129], v[144:147], v[214:217], v[126:129]
	v_mfma_f32_16x16x32_bf16 v[122:125], v[190:193], v[214:217], v[122:125]
	v_mfma_f32_16x16x32_bf16 v[118:121], v[144:147], v[222:225], v[118:121]
	v_mfma_f32_16x16x32_bf16 v[114:117], v[190:193], v[222:225], v[114:117]
	v_mfma_f32_16x16x32_bf16 v[110:113], v[144:147], v[230:233], v[110:113]
	v_mfma_f32_16x16x32_bf16 v[106:109], v[190:193], v[230:233], v[106:109]
	v_mfma_f32_16x16x32_bf16 v[102:105], v[144:147], v[238:241], v[102:105]
	v_mfma_f32_16x16x32_bf16 v[98:101], v[190:193], v[238:241], v[98:101]
	v_mfma_f32_16x16x32_bf16 v[66:69], v[194:197], v[210:213], v[66:69]
	v_mfma_f32_16x16x32_bf16 v[58:61], v[202:205], v[210:213], v[58:61]
	v_mfma_f32_16x16x32_bf16 v[54:57], v[194:197], v[218:221], v[54:57]
	v_mfma_f32_16x16x32_bf16 v[50:53], v[202:205], v[218:221], v[50:53]
	v_mfma_f32_16x16x32_bf16 v[46:49], v[194:197], v[226:229], v[46:49]
	v_mfma_f32_16x16x32_bf16 v[42:45], v[202:205], v[226:229], v[42:45]
	v_mfma_f32_16x16x32_bf16 v[38:41], v[194:197], v[234:237], v[38:41]
	v_mfma_f32_16x16x32_bf16 v[34:37], v[202:205], v[234:237], v[34:37]
	v_mfma_f32_16x16x32_bf16 v[66:69], v[198:201], v[214:217], v[66:69]
	v_mfma_f32_16x16x32_bf16 v[58:61], v[206:209], v[214:217], v[58:61]
	v_mfma_f32_16x16x32_bf16 v[54:57], v[198:201], v[222:225], v[54:57]
	v_mfma_f32_16x16x32_bf16 v[50:53], v[206:209], v[222:225], v[50:53]
	v_mfma_f32_16x16x32_bf16 v[46:49], v[198:201], v[230:233], v[46:49]
	v_mfma_f32_16x16x32_bf16 v[42:45], v[206:209], v[230:233], v[42:45]
	v_mfma_f32_16x16x32_bf16 v[38:41], v[198:201], v[238:241], v[38:41]
	v_mfma_f32_16x16x32_bf16 v[34:37], v[206:209], v[238:241], v[34:37]
	s_setprio 1
	s_barrier
	s_add_i32 s3, s3, s26
	v_lshl_add_u64 v[162:163], s[0:1], 0, v[4:5]
	s_mov_b32 m0, s3
	ds_read_b128 v[210:213], v151 offset:16384
	ds_read_b128 v[214:217], v151 offset:17408
	ds_read_b128 v[218:221], v151 offset:18432
	ds_read_b128 v[222:225], v151 offset:19456
	ds_read_b128 v[226:229], v151 offset:20480
	ds_read_b128 v[230:233], v151 offset:21504
	ds_read_b128 v[234:237], v151 offset:22528
	ds_read_b128 v[238:241], v151 offset:23552
	global_load_lds_dwordx4 v[162:163], off
	s_add_i32 m0, s3, 0x2000
	s_add_u32 s4, s0, 0x40000
	v_lshl_add_u64 v[166:167], s[0:1], 0, v[134:135]
	s_addc_u32 s5, s1, 0
	s_add_i32 s3, s6, s26
	global_load_lds_dwordx4 v[166:167], off
	v_lshl_add_u64 v[176:177], s[4:5], 0, v[4:5]
	s_mov_b32 m0, s3
	v_lshl_add_u64 v[180:181], s[14:15], 0, v[132:133]
	global_load_lds_dwordx4 v[176:177], off
	v_lshl_add_u64 v[176:177], s[4:5], 0, v[134:135]
	s_add_i32 m0, s3, 0x2000
	s_nop 0
	global_load_lds_dwordx4 v[176:177], off
	v_lshl_add_u64 v[176:177], s[14:15], 0, v[130:131]
	s_mov_b32 m0, s27
	s_nop 0
	global_load_lds_dwordx4 v[176:177], off
	s_mov_b32 m0, s30
	s_nop 0
	global_load_lds_dwordx4 v[180:181], off
	s_waitcnt vmcnt(8)
	s_waitcnt lgkmcnt(0)
	s_barrier
	s_setprio 0
	s_waitcnt lgkmcnt(0)
	v_mfma_f32_16x16x32_bf16 v[94:97], v[140:143], v[210:213], v[94:97]
	v_mfma_f32_16x16x32_bf16 v[90:93], v[172:175], v[210:213], v[90:93]
	v_mfma_f32_16x16x32_bf16 v[86:89], v[140:143], v[218:221], v[86:89]
	v_mfma_f32_16x16x32_bf16 v[82:85], v[172:175], v[218:221], v[82:85]
	v_mfma_f32_16x16x32_bf16 v[78:81], v[140:143], v[226:229], v[78:81]
	v_mfma_f32_16x16x32_bf16 v[74:77], v[172:175], v[226:229], v[74:77]
	v_mfma_f32_16x16x32_bf16 v[70:73], v[140:143], v[234:237], v[70:73]
	v_mfma_f32_16x16x32_bf16 v[62:65], v[172:175], v[234:237], v[62:65]
	v_mfma_f32_16x16x32_bf16 v[94:97], v[144:147], v[214:217], v[94:97]
	v_mfma_f32_16x16x32_bf16 v[90:93], v[190:193], v[214:217], v[90:93]
	v_mfma_f32_16x16x32_bf16 v[86:89], v[144:147], v[222:225], v[86:89]
	v_mfma_f32_16x16x32_bf16 v[82:85], v[190:193], v[222:225], v[82:85]
	v_mfma_f32_16x16x32_bf16 v[78:81], v[144:147], v[230:233], v[78:81]
	v_mfma_f32_16x16x32_bf16 v[74:77], v[190:193], v[230:233], v[74:77]
	v_mfma_f32_16x16x32_bf16 v[70:73], v[144:147], v[238:241], v[70:73]
	v_mfma_f32_16x16x32_bf16 v[62:65], v[190:193], v[238:241], v[62:65]
	v_mfma_f32_16x16x32_bf16 v[30:33], v[194:197], v[210:213], v[30:33]
	v_mfma_f32_16x16x32_bf16 v[26:29], v[202:205], v[210:213], v[26:29]
	v_mfma_f32_16x16x32_bf16 v[22:25], v[194:197], v[218:221], v[22:25]
	v_mfma_f32_16x16x32_bf16 v[18:21], v[202:205], v[218:221], v[18:21]
	v_mfma_f32_16x16x32_bf16 v[14:17], v[194:197], v[226:229], v[14:17]
	v_mfma_f32_16x16x32_bf16 v[10:13], v[202:205], v[226:229], v[10:13]
	v_mfma_f32_16x16x32_bf16 v[6:9], v[194:197], v[234:237], v[6:9]
	v_mfma_f32_16x16x32_bf16 v[0:3], v[202:205], v[234:237], v[0:3]
	v_mfma_f32_16x16x32_bf16 v[30:33], v[198:201], v[214:217], v[30:33]
	v_mfma_f32_16x16x32_bf16 v[26:29], v[206:209], v[214:217], v[26:29]
	v_mfma_f32_16x16x32_bf16 v[22:25], v[198:201], v[222:225], v[22:25]
	v_mfma_f32_16x16x32_bf16 v[18:21], v[206:209], v[222:225], v[18:21]
	v_mfma_f32_16x16x32_bf16 v[14:17], v[198:201], v[230:233], v[14:17]
	v_mfma_f32_16x16x32_bf16 v[10:13], v[206:209], v[230:233], v[10:13]
	v_mfma_f32_16x16x32_bf16 v[6:9], v[198:201], v[238:241], v[6:9]
	v_mfma_f32_16x16x32_bf16 v[0:3], v[206:209], v[238:241], v[0:3]
	s_setprio 1
	s_barrier
.Lpeelmid_228:
	s_add_i32 s3, 0, 0x18000
	v_add_u32_e32 v164, s3, v149
	s_add_i32 s6, 0, 0x1c000
	ds_read_b128 v[140:143], v164
	ds_read_b128 v[144:147], v164 offset:1024
	ds_read_b128 v[172:175], v164 offset:2048
	ds_read_b128 v[190:193], v164 offset:3072
	v_add_u32_e32 v164, s6, v149
	ds_read_b128 v[194:197], v164
	ds_read_b128 v[198:201], v164 offset:1024
	ds_read_b128 v[202:205], v164 offset:2048
	ds_read_b128 v[206:209], v164 offset:3072
	s_add_u32 s4, s14, 0x40000
	s_addc_u32 s5, s15, 0
	s_mov_b32 m0, s31
	v_lshl_add_u64 v[242:243], s[4:5], 0, v[130:131]
	ds_read_b128 v[210:213], v151 offset:32768
	ds_read_b128 v[214:217], v151 offset:33792
	ds_read_b128 v[218:221], v151 offset:34816
	ds_read_b128 v[222:225], v151 offset:35840
	ds_read_b128 v[226:229], v151 offset:36864
	ds_read_b128 v[230:233], v151 offset:37888
	ds_read_b128 v[234:237], v151 offset:38912
	ds_read_b128 v[238:241], v151 offset:39936
	global_load_lds_dwordx4 v[242:243], off
	v_lshl_add_u64 v[242:243], s[4:5], 0, v[132:133]
	s_mov_b32 m0, s34
	s_nop 0
	global_load_lds_dwordx4 v[242:243], off
	s_waitcnt vmcnt(8)
	s_waitcnt lgkmcnt(0)
	s_barrier
	s_setprio 0
	s_waitcnt lgkmcnt(0)
	v_mfma_f32_16x16x32_bf16 v[126:129], v[140:143], v[210:213], v[126:129]
	v_mfma_f32_16x16x32_bf16 v[122:125], v[172:175], v[210:213], v[122:125]
	v_mfma_f32_16x16x32_bf16 v[118:121], v[140:143], v[218:221], v[118:121]
	v_mfma_f32_16x16x32_bf16 v[114:117], v[172:175], v[218:221], v[114:117]
	v_mfma_f32_16x16x32_bf16 v[110:113], v[140:143], v[226:229], v[110:113]
	v_mfma_f32_16x16x32_bf16 v[106:109], v[172:175], v[226:229], v[106:109]
	v_mfma_f32_16x16x32_bf16 v[102:105], v[140:143], v[234:237], v[102:105]
	v_mfma_f32_16x16x32_bf16 v[98:101], v[172:175], v[234:237], v[98:101]
	v_mfma_f32_16x16x32_bf16 v[126:129], v[144:147], v[214:217], v[126:129]
	v_mfma_f32_16x16x32_bf16 v[122:125], v[190:193], v[214:217], v[122:125]
	v_mfma_f32_16x16x32_bf16 v[118:121], v[144:147], v[222:225], v[118:121]
	v_mfma_f32_16x16x32_bf16 v[114:117], v[190:193], v[222:225], v[114:117]
	v_mfma_f32_16x16x32_bf16 v[110:113], v[144:147], v[230:233], v[110:113]
	v_mfma_f32_16x16x32_bf16 v[106:109], v[190:193], v[230:233], v[106:109]
	v_mfma_f32_16x16x32_bf16 v[102:105], v[144:147], v[238:241], v[102:105]
	v_mfma_f32_16x16x32_bf16 v[98:101], v[190:193], v[238:241], v[98:101]
	v_mfma_f32_16x16x32_bf16 v[66:69], v[194:197], v[210:213], v[66:69]
	v_mfma_f32_16x16x32_bf16 v[58:61], v[202:205], v[210:213], v[58:61]
	v_mfma_f32_16x16x32_bf16 v[54:57], v[194:197], v[218:221], v[54:57]
	v_mfma_f32_16x16x32_bf16 v[50:53], v[202:205], v[218:221], v[50:53]
	v_mfma_f32_16x16x32_bf16 v[46:49], v[194:197], v[226:229], v[46:49]
	v_mfma_f32_16x16x32_bf16 v[42:45], v[202:205], v[226:229], v[42:45]
	v_mfma_f32_16x16x32_bf16 v[38:41], v[194:197], v[234:237], v[38:41]
	v_mfma_f32_16x16x32_bf16 v[34:37], v[202:205], v[234:237], v[34:37]
	v_mfma_f32_16x16x32_bf16 v[66:69], v[198:201], v[214:217], v[66:69]
	v_mfma_f32_16x16x32_bf16 v[58:61], v[206:209], v[214:217], v[58:61]
	v_mfma_f32_16x16x32_bf16 v[54:57], v[198:201], v[222:225], v[54:57]
	v_mfma_f32_16x16x32_bf16 v[50:53], v[206:209], v[222:225], v[50:53]
	v_mfma_f32_16x16x32_bf16 v[46:49], v[198:201], v[230:233], v[46:49]
	v_mfma_f32_16x16x32_bf16 v[42:45], v[206:209], v[230:233], v[42:45]
	v_mfma_f32_16x16x32_bf16 v[38:41], v[198:201], v[238:241], v[38:41]
	v_mfma_f32_16x16x32_bf16 v[34:37], v[206:209], v[238:241], v[34:37]
	s_setprio 1
	s_barrier
	s_add_i32 s3, s3, s26
	v_lshl_add_u64 v[162:163], v[162:163], 0, s[70:71]
	s_mov_b32 m0, s3
	ds_read_b128 v[210:213], v151 offset:49152
	ds_read_b128 v[214:217], v151 offset:50176
	ds_read_b128 v[218:221], v151 offset:51200
	ds_read_b128 v[222:225], v151 offset:52224
	ds_read_b128 v[226:229], v151 offset:53248
	ds_read_b128 v[230:233], v151 offset:54272
	ds_read_b128 v[234:237], v151 offset:55296
	ds_read_b128 v[238:241], v151 offset:56320
	global_load_lds_dwordx4 v[162:163], off
	s_add_i32 m0, s3, 0x2000
	s_add_u32 s0, s0, 0x40080
	v_lshl_add_u64 v[162:163], v[166:167], 0, s[70:71]
	s_addc_u32 s1, s1, 0
	s_add_i32 s3, s6, s26
	global_load_lds_dwordx4 v[162:163], off
	v_lshl_add_u64 v[162:163], s[0:1], 0, v[4:5]
	s_mov_b32 m0, s3
	s_nop 0
	global_load_lds_dwordx4 v[162:163], off
	v_lshl_add_u64 v[162:163], s[0:1], 0, v[134:135]
	s_add_i32 m0, s3, 0x2000
	s_nop 0
	global_load_lds_dwordx4 v[162:163], off
	v_lshl_add_u64 v[162:163], v[176:177], 0, s[70:71]
	s_mov_b32 m0, s35
	s_nop 0
	global_load_lds_dwordx4 v[162:163], off
	v_lshl_add_u64 v[162:163], v[180:181], 0, s[70:71]
	s_mov_b32 m0, s36
	s_nop 0
	global_load_lds_dwordx4 v[162:163], off
	s_waitcnt vmcnt(8)
	s_waitcnt lgkmcnt(0)
	s_barrier
	s_setprio 0
	s_waitcnt lgkmcnt(0)
	v_mfma_f32_16x16x32_bf16 v[94:97], v[140:143], v[210:213], v[94:97]
	v_mfma_f32_16x16x32_bf16 v[90:93], v[172:175], v[210:213], v[90:93]
	v_mfma_f32_16x16x32_bf16 v[86:89], v[140:143], v[218:221], v[86:89]
	v_mfma_f32_16x16x32_bf16 v[82:85], v[172:175], v[218:221], v[82:85]
	v_mfma_f32_16x16x32_bf16 v[78:81], v[140:143], v[226:229], v[78:81]
	v_mfma_f32_16x16x32_bf16 v[74:77], v[172:175], v[226:229], v[74:77]
	v_mfma_f32_16x16x32_bf16 v[70:73], v[140:143], v[234:237], v[70:73]
	v_mfma_f32_16x16x32_bf16 v[62:65], v[172:175], v[234:237], v[62:65]
	v_mfma_f32_16x16x32_bf16 v[94:97], v[144:147], v[214:217], v[94:97]
	v_mfma_f32_16x16x32_bf16 v[90:93], v[190:193], v[214:217], v[90:93]
	v_mfma_f32_16x16x32_bf16 v[86:89], v[144:147], v[222:225], v[86:89]
	v_mfma_f32_16x16x32_bf16 v[82:85], v[190:193], v[222:225], v[82:85]
	v_mfma_f32_16x16x32_bf16 v[78:81], v[144:147], v[230:233], v[78:81]
	v_mfma_f32_16x16x32_bf16 v[74:77], v[190:193], v[230:233], v[74:77]
	v_mfma_f32_16x16x32_bf16 v[70:73], v[144:147], v[238:241], v[70:73]
	v_mfma_f32_16x16x32_bf16 v[62:65], v[190:193], v[238:241], v[62:65]
	v_mfma_f32_16x16x32_bf16 v[30:33], v[194:197], v[210:213], v[30:33]
	v_mfma_f32_16x16x32_bf16 v[26:29], v[202:205], v[210:213], v[26:29]
	v_mfma_f32_16x16x32_bf16 v[22:25], v[194:197], v[218:221], v[22:25]
	v_mfma_f32_16x16x32_bf16 v[18:21], v[202:205], v[218:221], v[18:21]
	v_mfma_f32_16x16x32_bf16 v[14:17], v[194:197], v[226:229], v[14:17]
	v_mfma_f32_16x16x32_bf16 v[10:13], v[202:205], v[226:229], v[10:13]
	v_mfma_f32_16x16x32_bf16 v[6:9], v[194:197], v[234:237], v[6:9]
	v_mfma_f32_16x16x32_bf16 v[0:3], v[202:205], v[234:237], v[0:3]
	v_mfma_f32_16x16x32_bf16 v[30:33], v[198:201], v[214:217], v[30:33]
	v_mfma_f32_16x16x32_bf16 v[26:29], v[206:209], v[214:217], v[26:29]
	v_mfma_f32_16x16x32_bf16 v[22:25], v[198:201], v[222:225], v[22:25]
	v_mfma_f32_16x16x32_bf16 v[18:21], v[206:209], v[222:225], v[18:21]
	v_mfma_f32_16x16x32_bf16 v[14:17], v[198:201], v[230:233], v[14:17]
	v_mfma_f32_16x16x32_bf16 v[10:13], v[206:209], v[230:233], v[10:13]
	v_mfma_f32_16x16x32_bf16 v[6:9], v[198:201], v[238:241], v[6:9]
	v_mfma_f32_16x16x32_bf16 v[0:3], v[206:209], v[238:241], v[0:3]
	s_setprio 1
	s_barrier
	s_add_i32 s24, s24, 2
	s_add_u32 s22, s22, 0x100
	s_addc_u32 s23, s23, 0
	s_add_u32 s9, s9, 0x100
	s_addc_u32 s10, s10, 0
	s_cmp_gt_u32 s24, 13
	s_cbranch_scc0 .LBB0_228
	s_and_b64 vcc, exec, s[44:45]
	s_cbranch_vccz .LBB0_231
	s_barrier

.LBB0_251:
	s_ashr_i32 s47, s46, 31
	s_lshl_b64 s[2:3], s[46:47], 20
	v_readlane_b32 s4, v253, 36
	s_add_u32 s82, s4, s2
	v_readlane_b32 s2, v253, 37
	s_addc_u32 s83, s2, s3
	s_and_b64 s[2:3], s[40:41], exec
	s_cselect_b32 s2, s83, s15
	s_cselect_b32 s8, s82, s14
	s_add_u32 s22, s0, 0x80080
	s_addc_u32 s23, s1, 0
	s_add_u32 s9, s14, 0x100
	v_mov_b32_e32 v0, 0
	s_addc_u32 s10, s15, 0
	s_mov_b32 s24, -2
	v_mov_b32_e32 v1, v0
	v_mov_b32_e32 v2, v0
	v_mov_b32_e32 v3, v0
	v_mov_b32_e32 v6, v0
	v_mov_b32_e32 v7, v0
	v_mov_b32_e32 v8, v0
	v_mov_b32_e32 v9, v0
	v_mov_b32_e32 v10, v0
	v_mov_b32_e32 v11, v0
	v_mov_b32_e32 v12, v0
	v_mov_b32_e32 v13, v0
	v_mov_b32_e32 v14, v0
	v_mov_b32_e32 v15, v0
	v_mov_b32_e32 v16, v0
	v_mov_b32_e32 v17, v0
	v_mov_b32_e32 v18, v0
	v_mov_b32_e32 v19, v0
	v_mov_b32_e32 v20, v0
	v_mov_b32_e32 v21, v0
	v_mov_b32_e32 v22, v0
	v_mov_b32_e32 v23, v0
	v_mov_b32_e32 v24, v0
	v_mov_b32_e32 v25, v0
	v_mov_b32_e32 v26, v0
	v_mov_b32_e32 v27, v0
	v_mov_b32_e32 v28, v0
	v_mov_b32_e32 v29, v0
	v_mov_b32_e32 v30, v0
	v_mov_b32_e32 v31, v0
	v_mov_b32_e32 v32, v0
	v_mov_b32_e32 v33, v0
	v_mov_b32_e32 v62, v0
	v_mov_b32_e32 v63, v0
	v_mov_b32_e32 v64, v0
	v_mov_b32_e32 v65, v0
	v_mov_b32_e32 v70, v0
	v_mov_b32_e32 v71, v0
	v_mov_b32_e32 v72, v0
	v_mov_b32_e32 v73, v0
	v_mov_b32_e32 v74, v0
	v_mov_b32_e32 v75, v0
	v_mov_b32_e32 v76, v0
	v_mov_b32_e32 v77, v0
	v_mov_b32_e32 v78, v0
	v_mov_b32_e32 v79, v0
	v_mov_b32_e32 v80, v0
	v_mov_b32_e32 v81, v0
	v_mov_b32_e32 v82, v0
	v_mov_b32_e32 v83, v0
	v_mov_b32_e32 v84, v0
	v_mov_b32_e32 v85, v0
	v_mov_b32_e32 v86, v0
	v_mov_b32_e32 v87, v0
	v_mov_b32_e32 v88, v0
	v_mov_b32_e32 v89, v0
	v_mov_b32_e32 v90, v0
	v_mov_b32_e32 v91, v0
	v_mov_b32_e32 v92, v0
	v_mov_b32_e32 v93, v0
	v_mov_b32_e32 v94, v0
	v_mov_b32_e32 v95, v0
	v_mov_b32_e32 v96, v0
	v_mov_b32_e32 v97, v0
	v_mov_b32_e32 v34, v0
	v_mov_b32_e32 v35, v0
	v_mov_b32_e32 v36, v0
	v_mov_b32_e32 v37, v0
	v_mov_b32_e32 v38, v0
	v_mov_b32_e32 v39, v0
	v_mov_b32_e32 v40, v0
	v_mov_b32_e32 v41, v0
	v_mov_b32_e32 v42, v0
	v_mov_b32_e32 v43, v0
	v_mov_b32_e32 v44, v0
	v_mov_b32_e32 v45, v0
	v_mov_b32_e32 v46, v0
	v_mov_b32_e32 v47, v0
	v_mov_b32_e32 v48, v0
	v_mov_b32_e32 v49, v0
	v_mov_b32_e32 v50, v0
	v_mov_b32_e32 v51, v0
	v_mov_b32_e32 v52, v0
	v_mov_b32_e32 v53, v0
	v_mov_b32_e32 v54, v0
	v_mov_b32_e32 v55, v0
	v_mov_b32_e32 v56, v0
	v_mov_b32_e32 v57, v0
	v_mov_b32_e32 v58, v0
	v_mov_b32_e32 v59, v0
	v_mov_b32_e32 v60, v0
	v_mov_b32_e32 v61, v0
	v_mov_b32_e32 v66, v0
	v_mov_b32_e32 v67, v0
	v_mov_b32_e32 v68, v0
	v_mov_b32_e32 v69, v0
	v_mov_b32_e32 v98, v0
	v_mov_b32_e32 v99, v0
	v_mov_b32_e32 v100, v0
	v_mov_b32_e32 v101, v0
	v_mov_b32_e32 v102, v0
	v_mov_b32_e32 v103, v0
	v_mov_b32_e32 v104, v0
	v_mov_b32_e32 v105, v0
	v_mov_b32_e32 v106, v0
	v_mov_b32_e32 v107, v0
	v_mov_b32_e32 v108, v0
	v_mov_b32_e32 v109, v0
	v_mov_b32_e32 v110, v0
	v_mov_b32_e32 v111, v0
	v_mov_b32_e32 v112, v0
	v_mov_b32_e32 v113, v0
	v_mov_b32_e32 v114, v0
	v_mov_b32_e32 v115, v0
	v_mov_b32_e32 v116, v0
	v_mov_b32_e32 v117, v0
	v_mov_b32_e32 v118, v0
	v_mov_b32_e32 v119, v0
	v_mov_b32_e32 v120, v0
	v_mov_b32_e32 v121, v0
	v_mov_b32_e32 v122, v0
	v_mov_b32_e32 v123, v0
	v_mov_b32_e32 v124, v0
	v_mov_b32_e32 v125, v0
	v_mov_b32_e32 v126, v0
	v_mov_b32_e32 v127, v0
	v_mov_b32_e32 v128, v0
	v_mov_b32_e32 v129, v0
	s_cmp_eq_u32 s37, 1
	s_cbranch_scc1 .LBB0_252
	s_add_u32 s0, s22, 0xfff80080
	s_addc_u32 s1, s23, -1
	s_add_i32 s3, 0, 0x10000
	s_cmp_eq_u32 s24, 28
	s_cselect_b32 s15, s49, s1
	s_cselect_b32 s14, s48, s0
	v_add_u32_e32 v162, s3, v141
	s_cselect_b32 s1, s2, s10
	s_cselect_b32 s0, s8, s9
	s_add_i32 s6, 0, 0x14000
	ds_read_b128 v[144:147], v162
	ds_read_b128 v[148:151], v162 offset:1024
	ds_read_b128 v[172:175], v162 offset:2048
	ds_read_b128 v[190:193], v162 offset:3072
	v_add_u32_e32 v162, s6, v141
	ds_read_b128 v[194:197], v162
	ds_read_b128 v[198:201], v162 offset:1024
	ds_read_b128 v[202:205], v162 offset:2048
	ds_read_b128 v[206:209], v162 offset:3072
	v_lshl_add_u64 v[162:163], s[22:23], 0, v[136:137]
	s_add_i32 m0, s27, 0xc000
	ds_read_b128 v[210:213], v143
	ds_read_b128 v[214:217], v143 offset:1024
	ds_read_b128 v[218:221], v143 offset:2048
	ds_read_b128 v[222:225], v143 offset:3072
	ds_read_b128 v[226:229], v143 offset:4096
	ds_read_b128 v[230:233], v143 offset:5120
	ds_read_b128 v[234:237], v143 offset:6144
	ds_read_b128 v[238:241], v143 offset:7168
	global_load_lds_dwordx4 v[162:163], off
	v_lshl_add_u64 v[162:163], s[22:23], 0, v[138:139]
	s_add_i32 m0, s27, 0xe000
	s_nop 0
	global_load_lds_dwordx4 v[162:163], off
	s_waitcnt vmcnt(24)
	s_waitcnt lgkmcnt(0)
	s_barrier
	s_setprio 0
	s_waitcnt lgkmcnt(0)
	v_mfma_f32_16x16x32_bf16 v[126:129], v[144:147], v[210:213], v[126:129]
	v_mfma_f32_16x16x32_bf16 v[122:125], v[172:175], v[210:213], v[122:125]
	v_mfma_f32_16x16x32_bf16 v[118:121], v[144:147], v[218:221], v[118:121]
	v_mfma_f32_16x16x32_bf16 v[114:117], v[172:175], v[218:221], v[114:117]
	v_mfma_f32_16x16x32_bf16 v[110:113], v[144:147], v[226:229], v[110:113]
	v_mfma_f32_16x16x32_bf16 v[106:109], v[172:175], v[226:229], v[106:109]
	v_mfma_f32_16x16x32_bf16 v[102:105], v[144:147], v[234:237], v[102:105]
	v_mfma_f32_16x16x32_bf16 v[98:101], v[172:175], v[234:237], v[98:101]
	v_mfma_f32_16x16x32_bf16 v[126:129], v[148:151], v[214:217], v[126:129]
	v_mfma_f32_16x16x32_bf16 v[122:125], v[190:193], v[214:217], v[122:125]
	v_mfma_f32_16x16x32_bf16 v[118:121], v[148:151], v[222:225], v[118:121]
	v_mfma_f32_16x16x32_bf16 v[114:117], v[190:193], v[222:225], v[114:117]
	v_mfma_f32_16x16x32_bf16 v[110:113], v[148:151], v[230:233], v[110:113]
	v_mfma_f32_16x16x32_bf16 v[106:109], v[190:193], v[230:233], v[106:109]
	v_mfma_f32_16x16x32_bf16 v[102:105], v[148:151], v[238:241], v[102:105]
	v_mfma_f32_16x16x32_bf16 v[98:101], v[190:193], v[238:241], v[98:101]
	v_mfma_f32_16x16x32_bf16 v[66:69], v[194:197], v[210:213], v[66:69]
	v_mfma_f32_16x16x32_bf16 v[58:61], v[202:205], v[210:213], v[58:61]
	v_mfma_f32_16x16x32_bf16 v[54:57], v[194:197], v[218:221], v[54:57]
	v_mfma_f32_16x16x32_bf16 v[50:53], v[202:205], v[218:221], v[50:53]
	v_mfma_f32_16x16x32_bf16 v[46:49], v[194:197], v[226:229], v[46:49]
	v_mfma_f32_16x16x32_bf16 v[42:45], v[202:205], v[226:229], v[42:45]
	v_mfma_f32_16x16x32_bf16 v[38:41], v[194:197], v[234:237], v[38:41]
	v_mfma_f32_16x16x32_bf16 v[34:37], v[202:205], v[234:237], v[34:37]
	v_mfma_f32_16x16x32_bf16 v[66:69], v[198:201], v[214:217], v[66:69]
	v_mfma_f32_16x16x32_bf16 v[58:61], v[206:209], v[214:217], v[58:61]
	v_mfma_f32_16x16x32_bf16 v[54:57], v[198:201], v[222:225], v[54:57]
	v_mfma_f32_16x16x32_bf16 v[50:53], v[206:209], v[222:225], v[50:53]
	v_mfma_f32_16x16x32_bf16 v[46:49], v[198:201], v[230:233], v[46:49]
	v_mfma_f32_16x16x32_bf16 v[42:45], v[206:209], v[230:233], v[42:45]
	v_mfma_f32_16x16x32_bf16 v[38:41], v[198:201], v[238:241], v[38:41]
	v_mfma_f32_16x16x32_bf16 v[34:37], v[206:209], v[238:241], v[34:37]
	s_setprio 1
	s_barrier
	s_add_i32 s3, s3, s26
	v_lshl_add_u64 v[162:163], s[0:1], 0, v[4:5]
	s_mov_b32 m0, s3
	ds_read_b128 v[210:213], v143 offset:16384
	ds_read_b128 v[214:217], v143 offset:17408
	ds_read_b128 v[218:221], v143 offset:18432
	ds_read_b128 v[222:225], v143 offset:19456
	ds_read_b128 v[226:229], v143 offset:20480
	ds_read_b128 v[230:233], v143 offset:21504
	ds_read_b128 v[234:237], v143 offset:22528
	ds_read_b128 v[238:241], v143 offset:23552
	global_load_lds_dwordx4 v[162:163], off
	s_add_i32 m0, s3, 0x2000
	s_add_u32 s4, s0, 0x80000
	v_lshl_add_u64 v[166:167], s[0:1], 0, v[130:131]
	s_addc_u32 s5, s1, 0
	s_add_i32 s3, s6, s26
	global_load_lds_dwordx4 v[166:167], off
	v_lshl_add_u64 v[176:177], s[4:5], 0, v[4:5]
	s_mov_b32 m0, s3
	v_lshl_add_u64 v[242:243], s[14:15], 0, v[132:133]
	global_load_lds_dwordx4 v[176:177], off
	v_lshl_add_u64 v[176:177], s[4:5], 0, v[130:131]
	s_add_i32 m0, s3, 0x2000
	s_nop 0
	global_load_lds_dwordx4 v[176:177], off
	v_lshl_add_u64 v[176:177], s[14:15], 0, v[134:135]
	s_mov_b32 m0, s27
	s_nop 0
	global_load_lds_dwordx4 v[176:177], off
	s_mov_b32 m0, s30
	s_nop 0
	global_load_lds_dwordx4 v[242:243], off
	s_waitcnt vmcnt(24)
	s_waitcnt lgkmcnt(0)
	s_barrier
	s_setprio 0
	s_waitcnt lgkmcnt(0)
	v_mfma_f32_16x16x32_bf16 v[94:97], v[144:147], v[210:213], v[94:97]
	v_mfma_f32_16x16x32_bf16 v[90:93], v[172:175], v[210:213], v[90:93]
	v_mfma_f32_16x16x32_bf16 v[86:89], v[144:147], v[218:221], v[86:89]
	v_mfma_f32_16x16x32_bf16 v[82:85], v[172:175], v[218:221], v[82:85]
	v_mfma_f32_16x16x32_bf16 v[78:81], v[144:147], v[226:229], v[78:81]
	v_mfma_f32_16x16x32_bf16 v[74:77], v[172:175], v[226:229], v[74:77]
	v_mfma_f32_16x16x32_bf16 v[70:73], v[144:147], v[234:237], v[70:73]
	v_mfma_f32_16x16x32_bf16 v[62:65], v[172:175], v[234:237], v[62:65]
	v_mfma_f32_16x16x32_bf16 v[94:97], v[148:151], v[214:217], v[94:97]
	v_mfma_f32_16x16x32_bf16 v[90:93], v[190:193], v[214:217], v[90:93]
	v_mfma_f32_16x16x32_bf16 v[86:89], v[148:151], v[222:225], v[86:89]
	v_mfma_f32_16x16x32_bf16 v[82:85], v[190:193], v[222:225], v[82:85]
	v_mfma_f32_16x16x32_bf16 v[78:81], v[148:151], v[230:233], v[78:81]
	v_mfma_f32_16x16x32_bf16 v[74:77], v[190:193], v[230:233], v[74:77]
	v_mfma_f32_16x16x32_bf16 v[70:73], v[148:151], v[238:241], v[70:73]
	v_mfma_f32_16x16x32_bf16 v[62:65], v[190:193], v[238:241], v[62:65]
	v_mfma_f32_16x16x32_bf16 v[30:33], v[194:197], v[210:213], v[30:33]
	v_mfma_f32_16x16x32_bf16 v[26:29], v[202:205], v[210:213], v[26:29]
	v_mfma_f32_16x16x32_bf16 v[22:25], v[194:197], v[218:221], v[22:25]
	v_mfma_f32_16x16x32_bf16 v[18:21], v[202:205], v[218:221], v[18:21]
	v_mfma_f32_16x16x32_bf16 v[14:17], v[194:197], v[226:229], v[14:17]
	v_mfma_f32_16x16x32_bf16 v[10:13], v[202:205], v[226:229], v[10:13]
	v_mfma_f32_16x16x32_bf16 v[6:9], v[194:197], v[234:237], v[6:9]
	v_mfma_f32_16x16x32_bf16 v[0:3], v[202:205], v[234:237], v[0:3]
	v_mfma_f32_16x16x32_bf16 v[30:33], v[198:201], v[214:217], v[30:33]
	v_mfma_f32_16x16x32_bf16 v[26:29], v[206:209], v[214:217], v[26:29]
	v_mfma_f32_16x16x32_bf16 v[22:25], v[198:201], v[222:225], v[22:25]
	v_mfma_f32_16x16x32_bf16 v[18:21], v[206:209], v[222:225], v[18:21]
	v_mfma_f32_16x16x32_bf16 v[14:17], v[198:201], v[230:233], v[14:17]
	v_mfma_f32_16x16x32_bf16 v[10:13], v[206:209], v[230:233], v[10:13]
	v_mfma_f32_16x16x32_bf16 v[6:9], v[198:201], v[238:241], v[6:9]
	v_mfma_f32_16x16x32_bf16 v[0:3], v[206:209], v[238:241], v[0:3]
	s_setprio 1
	s_barrier
	s_branch .Lpeelmid_252
.LBB0_252:
	s_add_u32 s0, s22, 0xfff80080
	s_addc_u32 s1, s23, -1
	s_add_i32 s3, 0, 0x10000
	s_cmp_eq_u32 s24, 28
	s_cselect_b32 s15, s49, s1
	s_cselect_b32 s14, s48, s0
	v_add_u32_e32 v162, s3, v141
	s_cselect_b32 s1, s2, s10
	s_cselect_b32 s0, s8, s9
	s_add_i32 s6, 0, 0x14000
	ds_read_b128 v[144:147], v162
	ds_read_b128 v[148:151], v162 offset:1024
	ds_read_b128 v[172:175], v162 offset:2048
	ds_read_b128 v[190:193], v162 offset:3072
	v_add_u32_e32 v162, s6, v141
	ds_read_b128 v[194:197], v162
	ds_read_b128 v[198:201], v162 offset:1024
	ds_read_b128 v[202:205], v162 offset:2048
	ds_read_b128 v[206:209], v162 offset:3072
	v_lshl_add_u64 v[162:163], s[22:23], 0, v[136:137]
	s_add_i32 m0, s27, 0xc000
	ds_read_b128 v[210:213], v143
	ds_read_b128 v[214:217], v143 offset:1024
	ds_read_b128 v[218:221], v143 offset:2048
	ds_read_b128 v[222:225], v143 offset:3072
	ds_read_b128 v[226:229], v143 offset:4096
	ds_read_b128 v[230:233], v143 offset:5120
	ds_read_b128 v[234:237], v143 offset:6144
	ds_read_b128 v[238:241], v143 offset:7168
	global_load_lds_dwordx4 v[162:163], off
	v_lshl_add_u64 v[162:163], s[22:23], 0, v[138:139]
	s_add_i32 m0, s27, 0xe000
	s_nop 0
	global_load_lds_dwordx4 v[162:163], off
	s_waitcnt vmcnt(8)
	s_waitcnt lgkmcnt(0)
	s_barrier
	s_setprio 0
	s_waitcnt lgkmcnt(0)
	v_mfma_f32_16x16x32_bf16 v[126:129], v[144:147], v[210:213], v[126:129]
	v_mfma_f32_16x16x32_bf16 v[122:125], v[172:175], v[210:213], v[122:125]
	v_mfma_f32_16x16x32_bf16 v[118:121], v[144:147], v[218:221], v[118:121]
	v_mfma_f32_16x16x32_bf16 v[114:117], v[172:175], v[218:221], v[114:117]
	v_mfma_f32_16x16x32_bf16 v[110:113], v[144:147], v[226:229], v[110:113]
	v_mfma_f32_16x16x32_bf16 v[106:109], v[172:175], v[226:229], v[106:109]
	v_mfma_f32_16x16x32_bf16 v[102:105], v[144:147], v[234:237], v[102:105]
	v_mfma_f32_16x16x32_bf16 v[98:101], v[172:175], v[234:237], v[98:101]
	v_mfma_f32_16x16x32_bf16 v[126:129], v[148:151], v[214:217], v[126:129]
	v_mfma_f32_16x16x32_bf16 v[122:125], v[190:193], v[214:217], v[122:125]
	v_mfma_f32_16x16x32_bf16 v[118:121], v[148:151], v[222:225], v[118:121]
	v_mfma_f32_16x16x32_bf16 v[114:117], v[190:193], v[222:225], v[114:117]
	v_mfma_f32_16x16x32_bf16 v[110:113], v[148:151], v[230:233], v[110:113]
	v_mfma_f32_16x16x32_bf16 v[106:109], v[190:193], v[230:233], v[106:109]
	v_mfma_f32_16x16x32_bf16 v[102:105], v[148:151], v[238:241], v[102:105]
	v_mfma_f32_16x16x32_bf16 v[98:101], v[190:193], v[238:241], v[98:101]
	v_mfma_f32_16x16x32_bf16 v[66:69], v[194:197], v[210:213], v[66:69]
	v_mfma_f32_16x16x32_bf16 v[58:61], v[202:205], v[210:213], v[58:61]
	v_mfma_f32_16x16x32_bf16 v[54:57], v[194:197], v[218:221], v[54:57]
	v_mfma_f32_16x16x32_bf16 v[50:53], v[202:205], v[218:221], v[50:53]
	v_mfma_f32_16x16x32_bf16 v[46:49], v[194:197], v[226:229], v[46:49]
	v_mfma_f32_16x16x32_bf16 v[42:45], v[202:205], v[226:229], v[42:45]
	v_mfma_f32_16x16x32_bf16 v[38:41], v[194:197], v[234:237], v[38:41]
	v_mfma_f32_16x16x32_bf16 v[34:37], v[202:205], v[234:237], v[34:37]
	v_mfma_f32_16x16x32_bf16 v[66:69], v[198:201], v[214:217], v[66:69]
	v_mfma_f32_16x16x32_bf16 v[58:61], v[206:209], v[214:217], v[58:61]
	v_mfma_f32_16x16x32_bf16 v[54:57], v[198:201], v[222:225], v[54:57]
	v_mfma_f32_16x16x32_bf16 v[50:53], v[206:209], v[222:225], v[50:53]
	v_mfma_f32_16x16x32_bf16 v[46:49], v[198:201], v[230:233], v[46:49]
	v_mfma_f32_16x16x32_bf16 v[42:45], v[206:209], v[230:233], v[42:45]
	v_mfma_f32_16x16x32_bf16 v[38:41], v[198:201], v[238:241], v[38:41]
	v_mfma_f32_16x16x32_bf16 v[34:37], v[206:209], v[238:241], v[34:37]
	s_setprio 1
	s_barrier
	s_add_i32 s3, s3, s26
	v_lshl_add_u64 v[162:163], s[0:1], 0, v[4:5]
	s_mov_b32 m0, s3
	ds_read_b128 v[210:213], v143 offset:16384
	ds_read_b128 v[214:217], v143 offset:17408
	ds_read_b128 v[218:221], v143 offset:18432
	ds_read_b128 v[222:225], v143 offset:19456
	ds_read_b128 v[226:229], v143 offset:20480
	ds_read_b128 v[230:233], v143 offset:21504
	ds_read_b128 v[234:237], v143 offset:22528
	ds_read_b128 v[238:241], v143 offset:23552
	global_load_lds_dwordx4 v[162:163], off
	s_add_i32 m0, s3, 0x2000
	s_add_u32 s4, s0, 0x80000
	v_lshl_add_u64 v[166:167], s[0:1], 0, v[130:131]
	s_addc_u32 s5, s1, 0
	s_add_i32 s3, s6, s26
	global_load_lds_dwordx4 v[166:167], off
	v_lshl_add_u64 v[176:177], s[4:5], 0, v[4:5]
	s_mov_b32 m0, s3
	v_lshl_add_u64 v[242:243], s[14:15], 0, v[132:133]
	global_load_lds_dwordx4 v[176:177], off
	v_lshl_add_u64 v[176:177], s[4:5], 0, v[130:131]
	s_add_i32 m0, s3, 0x2000
	s_nop 0
	global_load_lds_dwordx4 v[176:177], off
	v_lshl_add_u64 v[176:177], s[14:15], 0, v[134:135]
	s_mov_b32 m0, s27
	s_nop 0
	global_load_lds_dwordx4 v[176:177], off
	s_mov_b32 m0, s30
	s_nop 0
	global_load_lds_dwordx4 v[242:243], off
	s_waitcnt vmcnt(8)
	s_waitcnt lgkmcnt(0)
	s_barrier
	s_setprio 0
	s_waitcnt lgkmcnt(0)
	v_mfma_f32_16x16x32_bf16 v[94:97], v[144:147], v[210:213], v[94:97]
	v_mfma_f32_16x16x32_bf16 v[90:93], v[172:175], v[210:213], v[90:93]
	v_mfma_f32_16x16x32_bf16 v[86:89], v[144:147], v[218:221], v[86:89]
	v_mfma_f32_16x16x32_bf16 v[82:85], v[172:175], v[218:221], v[82:85]
	v_mfma_f32_16x16x32_bf16 v[78:81], v[144:147], v[226:229], v[78:81]
	v_mfma_f32_16x16x32_bf16 v[74:77], v[172:175], v[226:229], v[74:77]
	v_mfma_f32_16x16x32_bf16 v[70:73], v[144:147], v[234:237], v[70:73]
	v_mfma_f32_16x16x32_bf16 v[62:65], v[172:175], v[234:237], v[62:65]
	v_mfma_f32_16x16x32_bf16 v[94:97], v[148:151], v[214:217], v[94:97]
	v_mfma_f32_16x16x32_bf16 v[90:93], v[190:193], v[214:217], v[90:93]
	v_mfma_f32_16x16x32_bf16 v[86:89], v[148:151], v[222:225], v[86:89]
	v_mfma_f32_16x16x32_bf16 v[82:85], v[190:193], v[222:225], v[82:85]
	v_mfma_f32_16x16x32_bf16 v[78:81], v[148:151], v[230:233], v[78:81]
	v_mfma_f32_16x16x32_bf16 v[74:77], v[190:193], v[230:233], v[74:77]
	v_mfma_f32_16x16x32_bf16 v[70:73], v[148:151], v[238:241], v[70:73]
	v_mfma_f32_16x16x32_bf16 v[62:65], v[190:193], v[238:241], v[62:65]
	v_mfma_f32_16x16x32_bf16 v[30:33], v[194:197], v[210:213], v[30:33]
	v_mfma_f32_16x16x32_bf16 v[26:29], v[202:205], v[210:213], v[26:29]
	v_mfma_f32_16x16x32_bf16 v[22:25], v[194:197], v[218:221], v[22:25]
	v_mfma_f32_16x16x32_bf16 v[18:21], v[202:205], v[218:221], v[18:21]
	v_mfma_f32_16x16x32_bf16 v[14:17], v[194:197], v[226:229], v[14:17]
	v_mfma_f32_16x16x32_bf16 v[10:13], v[202:205], v[226:229], v[10:13]
	v_mfma_f32_16x16x32_bf16 v[6:9], v[194:197], v[234:237], v[6:9]
	v_mfma_f32_16x16x32_bf16 v[0:3], v[202:205], v[234:237], v[0:3]
	v_mfma_f32_16x16x32_bf16 v[30:33], v[198:201], v[214:217], v[30:33]
	v_mfma_f32_16x16x32_bf16 v[26:29], v[206:209], v[214:217], v[26:29]
	v_mfma_f32_16x16x32_bf16 v[22:25], v[198:201], v[222:225], v[22:25]
	v_mfma_f32_16x16x32_bf16 v[18:21], v[206:209], v[222:225], v[18:21]
	v_mfma_f32_16x16x32_bf16 v[14:17], v[198:201], v[230:233], v[14:17]
	v_mfma_f32_16x16x32_bf16 v[10:13], v[206:209], v[230:233], v[10:13]
	v_mfma_f32_16x16x32_bf16 v[6:9], v[198:201], v[238:241], v[6:9]
	v_mfma_f32_16x16x32_bf16 v[0:3], v[206:209], v[238:241], v[0:3]
	s_setprio 1
	s_barrier
.Lpeelmid_252:
	s_add_i32 s3, 0, 0x18000
	v_add_u32_e32 v164, s3, v141
	s_add_i32 s6, 0, 0x1c000
	ds_read_b128 v[144:147], v164
	ds_read_b128 v[148:151], v164 offset:1024
	ds_read_b128 v[172:175], v164 offset:2048
	ds_read_b128 v[190:193], v164 offset:3072
	v_add_u32_e32 v164, s6, v141
	ds_read_b128 v[194:197], v164
	ds_read_b128 v[198:201], v164 offset:1024
	ds_read_b128 v[202:205], v164 offset:2048
	ds_read_b128 v[206:209], v164 offset:3072
	s_add_u32 s4, s14, 0x80000
	s_addc_u32 s5, s15, 0
	s_mov_b32 m0, s31
	v_lshl_add_u64 v[244:245], s[4:5], 0, v[134:135]
	ds_read_b128 v[210:213], v143 offset:32768
	ds_read_b128 v[214:217], v143 offset:33792
	ds_read_b128 v[218:221], v143 offset:34816
	ds_read_b128 v[222:225], v143 offset:35840
	ds_read_b128 v[226:229], v143 offset:36864
	ds_read_b128 v[230:233], v143 offset:37888
	ds_read_b128 v[234:237], v143 offset:38912
	ds_read_b128 v[238:241], v143 offset:39936
	global_load_lds_dwordx4 v[244:245], off
	v_lshl_add_u64 v[244:245], s[4:5], 0, v[132:133]
	s_mov_b32 m0, s34
	s_nop 0
	global_load_lds_dwordx4 v[244:245], off
	s_waitcnt vmcnt(8)
	s_waitcnt lgkmcnt(0)
	s_barrier
	s_setprio 0
	s_waitcnt lgkmcnt(0)
	v_mfma_f32_16x16x32_bf16 v[126:129], v[144:147], v[210:213], v[126:129]
	v_mfma_f32_16x16x32_bf16 v[122:125], v[172:175], v[210:213], v[122:125]
	v_mfma_f32_16x16x32_bf16 v[118:121], v[144:147], v[218:221], v[118:121]
	v_mfma_f32_16x16x32_bf16 v[114:117], v[172:175], v[218:221], v[114:117]
	v_mfma_f32_16x16x32_bf16 v[110:113], v[144:147], v[226:229], v[110:113]
	v_mfma_f32_16x16x32_bf16 v[106:109], v[172:175], v[226:229], v[106:109]
	v_mfma_f32_16x16x32_bf16 v[102:105], v[144:147], v[234:237], v[102:105]
	v_mfma_f32_16x16x32_bf16 v[98:101], v[172:175], v[234:237], v[98:101]
	v_mfma_f32_16x16x32_bf16 v[126:129], v[148:151], v[214:217], v[126:129]
	v_mfma_f32_16x16x32_bf16 v[122:125], v[190:193], v[214:217], v[122:125]
	v_mfma_f32_16x16x32_bf16 v[118:121], v[148:151], v[222:225], v[118:121]
	v_mfma_f32_16x16x32_bf16 v[114:117], v[190:193], v[222:225], v[114:117]
	v_mfma_f32_16x16x32_bf16 v[110:113], v[148:151], v[230:233], v[110:113]
	v_mfma_f32_16x16x32_bf16 v[106:109], v[190:193], v[230:233], v[106:109]
	v_mfma_f32_16x16x32_bf16 v[102:105], v[148:151], v[238:241], v[102:105]
	v_mfma_f32_16x16x32_bf16 v[98:101], v[190:193], v[238:241], v[98:101]
	v_mfma_f32_16x16x32_bf16 v[66:69], v[194:197], v[210:213], v[66:69]
	v_mfma_f32_16x16x32_bf16 v[58:61], v[202:205], v[210:213], v[58:61]
	v_mfma_f32_16x16x32_bf16 v[54:57], v[194:197], v[218:221], v[54:57]
	v_mfma_f32_16x16x32_bf16 v[50:53], v[202:205], v[218:221], v[50:53]
	v_mfma_f32_16x16x32_bf16 v[46:49], v[194:197], v[226:229], v[46:49]
	v_mfma_f32_16x16x32_bf16 v[42:45], v[202:205], v[226:229], v[42:45]
	v_mfma_f32_16x16x32_bf16 v[38:41], v[194:197], v[234:237], v[38:41]
	v_mfma_f32_16x16x32_bf16 v[34:37], v[202:205], v[234:237], v[34:37]
	v_mfma_f32_16x16x32_bf16 v[66:69], v[198:201], v[214:217], v[66:69]
	v_mfma_f32_16x16x32_bf16 v[58:61], v[206:209], v[214:217], v[58:61]
	v_mfma_f32_16x16x32_bf16 v[54:57], v[198:201], v[222:225], v[54:57]
	v_mfma_f32_16x16x32_bf16 v[50:53], v[206:209], v[222:225], v[50:53]
	v_mfma_f32_16x16x32_bf16 v[46:49], v[198:201], v[230:233], v[46:49]
	v_mfma_f32_16x16x32_bf16 v[42:45], v[206:209], v[230:233], v[42:45]
	v_mfma_f32_16x16x32_bf16 v[38:41], v[198:201], v[238:241], v[38:41]
	v_mfma_f32_16x16x32_bf16 v[34:37], v[206:209], v[238:241], v[34:37]
	s_setprio 1
	s_barrier
	s_add_i32 s3, s3, s26
	v_lshl_add_u64 v[162:163], v[162:163], 0, s[70:71]
	s_mov_b32 m0, s3
	ds_read_b128 v[210:213], v143 offset:49152
	ds_read_b128 v[214:217], v143 offset:50176
	ds_read_b128 v[218:221], v143 offset:51200
	ds_read_b128 v[222:225], v143 offset:52224
	ds_read_b128 v[226:229], v143 offset:53248
	ds_read_b128 v[230:233], v143 offset:54272
	ds_read_b128 v[234:237], v143 offset:55296
	ds_read_b128 v[238:241], v143 offset:56320
	global_load_lds_dwordx4 v[162:163], off
	s_add_i32 m0, s3, 0x2000
	s_add_u32 s0, s0, 0x80080
	v_lshl_add_u64 v[162:163], v[166:167], 0, s[70:71]
	s_addc_u32 s1, s1, 0
	s_add_i32 s3, s6, s26
	global_load_lds_dwordx4 v[162:163], off
	v_lshl_add_u64 v[162:163], s[0:1], 0, v[4:5]
	s_mov_b32 m0, s3
	s_nop 0
	global_load_lds_dwordx4 v[162:163], off
	v_lshl_add_u64 v[162:163], s[0:1], 0, v[130:131]
	s_add_i32 m0, s3, 0x2000
	s_nop 0
	global_load_lds_dwordx4 v[162:163], off
	v_lshl_add_u64 v[162:163], v[176:177], 0, s[70:71]
	s_mov_b32 m0, s35
	s_nop 0
	global_load_lds_dwordx4 v[162:163], off
	v_lshl_add_u64 v[162:163], v[242:243], 0, s[70:71]
	s_mov_b32 m0, s36
	s_nop 0
	global_load_lds_dwordx4 v[162:163], off
	s_waitcnt vmcnt(8)
	s_waitcnt lgkmcnt(0)
	s_barrier
	s_setprio 0
	s_waitcnt lgkmcnt(0)
	v_mfma_f32_16x16x32_bf16 v[94:97], v[144:147], v[210:213], v[94:97]
	v_mfma_f32_16x16x32_bf16 v[90:93], v[172:175], v[210:213], v[90:93]
	v_mfma_f32_16x16x32_bf16 v[86:89], v[144:147], v[218:221], v[86:89]
	v_mfma_f32_16x16x32_bf16 v[82:85], v[172:175], v[218:221], v[82:85]
	v_mfma_f32_16x16x32_bf16 v[78:81], v[144:147], v[226:229], v[78:81]
	v_mfma_f32_16x16x32_bf16 v[74:77], v[172:175], v[226:229], v[74:77]
	v_mfma_f32_16x16x32_bf16 v[70:73], v[144:147], v[234:237], v[70:73]
	v_mfma_f32_16x16x32_bf16 v[62:65], v[172:175], v[234:237], v[62:65]
	v_mfma_f32_16x16x32_bf16 v[94:97], v[148:151], v[214:217], v[94:97]
	v_mfma_f32_16x16x32_bf16 v[90:93], v[190:193], v[214:217], v[90:93]
	v_mfma_f32_16x16x32_bf16 v[86:89], v[148:151], v[222:225], v[86:89]
	v_mfma_f32_16x16x32_bf16 v[82:85], v[190:193], v[222:225], v[82:85]
	v_mfma_f32_16x16x32_bf16 v[78:81], v[148:151], v[230:233], v[78:81]
	v_mfma_f32_16x16x32_bf16 v[74:77], v[190:193], v[230:233], v[74:77]
	v_mfma_f32_16x16x32_bf16 v[70:73], v[148:151], v[238:241], v[70:73]
	v_mfma_f32_16x16x32_bf16 v[62:65], v[190:193], v[238:241], v[62:65]
	v_mfma_f32_16x16x32_bf16 v[30:33], v[194:197], v[210:213], v[30:33]
	v_mfma_f32_16x16x32_bf16 v[26:29], v[202:205], v[210:213], v[26:29]
	v_mfma_f32_16x16x32_bf16 v[22:25], v[194:197], v[218:221], v[22:25]
	v_mfma_f32_16x16x32_bf16 v[18:21], v[202:205], v[218:221], v[18:21]
	v_mfma_f32_16x16x32_bf16 v[14:17], v[194:197], v[226:229], v[14:17]
	v_mfma_f32_16x16x32_bf16 v[10:13], v[202:205], v[226:229], v[10:13]
	v_mfma_f32_16x16x32_bf16 v[6:9], v[194:197], v[234:237], v[6:9]
	v_mfma_f32_16x16x32_bf16 v[0:3], v[202:205], v[234:237], v[0:3]
	v_mfma_f32_16x16x32_bf16 v[30:33], v[198:201], v[214:217], v[30:33]
	v_mfma_f32_16x16x32_bf16 v[26:29], v[206:209], v[214:217], v[26:29]
	v_mfma_f32_16x16x32_bf16 v[22:25], v[198:201], v[222:225], v[22:25]
	v_mfma_f32_16x16x32_bf16 v[18:21], v[206:209], v[222:225], v[18:21]
	v_mfma_f32_16x16x32_bf16 v[14:17], v[198:201], v[230:233], v[14:17]
	v_mfma_f32_16x16x32_bf16 v[10:13], v[206:209], v[230:233], v[10:13]
	v_mfma_f32_16x16x32_bf16 v[6:9], v[198:201], v[238:241], v[6:9]
	v_mfma_f32_16x16x32_bf16 v[0:3], v[206:209], v[238:241], v[0:3]
	s_setprio 1
	s_barrier
	s_add_i32 s24, s24, 2
	s_add_u32 s22, s22, 0x100
	s_addc_u32 s23, s23, 0
	s_add_u32 s9, s9, 0x100
	s_addc_u32 s10, s10, 0
	s_cmp_gt_u32 s24, 29
	s_cbranch_scc0 .LBB0_252
	s_and_b64 vcc, exec, s[44:45]
	s_cbranch_vccz .LBB0_255
	s_barrier

.LBB0_851:
	s_ashr_i32 s3, s37, 24
	s_lshl_b32 s2, s37, 8
	s_andn2_b32 s3, s3, 63
	s_add_i32 s2, s3, s2
	s_ashr_i32 s3, s2, 31
	s_lshl_b64 s[2:3], s[2:3], 12
	v_readlane_b32 s4, v252, 6
	v_readlane_b32 s5, v252, 7
	s_add_u32 s76, s4, s2
	s_addc_u32 s77, s5, s3
	s_and_b64 s[2:3], s[38:39], exec
	s_cselect_b32 s2, s77, s15
	s_cselect_b32 s8, s76, s14
	s_ashr_i32 s59, s58, 31
	s_lshl_b64 s[4:5], s[58:59], 20
	v_readlane_b32 s6, v252, 4
	v_readlane_b32 s7, v252, 5
	s_add_u32 s78, s6, s4
	s_addc_u32 s79, s7, s5
	s_and_b64 s[4:5], s[38:39], exec
	s_cselect_b32 s10, s79, s1
	s_cselect_b32 s24, s78, s0
	s_add_u32 s22, s14, 0x80080
	s_addc_u32 s23, s15, 0
	s_add_u32 s9, s0, 0x100
	v_mov_b32_e32 v0, 0
	s_addc_u32 s25, s1, 0
	s_mov_b32 s28, -2
	v_mov_b32_e32 v1, v0
	v_mov_b32_e32 v2, v0
	v_mov_b32_e32 v3, v0
	v_mov_b32_e32 v6, v0
	v_mov_b32_e32 v7, v0
	v_mov_b32_e32 v8, v0
	v_mov_b32_e32 v9, v0
	v_mov_b32_e32 v10, v0
	v_mov_b32_e32 v11, v0
	v_mov_b32_e32 v12, v0
	v_mov_b32_e32 v13, v0
	v_mov_b32_e32 v14, v0
	v_mov_b32_e32 v15, v0
	v_mov_b32_e32 v16, v0
	v_mov_b32_e32 v17, v0
	v_mov_b32_e32 v18, v0
	v_mov_b32_e32 v19, v0
	v_mov_b32_e32 v20, v0
	v_mov_b32_e32 v21, v0
	v_mov_b32_e32 v22, v0
	v_mov_b32_e32 v23, v0
	v_mov_b32_e32 v24, v0
	v_mov_b32_e32 v25, v0
	v_mov_b32_e32 v26, v0
	v_mov_b32_e32 v27, v0
	v_mov_b32_e32 v28, v0
	v_mov_b32_e32 v29, v0
	v_mov_b32_e32 v30, v0
	v_mov_b32_e32 v31, v0
	v_mov_b32_e32 v32, v0
	v_mov_b32_e32 v33, v0
	v_mov_b32_e32 v66, v0
	v_mov_b32_e32 v67, v0
	v_mov_b32_e32 v68, v0
	v_mov_b32_e32 v69, v0
	v_mov_b32_e32 v70, v0
	v_mov_b32_e32 v71, v0
	v_mov_b32_e32 v72, v0
	v_mov_b32_e32 v73, v0
	v_mov_b32_e32 v74, v0
	v_mov_b32_e32 v75, v0
	v_mov_b32_e32 v76, v0
	v_mov_b32_e32 v77, v0
	v_mov_b32_e32 v78, v0
	v_mov_b32_e32 v79, v0
	v_mov_b32_e32 v80, v0
	v_mov_b32_e32 v81, v0
	v_mov_b32_e32 v82, v0
	v_mov_b32_e32 v83, v0
	v_mov_b32_e32 v84, v0
	v_mov_b32_e32 v85, v0
	v_mov_b32_e32 v86, v0
	v_mov_b32_e32 v87, v0
	v_mov_b32_e32 v88, v0
	v_mov_b32_e32 v89, v0
	v_mov_b32_e32 v90, v0
	v_mov_b32_e32 v91, v0
	v_mov_b32_e32 v92, v0
	v_mov_b32_e32 v93, v0
	v_mov_b32_e32 v94, v0
	v_mov_b32_e32 v95, v0
	v_mov_b32_e32 v96, v0
	v_mov_b32_e32 v97, v0
	v_mov_b32_e32 v34, v0
	v_mov_b32_e32 v35, v0
	v_mov_b32_e32 v36, v0
	v_mov_b32_e32 v37, v0
	v_mov_b32_e32 v38, v0
	v_mov_b32_e32 v39, v0
	v_mov_b32_e32 v40, v0
	v_mov_b32_e32 v41, v0
	v_mov_b32_e32 v42, v0
	v_mov_b32_e32 v43, v0
	v_mov_b32_e32 v44, v0
	v_mov_b32_e32 v45, v0
	v_mov_b32_e32 v46, v0
	v_mov_b32_e32 v47, v0
	v_mov_b32_e32 v48, v0
	v_mov_b32_e32 v49, v0
	v_mov_b32_e32 v50, v0
	v_mov_b32_e32 v51, v0
	v_mov_b32_e32 v52, v0
	v_mov_b32_e32 v53, v0
	v_mov_b32_e32 v54, v0
	v_mov_b32_e32 v55, v0
	v_mov_b32_e32 v56, v0
	v_mov_b32_e32 v57, v0
	v_mov_b32_e32 v58, v0
	v_mov_b32_e32 v59, v0
	v_mov_b32_e32 v60, v0
	v_mov_b32_e32 v61, v0
	v_mov_b32_e32 v62, v0
	v_mov_b32_e32 v63, v0
	v_mov_b32_e32 v64, v0
	v_mov_b32_e32 v65, v0
	v_mov_b32_e32 v98, v0
	v_mov_b32_e32 v99, v0
	v_mov_b32_e32 v100, v0
	v_mov_b32_e32 v101, v0
	v_mov_b32_e32 v102, v0
	v_mov_b32_e32 v103, v0
	v_mov_b32_e32 v104, v0
	v_mov_b32_e32 v105, v0
	v_mov_b32_e32 v106, v0
	v_mov_b32_e32 v107, v0
	v_mov_b32_e32 v108, v0
	v_mov_b32_e32 v109, v0
	v_mov_b32_e32 v110, v0
	v_mov_b32_e32 v111, v0
	v_mov_b32_e32 v112, v0
	v_mov_b32_e32 v113, v0
	v_mov_b32_e32 v114, v0
	v_mov_b32_e32 v115, v0
	v_mov_b32_e32 v116, v0
	v_mov_b32_e32 v117, v0
	v_mov_b32_e32 v118, v0
	v_mov_b32_e32 v119, v0
	v_mov_b32_e32 v120, v0
	v_mov_b32_e32 v121, v0
	v_mov_b32_e32 v122, v0
	v_mov_b32_e32 v123, v0
	v_mov_b32_e32 v124, v0
	v_mov_b32_e32 v125, v0
	v_mov_b32_e32 v126, v0
	v_mov_b32_e32 v127, v0
	v_mov_b32_e32 v128, v0
	v_mov_b32_e32 v129, v0
	s_cmp_eq_u32 s36, 1
	s_cbranch_scc1 .LBB0_852
	s_add_u32 s0, s22, 0xfff80080
	s_addc_u32 s1, s23, -1
	s_add_i32 s3, 0, 0x10000
	s_cmp_eq_u32 s28, 28
	s_cselect_b32 s15, s2, s1
	s_cselect_b32 s14, s8, s0
	v_add_u32_e32 v167, s3, v163
	s_cselect_b32 s1, s10, s25
	s_cselect_b32 s0, s24, s9
	s_add_i32 s6, 0, 0x14000
	ds_read_b128 v[140:143], v167
	ds_read_b128 v[144:147], v167 offset:1024
	ds_read_b128 v[148:151], v167 offset:2048
	ds_read_b128 v[172:175], v167 offset:3072
	v_add_u32_e32 v167, s6, v163
	ds_read_b128 v[190:193], v167
	ds_read_b128 v[194:197], v167 offset:1024
	ds_read_b128 v[198:201], v167 offset:2048
	ds_read_b128 v[202:205], v167 offset:3072
	v_lshl_add_u64 v[176:177], s[22:23], 0, v[136:137]
	s_add_i32 m0, s26, 0xc000
	ds_read_b128 v[206:209], v166
	ds_read_b128 v[210:213], v166 offset:1024
	ds_read_b128 v[214:217], v166 offset:2048
	ds_read_b128 v[218:221], v166 offset:3072
	ds_read_b128 v[222:225], v166 offset:4096
	ds_read_b128 v[226:229], v166 offset:5120
	ds_read_b128 v[230:233], v166 offset:6144
	ds_read_b128 v[234:237], v166 offset:7168
	global_load_lds_dwordx4 v[176:177], off
	v_lshl_add_u64 v[176:177], s[22:23], 0, v[138:139]
	s_add_i32 m0, s26, 0xe000
	s_nop 0
	global_load_lds_dwordx4 v[176:177], off
	s_waitcnt vmcnt(24)
	s_waitcnt lgkmcnt(0)
	s_barrier
	s_setprio 0
	s_waitcnt lgkmcnt(0)
	v_mfma_f32_16x16x32_bf16 v[126:129], v[140:143], v[206:209], v[126:129]
	v_mfma_f32_16x16x32_bf16 v[122:125], v[148:151], v[206:209], v[122:125]
	v_mfma_f32_16x16x32_bf16 v[118:121], v[140:143], v[214:217], v[118:121]
	v_mfma_f32_16x16x32_bf16 v[114:117], v[148:151], v[214:217], v[114:117]
	v_mfma_f32_16x16x32_bf16 v[110:113], v[140:143], v[222:225], v[110:113]
	v_mfma_f32_16x16x32_bf16 v[106:109], v[148:151], v[222:225], v[106:109]
	v_mfma_f32_16x16x32_bf16 v[102:105], v[140:143], v[230:233], v[102:105]
	v_mfma_f32_16x16x32_bf16 v[98:101], v[148:151], v[230:233], v[98:101]
	v_mfma_f32_16x16x32_bf16 v[126:129], v[144:147], v[210:213], v[126:129]
	v_mfma_f32_16x16x32_bf16 v[122:125], v[172:175], v[210:213], v[122:125]
	v_mfma_f32_16x16x32_bf16 v[118:121], v[144:147], v[218:221], v[118:121]
	v_mfma_f32_16x16x32_bf16 v[114:117], v[172:175], v[218:221], v[114:117]
	v_mfma_f32_16x16x32_bf16 v[110:113], v[144:147], v[226:229], v[110:113]
	v_mfma_f32_16x16x32_bf16 v[106:109], v[172:175], v[226:229], v[106:109]
	v_mfma_f32_16x16x32_bf16 v[102:105], v[144:147], v[234:237], v[102:105]
	v_mfma_f32_16x16x32_bf16 v[98:101], v[172:175], v[234:237], v[98:101]
	v_mfma_f32_16x16x32_bf16 v[62:65], v[190:193], v[206:209], v[62:65]
	v_mfma_f32_16x16x32_bf16 v[58:61], v[198:201], v[206:209], v[58:61]
	v_mfma_f32_16x16x32_bf16 v[54:57], v[190:193], v[214:217], v[54:57]
	v_mfma_f32_16x16x32_bf16 v[50:53], v[198:201], v[214:217], v[50:53]
	v_mfma_f32_16x16x32_bf16 v[46:49], v[190:193], v[222:225], v[46:49]
	v_mfma_f32_16x16x32_bf16 v[42:45], v[198:201], v[222:225], v[42:45]
	v_mfma_f32_16x16x32_bf16 v[38:41], v[190:193], v[230:233], v[38:41]
	v_mfma_f32_16x16x32_bf16 v[34:37], v[198:201], v[230:233], v[34:37]
	v_mfma_f32_16x16x32_bf16 v[62:65], v[194:197], v[210:213], v[62:65]
	v_mfma_f32_16x16x32_bf16 v[58:61], v[202:205], v[210:213], v[58:61]
	v_mfma_f32_16x16x32_bf16 v[54:57], v[194:197], v[218:221], v[54:57]
	v_mfma_f32_16x16x32_bf16 v[50:53], v[202:205], v[218:221], v[50:53]
	v_mfma_f32_16x16x32_bf16 v[46:49], v[194:197], v[226:229], v[46:49]
	v_mfma_f32_16x16x32_bf16 v[42:45], v[202:205], v[226:229], v[42:45]
	v_mfma_f32_16x16x32_bf16 v[38:41], v[194:197], v[234:237], v[38:41]
	v_mfma_f32_16x16x32_bf16 v[34:37], v[202:205], v[234:237], v[34:37]
	s_setprio 1
	s_barrier
	s_add_i32 s3, s3, s11
	v_lshl_add_u64 v[176:177], s[0:1], 0, v[4:5]
	s_mov_b32 m0, s3
	ds_read_b128 v[206:209], v166 offset:16384
	ds_read_b128 v[210:213], v166 offset:17408
	ds_read_b128 v[214:217], v166 offset:18432
	ds_read_b128 v[218:221], v166 offset:19456
	ds_read_b128 v[222:225], v166 offset:20480
	ds_read_b128 v[226:229], v166 offset:21504
	ds_read_b128 v[230:233], v166 offset:22528
	ds_read_b128 v[234:237], v166 offset:23552
	global_load_lds_dwordx4 v[176:177], off
	s_add_i32 m0, s3, 0x2000
	s_add_u32 s4, s0, 0x80000
	v_lshl_add_u64 v[238:239], s[0:1], 0, v[134:135]
	s_addc_u32 s5, s1, 0
	s_add_i32 s3, s6, s11
	global_load_lds_dwordx4 v[238:239], off
	v_lshl_add_u64 v[240:241], s[4:5], 0, v[4:5]
	s_mov_b32 m0, s3
	v_lshl_add_u64 v[242:243], s[14:15], 0, v[132:133]
	global_load_lds_dwordx4 v[240:241], off
	v_lshl_add_u64 v[240:241], s[4:5], 0, v[134:135]
	s_add_i32 m0, s3, 0x2000
	s_nop 0
	global_load_lds_dwordx4 v[240:241], off
	v_lshl_add_u64 v[240:241], s[14:15], 0, v[130:131]
	s_mov_b32 m0, s26
	s_nop 0
	global_load_lds_dwordx4 v[240:241], off
	s_mov_b32 m0, s27
	s_nop 0
	global_load_lds_dwordx4 v[242:243], off
	s_waitcnt vmcnt(24)
	s_waitcnt lgkmcnt(0)
	s_barrier
	s_setprio 0
	s_waitcnt lgkmcnt(0)
	v_mfma_f32_16x16x32_bf16 v[94:97], v[140:143], v[206:209], v[94:97]
	v_mfma_f32_16x16x32_bf16 v[90:93], v[148:151], v[206:209], v[90:93]
	v_mfma_f32_16x16x32_bf16 v[86:89], v[140:143], v[214:217], v[86:89]
	v_mfma_f32_16x16x32_bf16 v[82:85], v[148:151], v[214:217], v[82:85]
	v_mfma_f32_16x16x32_bf16 v[78:81], v[140:143], v[222:225], v[78:81]
	v_mfma_f32_16x16x32_bf16 v[74:77], v[148:151], v[222:225], v[74:77]
	v_mfma_f32_16x16x32_bf16 v[70:73], v[140:143], v[230:233], v[70:73]
	v_mfma_f32_16x16x32_bf16 v[66:69], v[148:151], v[230:233], v[66:69]
	v_mfma_f32_16x16x32_bf16 v[94:97], v[144:147], v[210:213], v[94:97]
	v_mfma_f32_16x16x32_bf16 v[90:93], v[172:175], v[210:213], v[90:93]
	v_mfma_f32_16x16x32_bf16 v[86:89], v[144:147], v[218:221], v[86:89]
	v_mfma_f32_16x16x32_bf16 v[82:85], v[172:175], v[218:221], v[82:85]
	v_mfma_f32_16x16x32_bf16 v[78:81], v[144:147], v[226:229], v[78:81]
	v_mfma_f32_16x16x32_bf16 v[74:77], v[172:175], v[226:229], v[74:77]
	v_mfma_f32_16x16x32_bf16 v[70:73], v[144:147], v[234:237], v[70:73]
	v_mfma_f32_16x16x32_bf16 v[66:69], v[172:175], v[234:237], v[66:69]
	v_mfma_f32_16x16x32_bf16 v[30:33], v[190:193], v[206:209], v[30:33]
	v_mfma_f32_16x16x32_bf16 v[26:29], v[198:201], v[206:209], v[26:29]
	v_mfma_f32_16x16x32_bf16 v[22:25], v[190:193], v[214:217], v[22:25]
	v_mfma_f32_16x16x32_bf16 v[18:21], v[198:201], v[214:217], v[18:21]
	v_mfma_f32_16x16x32_bf16 v[14:17], v[190:193], v[222:225], v[14:17]
	v_mfma_f32_16x16x32_bf16 v[10:13], v[198:201], v[222:225], v[10:13]
	v_mfma_f32_16x16x32_bf16 v[6:9], v[190:193], v[230:233], v[6:9]
	v_mfma_f32_16x16x32_bf16 v[0:3], v[198:201], v[230:233], v[0:3]
	v_mfma_f32_16x16x32_bf16 v[30:33], v[194:197], v[210:213], v[30:33]
	v_mfma_f32_16x16x32_bf16 v[26:29], v[202:205], v[210:213], v[26:29]
	v_mfma_f32_16x16x32_bf16 v[22:25], v[194:197], v[218:221], v[22:25]
	v_mfma_f32_16x16x32_bf16 v[18:21], v[202:205], v[218:221], v[18:21]
	v_mfma_f32_16x16x32_bf16 v[14:17], v[194:197], v[226:229], v[14:17]
	v_mfma_f32_16x16x32_bf16 v[10:13], v[202:205], v[226:229], v[10:13]
	v_mfma_f32_16x16x32_bf16 v[6:9], v[194:197], v[234:237], v[6:9]
	v_mfma_f32_16x16x32_bf16 v[0:3], v[202:205], v[234:237], v[0:3]
	s_setprio 1
	s_barrier
	s_branch .Lpeelmid_852
.LBB0_852:
	s_add_u32 s0, s22, 0xfff80080
	s_addc_u32 s1, s23, -1
	s_add_i32 s3, 0, 0x10000
	s_cmp_eq_u32 s28, 28
	s_cselect_b32 s15, s2, s1
	s_cselect_b32 s14, s8, s0
	v_add_u32_e32 v167, s3, v163
	s_cselect_b32 s1, s10, s25
	s_cselect_b32 s0, s24, s9
	s_add_i32 s6, 0, 0x14000
	ds_read_b128 v[140:143], v167
	ds_read_b128 v[144:147], v167 offset:1024
	ds_read_b128 v[148:151], v167 offset:2048
	ds_read_b128 v[172:175], v167 offset:3072
	v_add_u32_e32 v167, s6, v163
	ds_read_b128 v[190:193], v167
	ds_read_b128 v[194:197], v167 offset:1024
	ds_read_b128 v[198:201], v167 offset:2048
	ds_read_b128 v[202:205], v167 offset:3072
	v_lshl_add_u64 v[176:177], s[22:23], 0, v[136:137]
	s_add_i32 m0, s26, 0xc000
	ds_read_b128 v[206:209], v166
	ds_read_b128 v[210:213], v166 offset:1024
	ds_read_b128 v[214:217], v166 offset:2048
	ds_read_b128 v[218:221], v166 offset:3072
	ds_read_b128 v[222:225], v166 offset:4096
	ds_read_b128 v[226:229], v166 offset:5120
	ds_read_b128 v[230:233], v166 offset:6144
	ds_read_b128 v[234:237], v166 offset:7168
	global_load_lds_dwordx4 v[176:177], off
	v_lshl_add_u64 v[176:177], s[22:23], 0, v[138:139]
	s_add_i32 m0, s26, 0xe000
	s_nop 0
	global_load_lds_dwordx4 v[176:177], off
	s_waitcnt vmcnt(8)
	s_waitcnt lgkmcnt(0)
	s_barrier
	s_setprio 0
	s_waitcnt lgkmcnt(0)
	v_mfma_f32_16x16x32_bf16 v[126:129], v[140:143], v[206:209], v[126:129]
	v_mfma_f32_16x16x32_bf16 v[122:125], v[148:151], v[206:209], v[122:125]
	v_mfma_f32_16x16x32_bf16 v[118:121], v[140:143], v[214:217], v[118:121]
	v_mfma_f32_16x16x32_bf16 v[114:117], v[148:151], v[214:217], v[114:117]
	v_mfma_f32_16x16x32_bf16 v[110:113], v[140:143], v[222:225], v[110:113]
	v_mfma_f32_16x16x32_bf16 v[106:109], v[148:151], v[222:225], v[106:109]
	v_mfma_f32_16x16x32_bf16 v[102:105], v[140:143], v[230:233], v[102:105]
	v_mfma_f32_16x16x32_bf16 v[98:101], v[148:151], v[230:233], v[98:101]
	v_mfma_f32_16x16x32_bf16 v[126:129], v[144:147], v[210:213], v[126:129]
	v_mfma_f32_16x16x32_bf16 v[122:125], v[172:175], v[210:213], v[122:125]
	v_mfma_f32_16x16x32_bf16 v[118:121], v[144:147], v[218:221], v[118:121]
	v_mfma_f32_16x16x32_bf16 v[114:117], v[172:175], v[218:221], v[114:117]
	v_mfma_f32_16x16x32_bf16 v[110:113], v[144:147], v[226:229], v[110:113]
	v_mfma_f32_16x16x32_bf16 v[106:109], v[172:175], v[226:229], v[106:109]
	v_mfma_f32_16x16x32_bf16 v[102:105], v[144:147], v[234:237], v[102:105]
	v_mfma_f32_16x16x32_bf16 v[98:101], v[172:175], v[234:237], v[98:101]
	v_mfma_f32_16x16x32_bf16 v[62:65], v[190:193], v[206:209], v[62:65]
	v_mfma_f32_16x16x32_bf16 v[58:61], v[198:201], v[206:209], v[58:61]
	v_mfma_f32_16x16x32_bf16 v[54:57], v[190:193], v[214:217], v[54:57]
	v_mfma_f32_16x16x32_bf16 v[50:53], v[198:201], v[214:217], v[50:53]
	v_mfma_f32_16x16x32_bf16 v[46:49], v[190:193], v[222:225], v[46:49]
	v_mfma_f32_16x16x32_bf16 v[42:45], v[198:201], v[222:225], v[42:45]
	v_mfma_f32_16x16x32_bf16 v[38:41], v[190:193], v[230:233], v[38:41]
	v_mfma_f32_16x16x32_bf16 v[34:37], v[198:201], v[230:233], v[34:37]
	v_mfma_f32_16x16x32_bf16 v[62:65], v[194:197], v[210:213], v[62:65]
	v_mfma_f32_16x16x32_bf16 v[58:61], v[202:205], v[210:213], v[58:61]
	v_mfma_f32_16x16x32_bf16 v[54:57], v[194:197], v[218:221], v[54:57]
	v_mfma_f32_16x16x32_bf16 v[50:53], v[202:205], v[218:221], v[50:53]
	v_mfma_f32_16x16x32_bf16 v[46:49], v[194:197], v[226:229], v[46:49]
	v_mfma_f32_16x16x32_bf16 v[42:45], v[202:205], v[226:229], v[42:45]
	v_mfma_f32_16x16x32_bf16 v[38:41], v[194:197], v[234:237], v[38:41]
	v_mfma_f32_16x16x32_bf16 v[34:37], v[202:205], v[234:237], v[34:37]
	s_setprio 1
	s_barrier
	s_add_i32 s3, s3, s11
	v_lshl_add_u64 v[176:177], s[0:1], 0, v[4:5]
	s_mov_b32 m0, s3
	ds_read_b128 v[206:209], v166 offset:16384
	ds_read_b128 v[210:213], v166 offset:17408
	ds_read_b128 v[214:217], v166 offset:18432
	ds_read_b128 v[218:221], v166 offset:19456
	ds_read_b128 v[222:225], v166 offset:20480
	ds_read_b128 v[226:229], v166 offset:21504
	ds_read_b128 v[230:233], v166 offset:22528
	ds_read_b128 v[234:237], v166 offset:23552
	global_load_lds_dwordx4 v[176:177], off
	s_add_i32 m0, s3, 0x2000
	s_add_u32 s4, s0, 0x80000
	v_lshl_add_u64 v[238:239], s[0:1], 0, v[134:135]
	s_addc_u32 s5, s1, 0
	s_add_i32 s3, s6, s11
	global_load_lds_dwordx4 v[238:239], off
	v_lshl_add_u64 v[240:241], s[4:5], 0, v[4:5]
	s_mov_b32 m0, s3
	v_lshl_add_u64 v[242:243], s[14:15], 0, v[132:133]
	global_load_lds_dwordx4 v[240:241], off
	v_lshl_add_u64 v[240:241], s[4:5], 0, v[134:135]
	s_add_i32 m0, s3, 0x2000
	s_nop 0
	global_load_lds_dwordx4 v[240:241], off
	v_lshl_add_u64 v[240:241], s[14:15], 0, v[130:131]
	s_mov_b32 m0, s26
	s_nop 0
	global_load_lds_dwordx4 v[240:241], off
	s_mov_b32 m0, s27
	s_nop 0
	global_load_lds_dwordx4 v[242:243], off
	s_waitcnt vmcnt(8)
	s_waitcnt lgkmcnt(0)
	s_barrier
	s_setprio 0
	s_waitcnt lgkmcnt(0)
	v_mfma_f32_16x16x32_bf16 v[94:97], v[140:143], v[206:209], v[94:97]
	v_mfma_f32_16x16x32_bf16 v[90:93], v[148:151], v[206:209], v[90:93]
	v_mfma_f32_16x16x32_bf16 v[86:89], v[140:143], v[214:217], v[86:89]
	v_mfma_f32_16x16x32_bf16 v[82:85], v[148:151], v[214:217], v[82:85]
	v_mfma_f32_16x16x32_bf16 v[78:81], v[140:143], v[222:225], v[78:81]
	v_mfma_f32_16x16x32_bf16 v[74:77], v[148:151], v[222:225], v[74:77]
	v_mfma_f32_16x16x32_bf16 v[70:73], v[140:143], v[230:233], v[70:73]
	v_mfma_f32_16x16x32_bf16 v[66:69], v[148:151], v[230:233], v[66:69]
	v_mfma_f32_16x16x32_bf16 v[94:97], v[144:147], v[210:213], v[94:97]
	v_mfma_f32_16x16x32_bf16 v[90:93], v[172:175], v[210:213], v[90:93]
	v_mfma_f32_16x16x32_bf16 v[86:89], v[144:147], v[218:221], v[86:89]
	v_mfma_f32_16x16x32_bf16 v[82:85], v[172:175], v[218:221], v[82:85]
	v_mfma_f32_16x16x32_bf16 v[78:81], v[144:147], v[226:229], v[78:81]
	v_mfma_f32_16x16x32_bf16 v[74:77], v[172:175], v[226:229], v[74:77]
	v_mfma_f32_16x16x32_bf16 v[70:73], v[144:147], v[234:237], v[70:73]
	v_mfma_f32_16x16x32_bf16 v[66:69], v[172:175], v[234:237], v[66:69]
	v_mfma_f32_16x16x32_bf16 v[30:33], v[190:193], v[206:209], v[30:33]
	v_mfma_f32_16x16x32_bf16 v[26:29], v[198:201], v[206:209], v[26:29]
	v_mfma_f32_16x16x32_bf16 v[22:25], v[190:193], v[214:217], v[22:25]
	v_mfma_f32_16x16x32_bf16 v[18:21], v[198:201], v[214:217], v[18:21]
	v_mfma_f32_16x16x32_bf16 v[14:17], v[190:193], v[222:225], v[14:17]
	v_mfma_f32_16x16x32_bf16 v[10:13], v[198:201], v[222:225], v[10:13]
	v_mfma_f32_16x16x32_bf16 v[6:9], v[190:193], v[230:233], v[6:9]
	v_mfma_f32_16x16x32_bf16 v[0:3], v[198:201], v[230:233], v[0:3]
	v_mfma_f32_16x16x32_bf16 v[30:33], v[194:197], v[210:213], v[30:33]
	v_mfma_f32_16x16x32_bf16 v[26:29], v[202:205], v[210:213], v[26:29]
	v_mfma_f32_16x16x32_bf16 v[22:25], v[194:197], v[218:221], v[22:25]
	v_mfma_f32_16x16x32_bf16 v[18:21], v[202:205], v[218:221], v[18:21]
	v_mfma_f32_16x16x32_bf16 v[14:17], v[194:197], v[226:229], v[14:17]
	v_mfma_f32_16x16x32_bf16 v[10:13], v[202:205], v[226:229], v[10:13]
	v_mfma_f32_16x16x32_bf16 v[6:9], v[194:197], v[234:237], v[6:9]
	v_mfma_f32_16x16x32_bf16 v[0:3], v[202:205], v[234:237], v[0:3]
	s_setprio 1
	s_barrier
.Lpeelmid_852:
	s_add_i32 s3, 0, 0x18000
	v_add_u32_e32 v167, s3, v163
	s_add_i32 s6, 0, 0x1c000
	ds_read_b128 v[140:143], v167
	ds_read_b128 v[144:147], v167 offset:1024
	ds_read_b128 v[148:151], v167 offset:2048
	ds_read_b128 v[172:175], v167 offset:3072
	v_add_u32_e32 v167, s6, v163
	ds_read_b128 v[190:193], v167
	ds_read_b128 v[194:197], v167 offset:1024
	ds_read_b128 v[198:201], v167 offset:2048
	ds_read_b128 v[202:205], v167 offset:3072
	s_add_u32 s4, s14, 0x80000
	s_addc_u32 s5, s15, 0
	s_mov_b32 m0, s30
	v_lshl_add_u64 v[244:245], s[4:5], 0, v[130:131]
	ds_read_b128 v[206:209], v166 offset:32768
	ds_read_b128 v[210:213], v166 offset:33792
	ds_read_b128 v[214:217], v166 offset:34816
	ds_read_b128 v[218:221], v166 offset:35840
	ds_read_b128 v[222:225], v166 offset:36864
	ds_read_b128 v[226:229], v166 offset:37888
	ds_read_b128 v[230:233], v166 offset:38912
	ds_read_b128 v[234:237], v166 offset:39936
	global_load_lds_dwordx4 v[244:245], off
	v_lshl_add_u64 v[244:245], s[4:5], 0, v[132:133]
	s_mov_b32 m0, s31
	s_nop 0
	global_load_lds_dwordx4 v[244:245], off
	s_waitcnt vmcnt(8)
	s_waitcnt lgkmcnt(0)
	s_barrier
	s_setprio 0
	s_waitcnt lgkmcnt(0)
	v_mfma_f32_16x16x32_bf16 v[126:129], v[140:143], v[206:209], v[126:129]
	v_mfma_f32_16x16x32_bf16 v[122:125], v[148:151], v[206:209], v[122:125]
	v_mfma_f32_16x16x32_bf16 v[118:121], v[140:143], v[214:217], v[118:121]
	v_mfma_f32_16x16x32_bf16 v[114:117], v[148:151], v[214:217], v[114:117]
	v_mfma_f32_16x16x32_bf16 v[110:113], v[140:143], v[222:225], v[110:113]
	v_mfma_f32_16x16x32_bf16 v[106:109], v[148:151], v[222:225], v[106:109]
	v_mfma_f32_16x16x32_bf16 v[102:105], v[140:143], v[230:233], v[102:105]
	v_mfma_f32_16x16x32_bf16 v[98:101], v[148:151], v[230:233], v[98:101]
	v_mfma_f32_16x16x32_bf16 v[126:129], v[144:147], v[210:213], v[126:129]
	v_mfma_f32_16x16x32_bf16 v[122:125], v[172:175], v[210:213], v[122:125]
	v_mfma_f32_16x16x32_bf16 v[118:121], v[144:147], v[218:221], v[118:121]
	v_mfma_f32_16x16x32_bf16 v[114:117], v[172:175], v[218:221], v[114:117]
	v_mfma_f32_16x16x32_bf16 v[110:113], v[144:147], v[226:229], v[110:113]
	v_mfma_f32_16x16x32_bf16 v[106:109], v[172:175], v[226:229], v[106:109]
	v_mfma_f32_16x16x32_bf16 v[102:105], v[144:147], v[234:237], v[102:105]
	v_mfma_f32_16x16x32_bf16 v[98:101], v[172:175], v[234:237], v[98:101]
	v_mfma_f32_16x16x32_bf16 v[62:65], v[190:193], v[206:209], v[62:65]
	v_mfma_f32_16x16x32_bf16 v[58:61], v[198:201], v[206:209], v[58:61]
	v_mfma_f32_16x16x32_bf16 v[54:57], v[190:193], v[214:217], v[54:57]
	v_mfma_f32_16x16x32_bf16 v[50:53], v[198:201], v[214:217], v[50:53]
	v_mfma_f32_16x16x32_bf16 v[46:49], v[190:193], v[222:225], v[46:49]
	v_mfma_f32_16x16x32_bf16 v[42:45], v[198:201], v[222:225], v[42:45]
	v_mfma_f32_16x16x32_bf16 v[38:41], v[190:193], v[230:233], v[38:41]
	v_mfma_f32_16x16x32_bf16 v[34:37], v[198:201], v[230:233], v[34:37]
	v_mfma_f32_16x16x32_bf16 v[62:65], v[194:197], v[210:213], v[62:65]
	v_mfma_f32_16x16x32_bf16 v[58:61], v[202:205], v[210:213], v[58:61]
	v_mfma_f32_16x16x32_bf16 v[54:57], v[194:197], v[218:221], v[54:57]
	v_mfma_f32_16x16x32_bf16 v[50:53], v[202:205], v[218:221], v[50:53]
	v_mfma_f32_16x16x32_bf16 v[46:49], v[194:197], v[226:229], v[46:49]
	v_mfma_f32_16x16x32_bf16 v[42:45], v[202:205], v[226:229], v[42:45]
	v_mfma_f32_16x16x32_bf16 v[38:41], v[194:197], v[234:237], v[38:41]
	v_mfma_f32_16x16x32_bf16 v[34:37], v[202:205], v[234:237], v[34:37]
	s_setprio 1
	s_barrier
	s_add_i32 s3, s3, s11
	v_lshl_add_u64 v[176:177], v[176:177], 0, s[70:71]
	s_mov_b32 m0, s3
	ds_read_b128 v[206:209], v166 offset:49152
	ds_read_b128 v[210:213], v166 offset:50176
	ds_read_b128 v[214:217], v166 offset:51200
	ds_read_b128 v[218:221], v166 offset:52224
	ds_read_b128 v[222:225], v166 offset:53248
	ds_read_b128 v[226:229], v166 offset:54272
	ds_read_b128 v[230:233], v166 offset:55296
	ds_read_b128 v[234:237], v166 offset:56320
	global_load_lds_dwordx4 v[176:177], off
	s_add_i32 m0, s3, 0x2000
	s_add_u32 s0, s0, 0x80080
	v_lshl_add_u64 v[176:177], v[238:239], 0, s[70:71]
	s_addc_u32 s1, s1, 0
	s_add_i32 s3, s6, s11
	global_load_lds_dwordx4 v[176:177], off
	v_lshl_add_u64 v[176:177], s[0:1], 0, v[4:5]
	s_mov_b32 m0, s3
	s_nop 0
	global_load_lds_dwordx4 v[176:177], off
	v_lshl_add_u64 v[176:177], s[0:1], 0, v[134:135]
	s_add_i32 m0, s3, 0x2000
	s_nop 0
	global_load_lds_dwordx4 v[176:177], off
	v_lshl_add_u64 v[176:177], v[240:241], 0, s[70:71]
	s_mov_b32 m0, s34
	s_nop 0
	global_load_lds_dwordx4 v[176:177], off
	v_lshl_add_u64 v[176:177], v[242:243], 0, s[70:71]
	s_mov_b32 m0, s35
	s_nop 0
	global_load_lds_dwordx4 v[176:177], off
	s_waitcnt vmcnt(8)
	s_waitcnt lgkmcnt(0)
	s_barrier
	s_setprio 0
	s_waitcnt lgkmcnt(0)
	v_mfma_f32_16x16x32_bf16 v[94:97], v[140:143], v[206:209], v[94:97]
	v_mfma_f32_16x16x32_bf16 v[90:93], v[148:151], v[206:209], v[90:93]
	v_mfma_f32_16x16x32_bf16 v[86:89], v[140:143], v[214:217], v[86:89]
	v_mfma_f32_16x16x32_bf16 v[82:85], v[148:151], v[214:217], v[82:85]
	v_mfma_f32_16x16x32_bf16 v[78:81], v[140:143], v[222:225], v[78:81]
	v_mfma_f32_16x16x32_bf16 v[74:77], v[148:151], v[222:225], v[74:77]
	v_mfma_f32_16x16x32_bf16 v[70:73], v[140:143], v[230:233], v[70:73]
	v_mfma_f32_16x16x32_bf16 v[66:69], v[148:151], v[230:233], v[66:69]
	v_mfma_f32_16x16x32_bf16 v[94:97], v[144:147], v[210:213], v[94:97]
	v_mfma_f32_16x16x32_bf16 v[90:93], v[172:175], v[210:213], v[90:93]
	v_mfma_f32_16x16x32_bf16 v[86:89], v[144:147], v[218:221], v[86:89]
	v_mfma_f32_16x16x32_bf16 v[82:85], v[172:175], v[218:221], v[82:85]
	v_mfma_f32_16x16x32_bf16 v[78:81], v[144:147], v[226:229], v[78:81]
	v_mfma_f32_16x16x32_bf16 v[74:77], v[172:175], v[226:229], v[74:77]
	v_mfma_f32_16x16x32_bf16 v[70:73], v[144:147], v[234:237], v[70:73]
	v_mfma_f32_16x16x32_bf16 v[66:69], v[172:175], v[234:237], v[66:69]
	v_mfma_f32_16x16x32_bf16 v[30:33], v[190:193], v[206:209], v[30:33]
	v_mfma_f32_16x16x32_bf16 v[26:29], v[198:201], v[206:209], v[26:29]
	v_mfma_f32_16x16x32_bf16 v[22:25], v[190:193], v[214:217], v[22:25]
	v_mfma_f32_16x16x32_bf16 v[18:21], v[198:201], v[214:217], v[18:21]
	v_mfma_f32_16x16x32_bf16 v[14:17], v[190:193], v[222:225], v[14:17]
	v_mfma_f32_16x16x32_bf16 v[10:13], v[198:201], v[222:225], v[10:13]
	v_mfma_f32_16x16x32_bf16 v[6:9], v[190:193], v[230:233], v[6:9]
	v_mfma_f32_16x16x32_bf16 v[0:3], v[198:201], v[230:233], v[0:3]
	v_mfma_f32_16x16x32_bf16 v[30:33], v[194:197], v[210:213], v[30:33]
	v_mfma_f32_16x16x32_bf16 v[26:29], v[202:205], v[210:213], v[26:29]
	v_mfma_f32_16x16x32_bf16 v[22:25], v[194:197], v[218:221], v[22:25]
	v_mfma_f32_16x16x32_bf16 v[18:21], v[202:205], v[218:221], v[18:21]
	v_mfma_f32_16x16x32_bf16 v[14:17], v[194:197], v[226:229], v[14:17]
	v_mfma_f32_16x16x32_bf16 v[10:13], v[202:205], v[226:229], v[10:13]
	v_mfma_f32_16x16x32_bf16 v[6:9], v[194:197], v[234:237], v[6:9]
	v_mfma_f32_16x16x32_bf16 v[0:3], v[202:205], v[234:237], v[0:3]
	s_setprio 1
	s_barrier
	s_add_i32 s28, s28, 2
	s_add_u32 s22, s22, 0x100
	s_addc_u32 s23, s23, 0
	s_add_u32 s9, s9, 0x100
	s_addc_u32 s25, s25, 0
	s_cmp_gt_u32 s28, 29
	s_cbranch_scc0 .LBB0_852
	s_and_b64 vcc, exec, s[48:49]
	s_cbranch_vccz .LBB0_855
	s_barrier
